# GEMM K-loops: per-segment s_setprio flips deleted, one static s_setprio 1 for waves 4-7 for the duration of each K-loop (strategy 7.4)
# speedup vs baseline: 1.0097x; 1.0078x over previous
; #define PG8_STAGE(bufoff, gbase, voff) do { _Pragma("unroll") for (int _i = 0; _i < 2; ++_i) \
;         __builtin_amdgcn_global_load_lds((const unsigned*)((const char*)(gbase) + (voff)[_i]), (LAS unsigned*)(lds + (bufoff) + ldsw + _i * 8192), 16, 0, 0); } while (0)
; #define PG8_LDA(dst, b, h) do { _Pragma("unroll") for (int m = 0; m < 4; ++m) _Pragma("unroll") for (int k = 0; k < 2; ++k) dst[m][k] = *(const LAS bf16x8*)(lds + PG8_SA(b, h) + aoff + m * 2048 + k * 1024); } while (0)
; #define PG8_LDB(dst, b, h) do { _Pragma("unroll") for (int n = 0; n < 2; ++n) _Pragma("unroll") for (int k = 0; k < 2; ++k) dst[n][k] = *(const LAS bf16x8*)(lds + PG8_SB(b, h) + boff + n * 2048 + k * 1024); } while (0)
; #define PG8_MMA(ai, bj, At, Bt) do { __builtin_amdgcn_s_setprio(1); _Pragma("unroll") for (int m = 0; m < 4; ++m) _Pragma("unroll") for (int n = 0; n < 2; ++n) _Pragma("unroll") for (int k = 0; k < 2; ++k) \
;         acc[ai][bj][m][n] = __builtin_amdgcn_mfma_f32_16x16x32_bf16(Bt[n][k], At[m][k], acc[ai][bj][m][n], 0, 0, 0); __builtin_amdgcn_s_setprio(0); } while (0)
; #define PG8_WAIT_V(n) asm volatile("s_waitcnt vmcnt(" #n ")" ::: "memory")
; #define PG8_WAIT_L(n) asm volatile("s_waitcnt lgkmcnt(" #n ")" ::: "memory")
; #define PG8_BAR __builtin_amdgcn_s_barrier()
; #define PG8_SCHED __builtin_amdgcn_sched_barrier(0)
; template <class Epi, bool ALIGN_EPI>
; __device__ __forceinline__ void gemm_phase(LAS unsigned char* lds, const Gemm g, const StaticOrder S, const Epi E) {
;     ...
;         for (int t = 0; t < nt; t += 2) {
;             const bool last = (t == nt - 2);
;             const char* a1 = cA + (size_t)(t + 1) * kstep;
;             const char* a2 = last ? nA : cA + (size_t)(t + 2) * kstep; const char* b2 = last ? nB : cB + (size_t)(t + 2) * kstep;
;             const char* a3 = a2 + kstep; const char* b3 = b2 + kstep;
;             PG8_LDB(B0, 0, 0); PG8_LDB(B1, 0, 1); PG8_SCHED; PG8_LDA(At, 0, 0); PG8_STAGE(PG8_SA(1, 1), a1 + hstepA, voffA);
;             PG8_WAIT_V(8); PG8_WAIT_L(0); PG8_BAR; PG8_MMA(0, 0, At, B0); PG8_MMA(0, 1, At, B1); PG8_BAR; PG8_SCHED;
;     ...
; #pragma unroll
;         for (int a = 0; a < 2; ++a)
; #pragma unroll
;             for (int b = 0; b < 2; ++b)
; #pragma unroll
;                 for (int m = 0; m < 4; ++m)
; #pragma unroll
;                     for (int n = 0; n < 2; ++n) acc[a][b][m][n] = (f32x4){0.f, 0.f, 0.f, 0.f};
.LBB0_603:
	s_ashr_i32 s67, s66, 31
	s_lshl_b64 s[0:1], s[66:67], 19
	s_add_u32 s68, s94, s0
	s_addc_u32 s69, s95, s1
	s_and_b64 s[0:1], s[42:43], exec
	s_cselect_b32 s34, s69, s49
	s_cselect_b32 s35, s68, s48
	s_ashr_i32 s65, s64, 31
	s_lshl_b64 s[0:1], s[64:65], 19
	s_add_u32 s70, s58, s0
	s_addc_u32 s71, s72, s1
	s_and_b64 s[0:1], s[42:43], exec
	s_cselect_b32 s50, s71, s47
	s_cselect_b32 s51, s70, s46
	s_add_u32 s40, s48, 0x40080
	s_addc_u32 s41, s49, 0
	s_add_u32 s52, s46, 0x100
	v_mov_b32_e32 v0, 0
	s_addc_u32 s53, s47, 0
	s_mov_b32 s54, -2
	v_mov_b32_e32 v1, 0
	v_mov_b64_e32 v[2:3], 0
	v_mov_b64_e32 v[4:5], 0
	v_mov_b64_e32 v[6:7], 0
	v_mov_b64_e32 v[8:9], 0
	v_mov_b64_e32 v[10:11], 0
	v_mov_b64_e32 v[12:13], 0
	v_mov_b64_e32 v[14:15], 0
	v_mov_b64_e32 v[16:17], 0
	v_mov_b64_e32 v[18:19], 0
	v_mov_b64_e32 v[20:21], 0
	v_mov_b64_e32 v[22:23], 0
	v_mov_b64_e32 v[24:25], 0
	v_mov_b64_e32 v[26:27], 0
	v_mov_b64_e32 v[28:29], 0
	v_mov_b64_e32 v[30:31], 0
	v_mov_b64_e32 v[32:33], 0
	v_mov_b64_e32 v[34:35], 0
	v_mov_b64_e32 v[36:37], 0
	v_mov_b64_e32 v[38:39], 0
	v_mov_b64_e32 v[40:41], 0
	v_mov_b64_e32 v[42:43], 0
	v_mov_b64_e32 v[44:45], 0
	v_mov_b64_e32 v[46:47], 0
	v_mov_b64_e32 v[48:49], 0
	v_mov_b64_e32 v[50:51], 0
	v_mov_b64_e32 v[52:53], 0
	v_mov_b64_e32 v[54:55], 0
	v_mov_b64_e32 v[56:57], 0
	v_mov_b64_e32 v[58:59], 0
	v_mov_b64_e32 v[60:61], 0
	v_mov_b64_e32 v[62:63], 0
	v_mov_b64_e32 v[64:65], 0
	v_mov_b64_e32 v[66:67], 0
	v_mov_b64_e32 v[68:69], 0
	v_mov_b64_e32 v[70:71], 0
	v_mov_b64_e32 v[72:73], 0
	v_mov_b64_e32 v[74:75], 0
	v_mov_b64_e32 v[76:77], 0
	v_mov_b64_e32 v[78:79], 0
	v_mov_b64_e32 v[82:83], 0
	v_mov_b64_e32 v[84:85], 0
	v_mov_b64_e32 v[86:87], 0
	v_mov_b64_e32 v[88:89], 0
	v_mov_b64_e32 v[90:91], 0
	v_mov_b64_e32 v[92:93], 0
	v_mov_b64_e32 v[94:95], 0
	v_mov_b64_e32 v[96:97], 0
	v_mov_b64_e32 v[98:99], 0
	v_mov_b64_e32 v[100:101], 0
	v_mov_b64_e32 v[102:103], 0
	v_mov_b64_e32 v[104:105], 0
	v_mov_b64_e32 v[106:107], 0
	v_mov_b64_e32 v[108:109], 0
	v_mov_b64_e32 v[110:111], 0
	v_mov_b64_e32 v[112:113], 0
	v_mov_b64_e32 v[114:115], 0
	v_mov_b64_e32 v[116:117], 0
	v_mov_b64_e32 v[118:119], 0
	v_mov_b64_e32 v[120:121], 0
	v_mov_b64_e32 v[122:123], 0
	v_mov_b64_e32 v[124:125], 0
	v_mov_b64_e32 v[126:127], 0
	v_mov_b64_e32 v[128:129], 0
	v_readfirstlane_b32 s0, v167
	s_nop 3
	s_cmpk_lt_u32 s0, 0x100
	s_cbranch_scc1 .Lprio_k0
	s_setprio 1
.Lprio_k0:
.LBB0_604:
	s_add_u32 s0, s40, 0xfffc0080
	s_addc_u32 s1, s41, -1
	s_add_i32 s12, 0, 0x10000
	s_cmp_eq_u32 s54, 12
	s_cselect_b32 s49, s34, s1
	s_cselect_b32 s48, s35, s0
	v_add_u32_e32 v130, s12, v172
	s_cselect_b32 s47, s50, s53
	s_cselect_b32 s46, s51, s52
	s_add_i32 s15, 0, 0x14000
	ds_read_b128 v[182:185], v130
	ds_read_b128 v[186:189], v130 offset:1024
	ds_read_b128 v[190:193], v130 offset:2048
	ds_read_b128 v[194:197], v130 offset:3072
	v_add_u32_e32 v130, s15, v172
	ds_read_b128 v[198:201], v130
	ds_read_b128 v[202:205], v130 offset:1024
	ds_read_b128 v[206:209], v130 offset:2048
	ds_read_b128 v[210:213], v130 offset:3072
	v_lshl_add_u64 v[164:165], s[40:41], 0, v[150:151]
	s_add_i32 m0, s24, 0xc000
	ds_read_b128 v[214:217], v173
	ds_read_b128 v[218:221], v173 offset:1024
	ds_read_b128 v[222:225], v173 offset:2048
	ds_read_b128 v[226:229], v173 offset:3072
	ds_read_b128 v[230:233], v173 offset:4096
	ds_read_b128 v[234:237], v173 offset:5120
	ds_read_b128 v[238:241], v173 offset:6144
	ds_read_b128 v[242:245], v173 offset:7168
	global_load_lds_dwordx4 v[164:165], off
	v_lshl_add_u64 v[164:165], s[40:41], 0, v[152:153]
	s_add_i32 m0, s24, 0xe000
	s_nop 0
	global_load_lds_dwordx4 v[164:165], off
	s_waitcnt vmcnt(8)
	s_waitcnt lgkmcnt(0)
	s_barrier
	s_waitcnt lgkmcnt(0)
	v_mfma_f32_16x16x32_bf16 v[126:129], v[182:185], v[214:217], v[126:129]
	v_mfma_f32_16x16x32_bf16 v[118:121], v[190:193], v[214:217], v[118:121]
	v_mfma_f32_16x16x32_bf16 v[110:113], v[182:185], v[222:225], v[110:113]
	v_mfma_f32_16x16x32_bf16 v[106:109], v[190:193], v[222:225], v[106:109]
	v_mfma_f32_16x16x32_bf16 v[94:97], v[182:185], v[230:233], v[94:97]
	v_mfma_f32_16x16x32_bf16 v[86:89], v[190:193], v[230:233], v[86:89]
	v_mfma_f32_16x16x32_bf16 v[76:79], v[182:185], v[238:241], v[76:79]
	v_mfma_f32_16x16x32_bf16 v[72:75], v[190:193], v[238:241], v[72:75]
	v_mfma_f32_16x16x32_bf16 v[126:129], v[186:189], v[218:221], v[126:129]
	v_mfma_f32_16x16x32_bf16 v[118:121], v[194:197], v[218:221], v[118:121]
	v_mfma_f32_16x16x32_bf16 v[110:113], v[186:189], v[226:229], v[110:113]
	v_mfma_f32_16x16x32_bf16 v[106:109], v[194:197], v[226:229], v[106:109]
	v_mfma_f32_16x16x32_bf16 v[94:97], v[186:189], v[234:237], v[94:97]
	v_mfma_f32_16x16x32_bf16 v[86:89], v[194:197], v[234:237], v[86:89]
	v_mfma_f32_16x16x32_bf16 v[76:79], v[186:189], v[242:245], v[76:79]
	v_mfma_f32_16x16x32_bf16 v[72:75], v[194:197], v[242:245], v[72:75]
	v_mfma_f32_16x16x32_bf16 v[122:125], v[198:201], v[214:217], v[122:125]
	v_mfma_f32_16x16x32_bf16 v[114:117], v[206:209], v[214:217], v[114:117]
	v_mfma_f32_16x16x32_bf16 v[102:105], v[198:201], v[222:225], v[102:105]
	v_mfma_f32_16x16x32_bf16 v[98:101], v[206:209], v[222:225], v[98:101]
	v_mfma_f32_16x16x32_bf16 v[90:93], v[198:201], v[230:233], v[90:93]
	v_mfma_f32_16x16x32_bf16 v[82:85], v[206:209], v[230:233], v[82:85]
	v_mfma_f32_16x16x32_bf16 v[68:71], v[198:201], v[238:241], v[68:71]
	v_mfma_f32_16x16x32_bf16 v[64:67], v[206:209], v[238:241], v[64:67]
	v_mfma_f32_16x16x32_bf16 v[122:125], v[202:205], v[218:221], v[122:125]
	v_mfma_f32_16x16x32_bf16 v[114:117], v[210:213], v[218:221], v[114:117]
	v_mfma_f32_16x16x32_bf16 v[102:105], v[202:205], v[226:229], v[102:105]
	v_mfma_f32_16x16x32_bf16 v[98:101], v[210:213], v[226:229], v[98:101]
	v_mfma_f32_16x16x32_bf16 v[90:93], v[202:205], v[234:237], v[90:93]
	v_mfma_f32_16x16x32_bf16 v[82:85], v[210:213], v[234:237], v[82:85]
	v_mfma_f32_16x16x32_bf16 v[68:71], v[202:205], v[242:245], v[68:71]
	v_mfma_f32_16x16x32_bf16 v[64:67], v[210:213], v[242:245], v[64:67]
	s_barrier
; #define PG8_STAGE(bufoff, gbase, voff) do { _Pragma("unroll") for (int _i = 0; _i < 2; ++_i) \
;         __builtin_amdgcn_global_load_lds((const unsigned*)((const char*)(gbase) + (voff)[_i]), (LAS unsigned*)(lds + (bufoff) + ldsw + _i * 8192), 16, 0, 0); } while (0)
; #define PG8_LDA(dst, b, h) do { _Pragma("unroll") for (int m = 0; m < 4; ++m) _Pragma("unroll") for (int k = 0; k < 2; ++k) dst[m][k] = *(const LAS bf16x8*)(lds + PG8_SA(b, h) + aoff + m * 2048 + k * 1024); } while (0)
; #define PG8_LDB(dst, b, h) do { _Pragma("unroll") for (int n = 0; n < 2; ++n) _Pragma("unroll") for (int k = 0; k < 2; ++k) dst[n][k] = *(const LAS bf16x8*)(lds + PG8_SB(b, h) + boff + n * 2048 + k * 1024); } while (0)
; #define PG8_MMA(ai, bj, At, Bt) do { __builtin_amdgcn_s_setprio(1); _Pragma("unroll") for (int m = 0; m < 4; ++m) _Pragma("unroll") for (int n = 0; n < 2; ++n) _Pragma("unroll") for (int k = 0; k < 2; ++k) \
;         acc[ai][bj][m][n] = __builtin_amdgcn_mfma_f32_16x16x32_bf16(Bt[n][k], At[m][k], acc[ai][bj][m][n], 0, 0, 0); __builtin_amdgcn_s_setprio(0); } while (0)
; #define PG8_WAIT_V(n) asm volatile("s_waitcnt vmcnt(" #n ")" ::: "memory")
; #define PG8_WAIT_L(n) asm volatile("s_waitcnt lgkmcnt(" #n ")" ::: "memory")
; #define PG8_BAR __builtin_amdgcn_s_barrier()
; #define PG8_SCHED __builtin_amdgcn_sched_barrier(0)
; template <class Epi, bool ALIGN_EPI>
; __device__ __forceinline__ void gemm_phase(LAS unsigned char* lds, const Gemm g, const StaticOrder S, const Epi E) {
;     ...
;             PG8_LDA(At, 0, 1); PG8_STAGE(PG8_SB(0, 0), b2, voffB); PG8_STAGE(PG8_SB(0, 1), b2 + hstepB, voffB); PG8_STAGE(PG8_SA(0, 0), a2, voffA);
;             PG8_WAIT_V(8); PG8_WAIT_L(0); PG8_BAR; PG8_MMA(1, 0, At, B0); PG8_MMA(1, 1, At, B1); PG8_BAR; PG8_SCHED;
;             PG8_LDB(B0, 1, 0); PG8_LDB(B1, 1, 1); PG8_SCHED; PG8_LDA(At, 1, 0); PG8_STAGE(PG8_SA(0, 1), a2 + hstepA, voffA);
	s_add_i32 s0, s12, s73
	v_lshl_add_u64 v[164:165], s[46:47], 0, v[80:81]
	s_mov_b32 m0, s0
	ds_read_b128 v[214:217], v173 offset:16384
	ds_read_b128 v[218:221], v173 offset:17408
	ds_read_b128 v[222:225], v173 offset:18432
	ds_read_b128 v[226:229], v173 offset:19456
	ds_read_b128 v[230:233], v173 offset:20480
	ds_read_b128 v[234:237], v173 offset:21504
	ds_read_b128 v[238:241], v173 offset:22528
	ds_read_b128 v[242:245], v173 offset:23552
	global_load_lds_dwordx4 v[164:165], off
	s_add_i32 m0, s0, 0x2000
	s_add_u32 s0, s46, 0x40000
	v_lshl_add_u64 v[176:177], s[46:47], 0, v[136:137]
	s_addc_u32 s1, s47, 0
	s_add_i32 s12, s15, s73
	global_load_lds_dwordx4 v[176:177], off
	v_lshl_add_u64 v[178:179], s[0:1], 0, v[80:81]
	s_mov_b32 m0, s12
	v_lshl_add_u64 v[246:247], s[48:49], 0, v[138:139]
	global_load_lds_dwordx4 v[178:179], off
	v_lshl_add_u64 v[178:179], s[0:1], 0, v[136:137]
	s_add_i32 m0, s12, 0x2000
	s_nop 0
	global_load_lds_dwordx4 v[178:179], off
	v_lshl_add_u64 v[178:179], s[48:49], 0, v[140:141]
	s_mov_b32 m0, s24
	s_nop 0
	global_load_lds_dwordx4 v[178:179], off
	s_mov_b32 m0, s25
	s_nop 0
	global_load_lds_dwordx4 v[246:247], off
	s_waitcnt vmcnt(8)
	s_waitcnt lgkmcnt(0)
	s_barrier
	s_waitcnt lgkmcnt(0)
	v_mfma_f32_16x16x32_bf16 v[60:63], v[182:185], v[214:217], v[60:63]
	v_mfma_f32_16x16x32_bf16 v[52:55], v[190:193], v[214:217], v[52:55]
	v_mfma_f32_16x16x32_bf16 v[44:47], v[182:185], v[222:225], v[44:47]
	v_mfma_f32_16x16x32_bf16 v[40:43], v[190:193], v[222:225], v[40:43]
	v_mfma_f32_16x16x32_bf16 v[28:31], v[182:185], v[230:233], v[28:31]
	v_mfma_f32_16x16x32_bf16 v[20:23], v[190:193], v[230:233], v[20:23]
	v_mfma_f32_16x16x32_bf16 v[12:15], v[182:185], v[238:241], v[12:15]
	v_mfma_f32_16x16x32_bf16 v[8:11], v[190:193], v[238:241], v[8:11]
	v_mfma_f32_16x16x32_bf16 v[60:63], v[186:189], v[218:221], v[60:63]
	v_mfma_f32_16x16x32_bf16 v[52:55], v[194:197], v[218:221], v[52:55]
	v_mfma_f32_16x16x32_bf16 v[44:47], v[186:189], v[226:229], v[44:47]
	v_mfma_f32_16x16x32_bf16 v[40:43], v[194:197], v[226:229], v[40:43]
	v_mfma_f32_16x16x32_bf16 v[28:31], v[186:189], v[234:237], v[28:31]
	v_mfma_f32_16x16x32_bf16 v[20:23], v[194:197], v[234:237], v[20:23]
	v_mfma_f32_16x16x32_bf16 v[12:15], v[186:189], v[242:245], v[12:15]
	v_mfma_f32_16x16x32_bf16 v[8:11], v[194:197], v[242:245], v[8:11]
	v_mfma_f32_16x16x32_bf16 v[56:59], v[198:201], v[214:217], v[56:59]
	v_mfma_f32_16x16x32_bf16 v[48:51], v[206:209], v[214:217], v[48:51]
	v_mfma_f32_16x16x32_bf16 v[36:39], v[198:201], v[222:225], v[36:39]
	v_mfma_f32_16x16x32_bf16 v[32:35], v[206:209], v[222:225], v[32:35]
	v_mfma_f32_16x16x32_bf16 v[24:27], v[198:201], v[230:233], v[24:27]
	v_mfma_f32_16x16x32_bf16 v[16:19], v[206:209], v[230:233], v[16:19]
	v_mfma_f32_16x16x32_bf16 v[4:7], v[198:201], v[238:241], v[4:7]
	v_mfma_f32_16x16x32_bf16 v[0:3], v[206:209], v[238:241], v[0:3]
	v_mfma_f32_16x16x32_bf16 v[56:59], v[202:205], v[218:221], v[56:59]
	v_mfma_f32_16x16x32_bf16 v[48:51], v[210:213], v[218:221], v[48:51]
	v_mfma_f32_16x16x32_bf16 v[36:39], v[202:205], v[226:229], v[36:39]
	v_mfma_f32_16x16x32_bf16 v[32:35], v[210:213], v[226:229], v[32:35]
	v_mfma_f32_16x16x32_bf16 v[24:27], v[202:205], v[234:237], v[24:27]
	v_mfma_f32_16x16x32_bf16 v[16:19], v[210:213], v[234:237], v[16:19]
	v_mfma_f32_16x16x32_bf16 v[4:7], v[202:205], v[242:245], v[4:7]
	v_mfma_f32_16x16x32_bf16 v[0:3], v[210:213], v[242:245], v[0:3]
	s_barrier
	s_add_i32 s12, 0, 0x18000
	v_add_u32_e32 v130, s12, v172
	s_add_i32 s15, 0, 0x1c000
	ds_read_b128 v[182:185], v130
	ds_read_b128 v[186:189], v130 offset:1024
	ds_read_b128 v[190:193], v130 offset:2048
	ds_read_b128 v[194:197], v130 offset:3072
	v_add_u32_e32 v130, s15, v172
	ds_read_b128 v[198:201], v130
	ds_read_b128 v[202:205], v130 offset:1024
	ds_read_b128 v[206:209], v130 offset:2048
	ds_read_b128 v[210:213], v130 offset:3072
	s_add_u32 s0, s48, 0x40000
	s_addc_u32 s1, s49, 0
	s_mov_b32 m0, s26
	v_lshl_add_u64 v[248:249], s[0:1], 0, v[140:141]
	ds_read_b128 v[214:217], v173 offset:32768
	ds_read_b128 v[218:221], v173 offset:33792
	ds_read_b128 v[222:225], v173 offset:34816
	ds_read_b128 v[226:229], v173 offset:35840
	ds_read_b128 v[230:233], v173 offset:36864
	ds_read_b128 v[234:237], v173 offset:37888
	ds_read_b128 v[238:241], v173 offset:38912
	ds_read_b128 v[242:245], v173 offset:39936
	global_load_lds_dwordx4 v[248:249], off
	v_lshl_add_u64 v[248:249], s[0:1], 0, v[138:139]
	s_mov_b32 m0, s27
	s_nop 0
	global_load_lds_dwordx4 v[248:249], off
	s_waitcnt vmcnt(8)
	s_waitcnt lgkmcnt(0)
	s_barrier
; #define PG8_STAGE(bufoff, gbase, voff) do { _Pragma("unroll") for (int _i = 0; _i < 2; ++_i) \
;         __builtin_amdgcn_global_load_lds((const unsigned*)((const char*)(gbase) + (voff)[_i]), (LAS unsigned*)(lds + (bufoff) + ldsw + _i * 8192), 16, 0, 0); } while (0)
; #define PG8_LDA(dst, b, h) do { _Pragma("unroll") for (int m = 0; m < 4; ++m) _Pragma("unroll") for (int k = 0; k < 2; ++k) dst[m][k] = *(const LAS bf16x8*)(lds + PG8_SA(b, h) + aoff + m * 2048 + k * 1024); } while (0)
; #define PG8_LDB(dst, b, h) do { _Pragma("unroll") for (int n = 0; n < 2; ++n) _Pragma("unroll") for (int k = 0; k < 2; ++k) dst[n][k] = *(const LAS bf16x8*)(lds + PG8_SB(b, h) + boff + n * 2048 + k * 1024); } while (0)
; #define PG8_MMA(ai, bj, At, Bt) do { __builtin_amdgcn_s_setprio(1); _Pragma("unroll") for (int m = 0; m < 4; ++m) _Pragma("unroll") for (int n = 0; n < 2; ++n) _Pragma("unroll") for (int k = 0; k < 2; ++k) \
;         acc[ai][bj][m][n] = __builtin_amdgcn_mfma_f32_16x16x32_bf16(Bt[n][k], At[m][k], acc[ai][bj][m][n], 0, 0, 0); __builtin_amdgcn_s_setprio(0); } while (0)
; #define PG8_WAIT_V(n) asm volatile("s_waitcnt vmcnt(" #n ")" ::: "memory")
; #define PG8_WAIT_L(n) asm volatile("s_waitcnt lgkmcnt(" #n ")" ::: "memory")
; #define PG8_BAR __builtin_amdgcn_s_barrier()
; #define PG8_SCHED __builtin_amdgcn_sched_barrier(0)
; template <class Epi, bool ALIGN_EPI>
; __device__ __forceinline__ void gemm_phase(LAS unsigned char* lds, const Gemm g, const StaticOrder S, const Epi E) {
;     ...
;             PG8_LDB(B0, 1, 0); PG8_LDB(B1, 1, 1); PG8_SCHED; PG8_LDA(At, 1, 0); PG8_STAGE(PG8_SA(0, 1), a2 + hstepA, voffA);
;             PG8_WAIT_V(8); PG8_WAIT_L(0); PG8_BAR; PG8_MMA(0, 0, At, B0); PG8_MMA(0, 1, At, B1); PG8_BAR; PG8_SCHED;
;             PG8_LDA(At, 1, 1); PG8_STAGE(PG8_SB(1, 0), b3, voffB); PG8_STAGE(PG8_SB(1, 1), b3 + hstepB, voffB); PG8_STAGE(PG8_SA(1, 0), a3, voffA);
;             PG8_WAIT_V(8); PG8_WAIT_L(0); PG8_BAR; PG8_MMA(1, 0, At, B0); PG8_MMA(1, 1, At, B1); PG8_BAR; PG8_SCHED;
;         }
	s_waitcnt lgkmcnt(0)
	v_mfma_f32_16x16x32_bf16 v[126:129], v[182:185], v[214:217], v[126:129]
	v_mfma_f32_16x16x32_bf16 v[118:121], v[190:193], v[214:217], v[118:121]
	v_mfma_f32_16x16x32_bf16 v[110:113], v[182:185], v[222:225], v[110:113]
	v_mfma_f32_16x16x32_bf16 v[106:109], v[190:193], v[222:225], v[106:109]
	v_mfma_f32_16x16x32_bf16 v[94:97], v[182:185], v[230:233], v[94:97]
	v_mfma_f32_16x16x32_bf16 v[86:89], v[190:193], v[230:233], v[86:89]
	v_mfma_f32_16x16x32_bf16 v[76:79], v[182:185], v[238:241], v[76:79]
	v_mfma_f32_16x16x32_bf16 v[72:75], v[190:193], v[238:241], v[72:75]
	v_mfma_f32_16x16x32_bf16 v[126:129], v[186:189], v[218:221], v[126:129]
	v_mfma_f32_16x16x32_bf16 v[118:121], v[194:197], v[218:221], v[118:121]
	v_mfma_f32_16x16x32_bf16 v[110:113], v[186:189], v[226:229], v[110:113]
	v_mfma_f32_16x16x32_bf16 v[106:109], v[194:197], v[226:229], v[106:109]
	v_mfma_f32_16x16x32_bf16 v[94:97], v[186:189], v[234:237], v[94:97]
	v_mfma_f32_16x16x32_bf16 v[86:89], v[194:197], v[234:237], v[86:89]
	v_mfma_f32_16x16x32_bf16 v[76:79], v[186:189], v[242:245], v[76:79]
	v_mfma_f32_16x16x32_bf16 v[72:75], v[194:197], v[242:245], v[72:75]
	v_mfma_f32_16x16x32_bf16 v[122:125], v[198:201], v[214:217], v[122:125]
	v_mfma_f32_16x16x32_bf16 v[114:117], v[206:209], v[214:217], v[114:117]
	v_mfma_f32_16x16x32_bf16 v[102:105], v[198:201], v[222:225], v[102:105]
	v_mfma_f32_16x16x32_bf16 v[98:101], v[206:209], v[222:225], v[98:101]
	v_mfma_f32_16x16x32_bf16 v[90:93], v[198:201], v[230:233], v[90:93]
	v_mfma_f32_16x16x32_bf16 v[82:85], v[206:209], v[230:233], v[82:85]
	v_mfma_f32_16x16x32_bf16 v[68:71], v[198:201], v[238:241], v[68:71]
	v_mfma_f32_16x16x32_bf16 v[64:67], v[206:209], v[238:241], v[64:67]
	v_mfma_f32_16x16x32_bf16 v[122:125], v[202:205], v[218:221], v[122:125]
	v_mfma_f32_16x16x32_bf16 v[114:117], v[210:213], v[218:221], v[114:117]
	v_mfma_f32_16x16x32_bf16 v[102:105], v[202:205], v[226:229], v[102:105]
	v_mfma_f32_16x16x32_bf16 v[98:101], v[210:213], v[226:229], v[98:101]
	v_mfma_f32_16x16x32_bf16 v[90:93], v[202:205], v[234:237], v[90:93]
	v_mfma_f32_16x16x32_bf16 v[82:85], v[210:213], v[234:237], v[82:85]
	v_mfma_f32_16x16x32_bf16 v[68:71], v[202:205], v[242:245], v[68:71]
	v_mfma_f32_16x16x32_bf16 v[64:67], v[210:213], v[242:245], v[64:67]
	s_barrier
	s_add_i32 s0, s12, s73
	v_lshl_add_u64 v[164:165], v[164:165], 0, s[80:81]
	s_mov_b32 m0, s0
	ds_read_b128 v[214:217], v173 offset:49152
	ds_read_b128 v[218:221], v173 offset:50176
	ds_read_b128 v[222:225], v173 offset:51200
	ds_read_b128 v[226:229], v173 offset:52224
	ds_read_b128 v[230:233], v173 offset:53248
	ds_read_b128 v[234:237], v173 offset:54272
	ds_read_b128 v[238:241], v173 offset:55296
	ds_read_b128 v[242:245], v173 offset:56320
	global_load_lds_dwordx4 v[164:165], off
	s_add_i32 m0, s0, 0x2000
	s_add_u32 s0, s46, 0x40080
	v_lshl_add_u64 v[164:165], v[176:177], 0, s[80:81]
	s_addc_u32 s1, s47, 0
	s_add_i32 s12, s15, s73
	global_load_lds_dwordx4 v[164:165], off
	v_lshl_add_u64 v[164:165], s[0:1], 0, v[80:81]
	s_mov_b32 m0, s12
	s_nop 0
	global_load_lds_dwordx4 v[164:165], off
	v_lshl_add_u64 v[164:165], s[0:1], 0, v[136:137]
	s_add_i32 m0, s12, 0x2000
	s_nop 0
	global_load_lds_dwordx4 v[164:165], off
	v_lshl_add_u64 v[164:165], v[178:179], 0, s[80:81]
	s_mov_b32 m0, s29
	s_nop 0
	global_load_lds_dwordx4 v[164:165], off
	v_lshl_add_u64 v[164:165], v[246:247], 0, s[80:81]
	s_mov_b32 m0, s30
	s_nop 0
	global_load_lds_dwordx4 v[164:165], off
	s_waitcnt vmcnt(8)
	s_waitcnt lgkmcnt(0)
	s_barrier
	s_waitcnt lgkmcnt(0)
	v_mfma_f32_16x16x32_bf16 v[60:63], v[182:185], v[214:217], v[60:63]
	v_mfma_f32_16x16x32_bf16 v[52:55], v[190:193], v[214:217], v[52:55]
	v_mfma_f32_16x16x32_bf16 v[44:47], v[182:185], v[222:225], v[44:47]
	v_mfma_f32_16x16x32_bf16 v[40:43], v[190:193], v[222:225], v[40:43]
	v_mfma_f32_16x16x32_bf16 v[28:31], v[182:185], v[230:233], v[28:31]
	v_mfma_f32_16x16x32_bf16 v[20:23], v[190:193], v[230:233], v[20:23]
	v_mfma_f32_16x16x32_bf16 v[12:15], v[182:185], v[238:241], v[12:15]
	v_mfma_f32_16x16x32_bf16 v[8:11], v[190:193], v[238:241], v[8:11]
	v_mfma_f32_16x16x32_bf16 v[60:63], v[186:189], v[218:221], v[60:63]
	v_mfma_f32_16x16x32_bf16 v[52:55], v[194:197], v[218:221], v[52:55]
	v_mfma_f32_16x16x32_bf16 v[44:47], v[186:189], v[226:229], v[44:47]
	v_mfma_f32_16x16x32_bf16 v[40:43], v[194:197], v[226:229], v[40:43]
	v_mfma_f32_16x16x32_bf16 v[28:31], v[186:189], v[234:237], v[28:31]
	v_mfma_f32_16x16x32_bf16 v[20:23], v[194:197], v[234:237], v[20:23]
	v_mfma_f32_16x16x32_bf16 v[12:15], v[186:189], v[242:245], v[12:15]
	v_mfma_f32_16x16x32_bf16 v[8:11], v[194:197], v[242:245], v[8:11]
	v_mfma_f32_16x16x32_bf16 v[56:59], v[198:201], v[214:217], v[56:59]
	v_mfma_f32_16x16x32_bf16 v[48:51], v[206:209], v[214:217], v[48:51]
	v_mfma_f32_16x16x32_bf16 v[36:39], v[198:201], v[222:225], v[36:39]
	v_mfma_f32_16x16x32_bf16 v[32:35], v[206:209], v[222:225], v[32:35]
	v_mfma_f32_16x16x32_bf16 v[24:27], v[198:201], v[230:233], v[24:27]
	v_mfma_f32_16x16x32_bf16 v[16:19], v[206:209], v[230:233], v[16:19]
	v_mfma_f32_16x16x32_bf16 v[4:7], v[198:201], v[238:241], v[4:7]
	v_mfma_f32_16x16x32_bf16 v[0:3], v[206:209], v[238:241], v[0:3]
	v_mfma_f32_16x16x32_bf16 v[56:59], v[202:205], v[218:221], v[56:59]
	v_mfma_f32_16x16x32_bf16 v[48:51], v[210:213], v[218:221], v[48:51]
	v_mfma_f32_16x16x32_bf16 v[36:39], v[202:205], v[226:229], v[36:39]
	v_mfma_f32_16x16x32_bf16 v[32:35], v[210:213], v[226:229], v[32:35]
	v_mfma_f32_16x16x32_bf16 v[24:27], v[202:205], v[234:237], v[24:27]
	v_mfma_f32_16x16x32_bf16 v[16:19], v[210:213], v[234:237], v[16:19]
	v_mfma_f32_16x16x32_bf16 v[4:7], v[202:205], v[242:245], v[4:7]
	v_mfma_f32_16x16x32_bf16 v[0:3], v[210:213], v[242:245], v[0:3]
	s_barrier
	s_add_i32 s54, s54, 2
	s_add_u32 s40, s40, 0x100
	s_addc_u32 s41, s41, 0
	s_add_u32 s52, s52, 0x100
	s_addc_u32 s53, s53, 0
	s_cmp_gt_u32 s54, 13
	s_cbranch_scc0 .LBB0_604
	s_setprio 0
	s_and_b64 vcc, exec, s[2:3]
	s_cbranch_vccz .LBB0_607
	s_barrier

; #define PG8_STAGE(bufoff, gbase, voff) do { _Pragma("unroll") for (int _i = 0; _i < 2; ++_i) \
;         __builtin_amdgcn_global_load_lds((const unsigned*)((const char*)(gbase) + (voff)[_i]), (LAS unsigned*)(lds + (bufoff) + ldsw + _i * 8192), 16, 0, 0); } while (0)
; #define PG8_LDA(dst, b, h) do { _Pragma("unroll") for (int m = 0; m < 4; ++m) _Pragma("unroll") for (int k = 0; k < 2; ++k) dst[m][k] = *(const LAS bf16x8*)(lds + PG8_SA(b, h) + aoff + m * 2048 + k * 1024); } while (0)
; #define PG8_LDB(dst, b, h) do { _Pragma("unroll") for (int n = 0; n < 2; ++n) _Pragma("unroll") for (int k = 0; k < 2; ++k) dst[n][k] = *(const LAS bf16x8*)(lds + PG8_SB(b, h) + boff + n * 2048 + k * 1024); } while (0)
; #define PG8_MMA(ai, bj, At, Bt) do { __builtin_amdgcn_s_setprio(1); _Pragma("unroll") for (int m = 0; m < 4; ++m) _Pragma("unroll") for (int n = 0; n < 2; ++n) _Pragma("unroll") for (int k = 0; k < 2; ++k) \
;         acc[ai][bj][m][n] = __builtin_amdgcn_mfma_f32_16x16x32_bf16(Bt[n][k], At[m][k], acc[ai][bj][m][n], 0, 0, 0); __builtin_amdgcn_s_setprio(0); } while (0)
; #define PG8_WAIT_V(n) asm volatile("s_waitcnt vmcnt(" #n ")" ::: "memory")
; #define PG8_WAIT_L(n) asm volatile("s_waitcnt lgkmcnt(" #n ")" ::: "memory")
; #define PG8_BAR __builtin_amdgcn_s_barrier()
; #define PG8_SCHED __builtin_amdgcn_sched_barrier(0)
; template <class Epi, bool ALIGN_EPI>
; __device__ __forceinline__ void gemm_phase(LAS unsigned char* lds, const Gemm g, const StaticOrder S, const Epi E) {
;     ...
;         for (int t = 0; t < nt; t += 2) {
;             const bool last = (t == nt - 2);
;             const char* a1 = cA + (size_t)(t + 1) * kstep;
;             const char* a2 = last ? nA : cA + (size_t)(t + 2) * kstep; const char* b2 = last ? nB : cB + (size_t)(t + 2) * kstep;
;             const char* a3 = a2 + kstep; const char* b3 = b2 + kstep;
;             PG8_LDB(B0, 0, 0); PG8_LDB(B1, 0, 1); PG8_SCHED; PG8_LDA(At, 0, 0); PG8_STAGE(PG8_SA(1, 1), a1 + hstepA, voffA);
;             PG8_WAIT_V(8); PG8_WAIT_L(0); PG8_BAR; PG8_MMA(0, 0, At, B0); PG8_MMA(0, 1, At, B1); PG8_BAR; PG8_SCHED;
;     ...
; #pragma unroll
;         for (int a = 0; a < 2; ++a)
; #pragma unroll
;             for (int b = 0; b < 2; ++b)
; #pragma unroll
;                 for (int m = 0; m < 4; ++m)
; #pragma unroll
;                     for (int n = 0; n < 2; ++n) acc[a][b][m][n] = (f32x4){0.f, 0.f, 0.f, 0.f};
.LBB0_727:
	s_add_u32 s28, s50, 0x100
	v_mov_b32_e32 v0, 0
	s_addc_u32 s29, s51, 0
	s_mov_b32 s30, -2
	v_mov_b32_e32 v1, 0
	v_mov_b64_e32 v[2:3], 0
	v_mov_b64_e32 v[4:5], 0
	v_mov_b64_e32 v[6:7], 0
	v_mov_b64_e32 v[8:9], 0
	v_mov_b64_e32 v[10:11], 0
	v_mov_b64_e32 v[12:13], 0
	v_mov_b64_e32 v[14:15], 0
	v_mov_b64_e32 v[16:17], 0
	v_mov_b64_e32 v[18:19], 0
	v_mov_b64_e32 v[20:21], 0
	v_mov_b64_e32 v[22:23], 0
	v_mov_b64_e32 v[24:25], 0
	v_mov_b64_e32 v[26:27], 0
	v_mov_b64_e32 v[28:29], 0
	v_mov_b64_e32 v[30:31], 0
	v_mov_b64_e32 v[32:33], 0
	v_mov_b64_e32 v[34:35], 0
	v_mov_b64_e32 v[36:37], 0
	v_mov_b64_e32 v[38:39], 0
	v_mov_b64_e32 v[40:41], 0
	v_mov_b64_e32 v[42:43], 0
	v_mov_b64_e32 v[44:45], 0
	v_mov_b64_e32 v[46:47], 0
	v_mov_b64_e32 v[48:49], 0
	v_mov_b64_e32 v[50:51], 0
	v_mov_b64_e32 v[52:53], 0
	v_mov_b64_e32 v[54:55], 0
	v_mov_b64_e32 v[56:57], 0
	v_mov_b64_e32 v[58:59], 0
	v_mov_b64_e32 v[60:61], 0
	v_mov_b64_e32 v[62:63], 0
	v_mov_b64_e32 v[64:65], 0
	v_mov_b64_e32 v[66:67], 0
	v_mov_b64_e32 v[68:69], 0
	v_mov_b64_e32 v[70:71], 0
	v_mov_b64_e32 v[72:73], 0
	v_mov_b64_e32 v[74:75], 0
	v_mov_b64_e32 v[76:77], 0
	v_mov_b64_e32 v[78:79], 0
	v_mov_b64_e32 v[82:83], 0
	v_mov_b64_e32 v[84:85], 0
	v_mov_b64_e32 v[86:87], 0
	v_mov_b64_e32 v[88:89], 0
	v_mov_b64_e32 v[90:91], 0
	v_mov_b64_e32 v[92:93], 0
	v_mov_b64_e32 v[94:95], 0
	v_mov_b64_e32 v[96:97], 0
	v_mov_b64_e32 v[98:99], 0
	v_mov_b64_e32 v[100:101], 0
	v_mov_b64_e32 v[102:103], 0
	v_mov_b64_e32 v[104:105], 0
	v_mov_b64_e32 v[106:107], 0
	v_mov_b64_e32 v[108:109], 0
	v_mov_b64_e32 v[110:111], 0
	v_mov_b64_e32 v[112:113], 0
	v_mov_b64_e32 v[114:115], 0
	v_mov_b64_e32 v[116:117], 0
	v_mov_b64_e32 v[118:119], 0
	v_mov_b64_e32 v[120:121], 0
	v_mov_b64_e32 v[122:123], 0
	v_mov_b64_e32 v[124:125], 0
	v_mov_b64_e32 v[126:127], 0
	v_mov_b64_e32 v[128:129], 0
	v_readfirstlane_b32 s0, v167
	s_nop 3
	s_cmpk_lt_u32 s0, 0x100
	s_cbranch_scc1 .Lprio_k1
	s_setprio 1
.Lprio_k1:
.LBB0_728:
	s_add_u32 s50, s48, 0x100
	s_addc_u32 s51, s49, 0
	s_add_i32 s0, 0, 0x10000
	s_cmp_eq_u32 s30, 40
	s_cselect_b32 s55, s43, s51
	s_cselect_b32 s54, s42, s50
	v_add_u32_e32 v130, s0, v152
	s_cselect_b32 s53, s47, s29
	s_cselect_b32 s52, s46, s28
	s_add_i32 s12, 0, 0x14000
	ds_read_b128 v[146:149], v130
	ds_read_b128 v[154:157], v130 offset:1024
	ds_read_b128 v[158:161], v130 offset:2048
	ds_read_b128 v[162:165], v130 offset:3072
	v_add_u32_e32 v130, s12, v152
	ds_read_b128 v[182:185], v130
	ds_read_b128 v[186:189], v130 offset:1024
	ds_read_b128 v[190:193], v130 offset:2048
	ds_read_b128 v[194:197], v130 offset:3072
	v_lshl_add_u64 v[168:169], s[48:49], 0, v[142:143]
	s_add_i32 m0, s66, 0xc000
	ds_read_b128 v[198:201], v153
	ds_read_b128 v[202:205], v153 offset:1024
	ds_read_b128 v[206:209], v153 offset:2048
	ds_read_b128 v[210:213], v153 offset:3072
	ds_read_b128 v[214:217], v153 offset:4096
	ds_read_b128 v[218:221], v153 offset:5120
	ds_read_b128 v[222:225], v153 offset:6144
	ds_read_b128 v[226:229], v153 offset:7168
	global_load_lds_dwordx4 v[168:169], off
	v_lshl_add_u64 v[168:169], s[48:49], 0, v[144:145]
	s_add_i32 m0, s66, 0xe000
	s_nop 0
	global_load_lds_dwordx4 v[168:169], off
	s_waitcnt vmcnt(8)
	s_waitcnt lgkmcnt(0)
	s_barrier
	s_waitcnt lgkmcnt(0)
	v_mfma_f32_16x16x32_bf16 v[126:129], v[146:149], v[198:201], v[126:129]
	v_mfma_f32_16x16x32_bf16 v[122:125], v[158:161], v[198:201], v[122:125]
	v_mfma_f32_16x16x32_bf16 v[110:113], v[146:149], v[206:209], v[110:113]
	v_mfma_f32_16x16x32_bf16 v[106:109], v[158:161], v[206:209], v[106:109]
	v_mfma_f32_16x16x32_bf16 v[94:97], v[146:149], v[214:217], v[94:97]
	v_mfma_f32_16x16x32_bf16 v[90:93], v[158:161], v[214:217], v[90:93]
	v_mfma_f32_16x16x32_bf16 v[76:79], v[146:149], v[222:225], v[76:79]
	v_mfma_f32_16x16x32_bf16 v[72:75], v[158:161], v[222:225], v[72:75]
	v_mfma_f32_16x16x32_bf16 v[126:129], v[154:157], v[202:205], v[126:129]
	v_mfma_f32_16x16x32_bf16 v[122:125], v[162:165], v[202:205], v[122:125]
	v_mfma_f32_16x16x32_bf16 v[110:113], v[154:157], v[210:213], v[110:113]
	v_mfma_f32_16x16x32_bf16 v[106:109], v[162:165], v[210:213], v[106:109]
	v_mfma_f32_16x16x32_bf16 v[94:97], v[154:157], v[218:221], v[94:97]
	v_mfma_f32_16x16x32_bf16 v[90:93], v[162:165], v[218:221], v[90:93]
	v_mfma_f32_16x16x32_bf16 v[76:79], v[154:157], v[226:229], v[76:79]
	v_mfma_f32_16x16x32_bf16 v[72:75], v[162:165], v[226:229], v[72:75]
	v_mfma_f32_16x16x32_bf16 v[118:121], v[182:185], v[198:201], v[118:121]
	v_mfma_f32_16x16x32_bf16 v[114:117], v[190:193], v[198:201], v[114:117]
	v_mfma_f32_16x16x32_bf16 v[102:105], v[182:185], v[206:209], v[102:105]
	v_mfma_f32_16x16x32_bf16 v[98:101], v[190:193], v[206:209], v[98:101]
	v_mfma_f32_16x16x32_bf16 v[86:89], v[182:185], v[214:217], v[86:89]
	v_mfma_f32_16x16x32_bf16 v[82:85], v[190:193], v[214:217], v[82:85]
	v_mfma_f32_16x16x32_bf16 v[68:71], v[182:185], v[222:225], v[68:71]
	v_mfma_f32_16x16x32_bf16 v[64:67], v[190:193], v[222:225], v[64:67]
	v_mfma_f32_16x16x32_bf16 v[118:121], v[186:189], v[202:205], v[118:121]
	v_mfma_f32_16x16x32_bf16 v[114:117], v[194:197], v[202:205], v[114:117]
	v_mfma_f32_16x16x32_bf16 v[102:105], v[186:189], v[210:213], v[102:105]
	v_mfma_f32_16x16x32_bf16 v[98:101], v[194:197], v[210:213], v[98:101]
	v_mfma_f32_16x16x32_bf16 v[86:89], v[186:189], v[218:221], v[86:89]
	v_mfma_f32_16x16x32_bf16 v[82:85], v[194:197], v[218:221], v[82:85]
	v_mfma_f32_16x16x32_bf16 v[68:71], v[186:189], v[226:229], v[68:71]
	v_mfma_f32_16x16x32_bf16 v[64:67], v[194:197], v[226:229], v[64:67]
	s_barrier
; #define PG8_STAGE(bufoff, gbase, voff) do { _Pragma("unroll") for (int _i = 0; _i < 2; ++_i) \
;         __builtin_amdgcn_global_load_lds((const unsigned*)((const char*)(gbase) + (voff)[_i]), (LAS unsigned*)(lds + (bufoff) + ldsw + _i * 8192), 16, 0, 0); } while (0)
; #define PG8_LDA(dst, b, h) do { _Pragma("unroll") for (int m = 0; m < 4; ++m) _Pragma("unroll") for (int k = 0; k < 2; ++k) dst[m][k] = *(const LAS bf16x8*)(lds + PG8_SA(b, h) + aoff + m * 2048 + k * 1024); } while (0)
; #define PG8_LDB(dst, b, h) do { _Pragma("unroll") for (int n = 0; n < 2; ++n) _Pragma("unroll") for (int k = 0; k < 2; ++k) dst[n][k] = *(const LAS bf16x8*)(lds + PG8_SB(b, h) + boff + n * 2048 + k * 1024); } while (0)
; #define PG8_MMA(ai, bj, At, Bt) do { __builtin_amdgcn_s_setprio(1); _Pragma("unroll") for (int m = 0; m < 4; ++m) _Pragma("unroll") for (int n = 0; n < 2; ++n) _Pragma("unroll") for (int k = 0; k < 2; ++k) \
;         acc[ai][bj][m][n] = __builtin_amdgcn_mfma_f32_16x16x32_bf16(Bt[n][k], At[m][k], acc[ai][bj][m][n], 0, 0, 0); __builtin_amdgcn_s_setprio(0); } while (0)
; #define PG8_WAIT_V(n) asm volatile("s_waitcnt vmcnt(" #n ")" ::: "memory")
; #define PG8_WAIT_L(n) asm volatile("s_waitcnt lgkmcnt(" #n ")" ::: "memory")
; #define PG8_BAR __builtin_amdgcn_s_barrier()
; #define PG8_SCHED __builtin_amdgcn_sched_barrier(0)
; template <class Epi, bool ALIGN_EPI>
; __device__ __forceinline__ void gemm_phase(LAS unsigned char* lds, const Gemm g, const StaticOrder S, const Epi E) {
;     ...
;             PG8_LDA(At, 0, 1); PG8_STAGE(PG8_SB(0, 0), b2, voffB); PG8_STAGE(PG8_SB(0, 1), b2 + hstepB, voffB); PG8_STAGE(PG8_SA(0, 0), a2, voffA);
;             PG8_WAIT_V(8); PG8_WAIT_L(0); PG8_BAR; PG8_MMA(1, 0, At, B0); PG8_MMA(1, 1, At, B1); PG8_BAR; PG8_SCHED;
;             PG8_LDB(B0, 1, 0); PG8_LDB(B1, 1, 1); PG8_SCHED; PG8_LDA(At, 1, 0); PG8_STAGE(PG8_SA(0, 1), a2 + hstepA, voffA);
;             PG8_WAIT_V(8); PG8_WAIT_L(0); PG8_BAR; PG8_MMA(0, 0, At, B0); PG8_MMA(0, 1, At, B1); PG8_BAR; PG8_SCHED;
	s_add_i32 s0, s0, s65
	v_lshl_add_u64 v[168:169], s[52:53], 0, v[80:81]
	s_mov_b32 m0, s0
	ds_read_b128 v[198:201], v153 offset:16384
	ds_read_b128 v[202:205], v153 offset:17408
	ds_read_b128 v[206:209], v153 offset:18432
	ds_read_b128 v[210:213], v153 offset:19456
	ds_read_b128 v[214:217], v153 offset:20480
	ds_read_b128 v[218:221], v153 offset:21504
	ds_read_b128 v[222:225], v153 offset:22528
	ds_read_b128 v[226:229], v153 offset:23552
	global_load_lds_dwordx4 v[168:169], off
	s_add_i32 m0, s0, 0x2000
	s_add_u32 s0, s52, 0xb0000
	v_lshl_add_u64 v[170:171], s[52:53], 0, v[140:141]
	s_addc_u32 s1, s53, 0
	s_add_i32 s12, s12, s65
	global_load_lds_dwordx4 v[170:171], off
	v_lshl_add_u64 v[172:173], s[0:1], 0, v[80:81]
	s_mov_b32 m0, s12
	v_lshl_add_u64 v[176:177], s[54:55], 0, v[138:139]
	global_load_lds_dwordx4 v[172:173], off
	v_lshl_add_u64 v[172:173], s[0:1], 0, v[140:141]
	s_add_i32 m0, s12, 0x2000
	s_nop 0
	global_load_lds_dwordx4 v[172:173], off
	v_lshl_add_u64 v[172:173], s[54:55], 0, v[136:137]
	s_mov_b32 m0, s66
	s_nop 0
	global_load_lds_dwordx4 v[172:173], off
	s_mov_b32 m0, s67
	s_nop 0
	global_load_lds_dwordx4 v[176:177], off
	s_waitcnt vmcnt(8)
	s_waitcnt lgkmcnt(0)
	s_barrier
	s_waitcnt lgkmcnt(0)
	v_mfma_f32_16x16x32_bf16 v[60:63], v[146:149], v[198:201], v[60:63]
	v_mfma_f32_16x16x32_bf16 v[56:59], v[158:161], v[198:201], v[56:59]
	v_mfma_f32_16x16x32_bf16 v[44:47], v[146:149], v[206:209], v[44:47]
	v_mfma_f32_16x16x32_bf16 v[40:43], v[158:161], v[206:209], v[40:43]
	v_mfma_f32_16x16x32_bf16 v[28:31], v[146:149], v[214:217], v[28:31]
	v_mfma_f32_16x16x32_bf16 v[24:27], v[158:161], v[214:217], v[24:27]
	v_mfma_f32_16x16x32_bf16 v[12:15], v[146:149], v[222:225], v[12:15]
	v_mfma_f32_16x16x32_bf16 v[8:11], v[158:161], v[222:225], v[8:11]
	v_mfma_f32_16x16x32_bf16 v[60:63], v[154:157], v[202:205], v[60:63]
	v_mfma_f32_16x16x32_bf16 v[56:59], v[162:165], v[202:205], v[56:59]
	v_mfma_f32_16x16x32_bf16 v[44:47], v[154:157], v[210:213], v[44:47]
	v_mfma_f32_16x16x32_bf16 v[40:43], v[162:165], v[210:213], v[40:43]
	v_mfma_f32_16x16x32_bf16 v[28:31], v[154:157], v[218:221], v[28:31]
	v_mfma_f32_16x16x32_bf16 v[24:27], v[162:165], v[218:221], v[24:27]
	v_mfma_f32_16x16x32_bf16 v[12:15], v[154:157], v[226:229], v[12:15]
	v_mfma_f32_16x16x32_bf16 v[8:11], v[162:165], v[226:229], v[8:11]
	v_mfma_f32_16x16x32_bf16 v[52:55], v[182:185], v[198:201], v[52:55]
	v_mfma_f32_16x16x32_bf16 v[48:51], v[190:193], v[198:201], v[48:51]
	v_mfma_f32_16x16x32_bf16 v[36:39], v[182:185], v[206:209], v[36:39]
	v_mfma_f32_16x16x32_bf16 v[32:35], v[190:193], v[206:209], v[32:35]
	v_mfma_f32_16x16x32_bf16 v[20:23], v[182:185], v[214:217], v[20:23]
	v_mfma_f32_16x16x32_bf16 v[16:19], v[190:193], v[214:217], v[16:19]
	v_mfma_f32_16x16x32_bf16 v[4:7], v[182:185], v[222:225], v[4:7]
	v_mfma_f32_16x16x32_bf16 v[0:3], v[190:193], v[222:225], v[0:3]
	v_mfma_f32_16x16x32_bf16 v[52:55], v[186:189], v[202:205], v[52:55]
	v_mfma_f32_16x16x32_bf16 v[48:51], v[194:197], v[202:205], v[48:51]
	v_mfma_f32_16x16x32_bf16 v[36:39], v[186:189], v[210:213], v[36:39]
	v_mfma_f32_16x16x32_bf16 v[32:35], v[194:197], v[210:213], v[32:35]
	v_mfma_f32_16x16x32_bf16 v[20:23], v[186:189], v[218:221], v[20:23]
	v_mfma_f32_16x16x32_bf16 v[16:19], v[194:197], v[218:221], v[16:19]
	v_mfma_f32_16x16x32_bf16 v[4:7], v[186:189], v[226:229], v[4:7]
	v_mfma_f32_16x16x32_bf16 v[0:3], v[194:197], v[226:229], v[0:3]
	s_barrier
	s_add_i32 s12, 0, 0x18000
	v_add_u32_e32 v130, s12, v152
	s_add_i32 s15, 0, 0x1c000
	ds_read_b128 v[146:149], v130
	ds_read_b128 v[154:157], v130 offset:1024
	ds_read_b128 v[158:161], v130 offset:2048
	ds_read_b128 v[162:165], v130 offset:3072
	v_add_u32_e32 v130, s15, v152
	ds_read_b128 v[182:185], v130
	ds_read_b128 v[186:189], v130 offset:1024
	ds_read_b128 v[190:193], v130 offset:2048
	ds_read_b128 v[194:197], v130 offset:3072
	s_add_u32 s0, s54, 0xb0000
	s_addc_u32 s1, s55, 0
	s_mov_b32 m0, s68
	v_lshl_add_u64 v[178:179], s[0:1], 0, v[136:137]
	ds_read_b128 v[198:201], v153 offset:32768
	ds_read_b128 v[202:205], v153 offset:33792
	ds_read_b128 v[206:209], v153 offset:34816
	ds_read_b128 v[210:213], v153 offset:35840
	ds_read_b128 v[214:217], v153 offset:36864
	ds_read_b128 v[218:221], v153 offset:37888
	ds_read_b128 v[222:225], v153 offset:38912
	ds_read_b128 v[226:229], v153 offset:39936
	global_load_lds_dwordx4 v[178:179], off
	v_lshl_add_u64 v[178:179], s[0:1], 0, v[138:139]
	s_mov_b32 m0, s69
	s_nop 0
	global_load_lds_dwordx4 v[178:179], off
	s_waitcnt vmcnt(8)
	s_waitcnt lgkmcnt(0)
	s_barrier
; #define PG8_STAGE(bufoff, gbase, voff) do { _Pragma("unroll") for (int _i = 0; _i < 2; ++_i) \
;         __builtin_amdgcn_global_load_lds((const unsigned*)((const char*)(gbase) + (voff)[_i]), (LAS unsigned*)(lds + (bufoff) + ldsw + _i * 8192), 16, 0, 0); } while (0)
; #define PG8_LDA(dst, b, h) do { _Pragma("unroll") for (int m = 0; m < 4; ++m) _Pragma("unroll") for (int k = 0; k < 2; ++k) dst[m][k] = *(const LAS bf16x8*)(lds + PG8_SA(b, h) + aoff + m * 2048 + k * 1024); } while (0)
; #define PG8_MMA(ai, bj, At, Bt) do { __builtin_amdgcn_s_setprio(1); _Pragma("unroll") for (int m = 0; m < 4; ++m) _Pragma("unroll") for (int n = 0; n < 2; ++n) _Pragma("unroll") for (int k = 0; k < 2; ++k) \
;         acc[ai][bj][m][n] = __builtin_amdgcn_mfma_f32_16x16x32_bf16(Bt[n][k], At[m][k], acc[ai][bj][m][n], 0, 0, 0); __builtin_amdgcn_s_setprio(0); } while (0)
; #define PG8_WAIT_V(n) asm volatile("s_waitcnt vmcnt(" #n ")" ::: "memory")
; #define PG8_WAIT_L(n) asm volatile("s_waitcnt lgkmcnt(" #n ")" ::: "memory")
; #define PG8_BAR __builtin_amdgcn_s_barrier()
; #define PG8_SCHED __builtin_amdgcn_sched_barrier(0)
; template <class Epi, bool ALIGN_EPI>
; __device__ __forceinline__ void gemm_phase(LAS unsigned char* lds, const Gemm g, const StaticOrder S, const Epi E) {
;     ...
;             PG8_WAIT_V(8); PG8_WAIT_L(0); PG8_BAR; PG8_MMA(0, 0, At, B0); PG8_MMA(0, 1, At, B1); PG8_BAR; PG8_SCHED;
;             PG8_LDA(At, 1, 1); PG8_STAGE(PG8_SB(1, 0), b3, voffB); PG8_STAGE(PG8_SB(1, 1), b3 + hstepB, voffB); PG8_STAGE(PG8_SA(1, 0), a3, voffA);
;             PG8_WAIT_V(8); PG8_WAIT_L(0); PG8_BAR; PG8_MMA(1, 0, At, B0); PG8_MMA(1, 1, At, B1); PG8_BAR; PG8_SCHED;
;         }
;         if constexpr (ALIGN_EPI) { if (wr == 0) PG8_BAR; }
	s_waitcnt lgkmcnt(0)
	v_mfma_f32_16x16x32_bf16 v[126:129], v[146:149], v[198:201], v[126:129]
	v_mfma_f32_16x16x32_bf16 v[122:125], v[158:161], v[198:201], v[122:125]
	v_mfma_f32_16x16x32_bf16 v[110:113], v[146:149], v[206:209], v[110:113]
	v_mfma_f32_16x16x32_bf16 v[106:109], v[158:161], v[206:209], v[106:109]
	v_mfma_f32_16x16x32_bf16 v[94:97], v[146:149], v[214:217], v[94:97]
	v_mfma_f32_16x16x32_bf16 v[90:93], v[158:161], v[214:217], v[90:93]
	v_mfma_f32_16x16x32_bf16 v[76:79], v[146:149], v[222:225], v[76:79]
	v_mfma_f32_16x16x32_bf16 v[72:75], v[158:161], v[222:225], v[72:75]
	v_mfma_f32_16x16x32_bf16 v[126:129], v[154:157], v[202:205], v[126:129]
	v_mfma_f32_16x16x32_bf16 v[122:125], v[162:165], v[202:205], v[122:125]
	v_mfma_f32_16x16x32_bf16 v[110:113], v[154:157], v[210:213], v[110:113]
	v_mfma_f32_16x16x32_bf16 v[106:109], v[162:165], v[210:213], v[106:109]
	v_mfma_f32_16x16x32_bf16 v[94:97], v[154:157], v[218:221], v[94:97]
	v_mfma_f32_16x16x32_bf16 v[90:93], v[162:165], v[218:221], v[90:93]
	v_mfma_f32_16x16x32_bf16 v[76:79], v[154:157], v[226:229], v[76:79]
	v_mfma_f32_16x16x32_bf16 v[72:75], v[162:165], v[226:229], v[72:75]
	v_mfma_f32_16x16x32_bf16 v[118:121], v[182:185], v[198:201], v[118:121]
	v_mfma_f32_16x16x32_bf16 v[114:117], v[190:193], v[198:201], v[114:117]
	v_mfma_f32_16x16x32_bf16 v[102:105], v[182:185], v[206:209], v[102:105]
	v_mfma_f32_16x16x32_bf16 v[98:101], v[190:193], v[206:209], v[98:101]
	v_mfma_f32_16x16x32_bf16 v[86:89], v[182:185], v[214:217], v[86:89]
	v_mfma_f32_16x16x32_bf16 v[82:85], v[190:193], v[214:217], v[82:85]
	v_mfma_f32_16x16x32_bf16 v[68:71], v[182:185], v[222:225], v[68:71]
	v_mfma_f32_16x16x32_bf16 v[64:67], v[190:193], v[222:225], v[64:67]
	v_mfma_f32_16x16x32_bf16 v[118:121], v[186:189], v[202:205], v[118:121]
	v_mfma_f32_16x16x32_bf16 v[114:117], v[194:197], v[202:205], v[114:117]
	v_mfma_f32_16x16x32_bf16 v[102:105], v[186:189], v[210:213], v[102:105]
	v_mfma_f32_16x16x32_bf16 v[98:101], v[194:197], v[210:213], v[98:101]
	v_mfma_f32_16x16x32_bf16 v[86:89], v[186:189], v[218:221], v[86:89]
	v_mfma_f32_16x16x32_bf16 v[82:85], v[194:197], v[218:221], v[82:85]
	v_mfma_f32_16x16x32_bf16 v[68:71], v[186:189], v[226:229], v[68:71]
	v_mfma_f32_16x16x32_bf16 v[64:67], v[194:197], v[226:229], v[64:67]
	s_barrier
	s_add_i32 s0, s12, s65
	v_lshl_add_u64 v[168:169], v[168:169], 0, s[80:81]
	s_mov_b32 m0, s0
	ds_read_b128 v[198:201], v153 offset:49152
	ds_read_b128 v[202:205], v153 offset:50176
	ds_read_b128 v[206:209], v153 offset:51200
	ds_read_b128 v[210:213], v153 offset:52224
	ds_read_b128 v[214:217], v153 offset:53248
	ds_read_b128 v[218:221], v153 offset:54272
	ds_read_b128 v[222:225], v153 offset:55296
	ds_read_b128 v[226:229], v153 offset:56320
	global_load_lds_dwordx4 v[168:169], off
	s_add_i32 m0, s0, 0x2000
	s_add_u32 s0, s52, 0xb0080
	v_lshl_add_u64 v[168:169], v[170:171], 0, s[80:81]
	s_addc_u32 s1, s53, 0
	s_add_i32 s12, s15, s65
	global_load_lds_dwordx4 v[168:169], off
	v_lshl_add_u64 v[168:169], s[0:1], 0, v[80:81]
	s_mov_b32 m0, s12
	s_nop 0
	global_load_lds_dwordx4 v[168:169], off
	v_lshl_add_u64 v[168:169], s[0:1], 0, v[140:141]
	s_add_i32 m0, s12, 0x2000
	s_nop 0
	global_load_lds_dwordx4 v[168:169], off
	v_lshl_add_u64 v[168:169], v[172:173], 0, s[80:81]
	s_mov_b32 m0, s73
	s_nop 0
	global_load_lds_dwordx4 v[168:169], off
	v_lshl_add_u64 v[168:169], v[176:177], 0, s[80:81]
	s_mov_b32 m0, s74
	s_nop 0
	global_load_lds_dwordx4 v[168:169], off
	s_waitcnt vmcnt(8)
	s_waitcnt lgkmcnt(0)
	s_barrier
	s_waitcnt lgkmcnt(0)
	v_mfma_f32_16x16x32_bf16 v[60:63], v[146:149], v[198:201], v[60:63]
	v_mfma_f32_16x16x32_bf16 v[56:59], v[158:161], v[198:201], v[56:59]
	v_mfma_f32_16x16x32_bf16 v[44:47], v[146:149], v[206:209], v[44:47]
	v_mfma_f32_16x16x32_bf16 v[40:43], v[158:161], v[206:209], v[40:43]
	v_mfma_f32_16x16x32_bf16 v[28:31], v[146:149], v[214:217], v[28:31]
	v_mfma_f32_16x16x32_bf16 v[24:27], v[158:161], v[214:217], v[24:27]
	v_mfma_f32_16x16x32_bf16 v[12:15], v[146:149], v[222:225], v[12:15]
	v_mfma_f32_16x16x32_bf16 v[8:11], v[158:161], v[222:225], v[8:11]
	v_mfma_f32_16x16x32_bf16 v[60:63], v[154:157], v[202:205], v[60:63]
	v_mfma_f32_16x16x32_bf16 v[56:59], v[162:165], v[202:205], v[56:59]
	v_mfma_f32_16x16x32_bf16 v[44:47], v[154:157], v[210:213], v[44:47]
	v_mfma_f32_16x16x32_bf16 v[40:43], v[162:165], v[210:213], v[40:43]
	v_mfma_f32_16x16x32_bf16 v[28:31], v[154:157], v[218:221], v[28:31]
	v_mfma_f32_16x16x32_bf16 v[24:27], v[162:165], v[218:221], v[24:27]
	v_mfma_f32_16x16x32_bf16 v[12:15], v[154:157], v[226:229], v[12:15]
	v_mfma_f32_16x16x32_bf16 v[8:11], v[162:165], v[226:229], v[8:11]
	v_mfma_f32_16x16x32_bf16 v[52:55], v[182:185], v[198:201], v[52:55]
	v_mfma_f32_16x16x32_bf16 v[48:51], v[190:193], v[198:201], v[48:51]
	v_mfma_f32_16x16x32_bf16 v[36:39], v[182:185], v[206:209], v[36:39]
	v_mfma_f32_16x16x32_bf16 v[32:35], v[190:193], v[206:209], v[32:35]
	v_mfma_f32_16x16x32_bf16 v[20:23], v[182:185], v[214:217], v[20:23]
	v_mfma_f32_16x16x32_bf16 v[16:19], v[190:193], v[214:217], v[16:19]
	v_mfma_f32_16x16x32_bf16 v[4:7], v[182:185], v[222:225], v[4:7]
	v_mfma_f32_16x16x32_bf16 v[0:3], v[190:193], v[222:225], v[0:3]
	v_mfma_f32_16x16x32_bf16 v[52:55], v[186:189], v[202:205], v[52:55]
	v_mfma_f32_16x16x32_bf16 v[48:51], v[194:197], v[202:205], v[48:51]
	v_mfma_f32_16x16x32_bf16 v[36:39], v[186:189], v[210:213], v[36:39]
	v_mfma_f32_16x16x32_bf16 v[32:35], v[194:197], v[210:213], v[32:35]
	v_mfma_f32_16x16x32_bf16 v[20:23], v[186:189], v[218:221], v[20:23]
	v_mfma_f32_16x16x32_bf16 v[16:19], v[194:197], v[218:221], v[16:19]
	v_mfma_f32_16x16x32_bf16 v[4:7], v[186:189], v[226:229], v[4:7]
	v_mfma_f32_16x16x32_bf16 v[0:3], v[194:197], v[226:229], v[0:3]
	s_barrier
	s_add_i32 s30, s30, 2
	s_add_u32 s28, s28, 0x100
	s_addc_u32 s29, s29, 0
	s_cmp_gt_u32 s30, 41
	s_mov_b64 s[48:49], s[50:51]
	s_cbranch_scc0 .LBB0_728
	s_setprio 0
	s_and_b64 vcc, exec, s[44:45]
	s_cbranch_vccz .LBB0_731
	s_barrier

; #define PG8_STAGE(bufoff, gbase, voff) do { _Pragma("unroll") for (int _i = 0; _i < 2; ++_i) \
;         __builtin_amdgcn_global_load_lds((const unsigned*)((const char*)(gbase) + (voff)[_i]), (LAS unsigned*)(lds + (bufoff) + ldsw + _i * 8192), 16, 0, 0); } while (0)
; #define PG8_LDA(dst, b, h) do { _Pragma("unroll") for (int m = 0; m < 4; ++m) _Pragma("unroll") for (int k = 0; k < 2; ++k) dst[m][k] = *(const LAS bf16x8*)(lds + PG8_SA(b, h) + aoff + m * 2048 + k * 1024); } while (0)
; #define PG8_LDB(dst, b, h) do { _Pragma("unroll") for (int n = 0; n < 2; ++n) _Pragma("unroll") for (int k = 0; k < 2; ++k) dst[n][k] = *(const LAS bf16x8*)(lds + PG8_SB(b, h) + boff + n * 2048 + k * 1024); } while (0)
; #define PG8_MMA(ai, bj, At, Bt) do { __builtin_amdgcn_s_setprio(1); _Pragma("unroll") for (int m = 0; m < 4; ++m) _Pragma("unroll") for (int n = 0; n < 2; ++n) _Pragma("unroll") for (int k = 0; k < 2; ++k) \
;         acc[ai][bj][m][n] = __builtin_amdgcn_mfma_f32_16x16x32_bf16(Bt[n][k], At[m][k], acc[ai][bj][m][n], 0, 0, 0); __builtin_amdgcn_s_setprio(0); } while (0)
; #define PG8_WAIT_V(n) asm volatile("s_waitcnt vmcnt(" #n ")" ::: "memory")
; #define PG8_WAIT_L(n) asm volatile("s_waitcnt lgkmcnt(" #n ")" ::: "memory")
; #define PG8_BAR __builtin_amdgcn_s_barrier()
; #define PG8_SCHED __builtin_amdgcn_sched_barrier(0)
; template <class Epi, bool ALIGN_EPI>
; __device__ __forceinline__ void gemm_phase(LAS unsigned char* lds, const Gemm g, const StaticOrder S, const Epi E) {
;     ...
;             const bool last = (t == nt - 2);
;             const char* a1 = cA + (size_t)(t + 1) * kstep;
;             const char* a2 = last ? nA : cA + (size_t)(t + 2) * kstep; const char* b2 = last ? nB : cB + (size_t)(t + 2) * kstep;
;             const char* a3 = a2 + kstep; const char* b3 = b2 + kstep;
;             PG8_LDB(B0, 0, 0); PG8_LDB(B1, 0, 1); PG8_SCHED; PG8_LDA(At, 0, 0); PG8_STAGE(PG8_SA(1, 1), a1 + hstepA, voffA);
;             PG8_WAIT_V(8); PG8_WAIT_L(0); PG8_BAR; PG8_MMA(0, 0, At, B0); PG8_MMA(0, 1, At, B1); PG8_BAR; PG8_SCHED;
;     ...
; #pragma unroll
;         for (int a = 0; a < 2; ++a)
; #pragma unroll
;             for (int b = 0; b < 2; ++b)
; #pragma unroll
;                 for (int m = 0; m < 4; ++m)
; #pragma unroll
;                     for (int n = 0; n < 2; ++n) acc[a][b][m][n] = (f32x4){0.f, 0.f, 0.f, 0.f};
;         cur = nxt; cA = nA; cB = nB; ++ui;
.LBB0_852:
	s_ashr_i32 s53, s52, 31
	s_lshl_b64 s[0:1], s[52:53], 19
	s_add_u32 s62, s94, s0
	s_addc_u32 s63, s95, s1
	s_and_b64 s[0:1], s[42:43], exec
	s_cselect_b32 s34, s63, s67
	s_cselect_b32 s35, s62, s66
	s_ashr_i32 s51, s50, 31
	s_lshl_b64 s[0:1], s[50:51], 19
	v_readlane_b32 s2, v255, 14
	s_add_u32 s64, s2, s0
	v_readlane_b32 s0, v255, 15
	s_addc_u32 s65, s0, s1
	s_and_b64 s[0:1], s[42:43], exec
	s_cselect_b32 s51, s65, s45
	s_cselect_b32 s53, s64, s44
	s_add_u32 s2, s66, 0x40080
	s_addc_u32 s3, s67, 0
	s_add_u32 s58, s44, 0x100
	v_mov_b32_e32 v0, 0
	s_addc_u32 s61, s45, 0
	s_mov_b32 s68, -2
	v_mov_b32_e32 v1, 0
	v_mov_b64_e32 v[2:3], 0
	v_mov_b64_e32 v[4:5], 0
	v_mov_b64_e32 v[6:7], 0
	v_mov_b64_e32 v[8:9], 0
	v_mov_b64_e32 v[10:11], 0
	v_mov_b64_e32 v[12:13], 0
	v_mov_b64_e32 v[14:15], 0
	v_mov_b64_e32 v[16:17], 0
	v_mov_b64_e32 v[18:19], 0
	v_mov_b64_e32 v[20:21], 0
	v_mov_b64_e32 v[22:23], 0
	v_mov_b64_e32 v[24:25], 0
	v_mov_b64_e32 v[26:27], 0
	v_mov_b64_e32 v[28:29], 0
	v_mov_b64_e32 v[30:31], 0
	v_mov_b64_e32 v[32:33], 0
	v_mov_b64_e32 v[34:35], 0
	v_mov_b64_e32 v[36:37], 0
	v_mov_b64_e32 v[38:39], 0
	v_mov_b64_e32 v[40:41], 0
	v_mov_b64_e32 v[42:43], 0
	v_mov_b64_e32 v[44:45], 0
	v_mov_b64_e32 v[46:47], 0
	v_mov_b64_e32 v[48:49], 0
	v_mov_b64_e32 v[50:51], 0
	v_mov_b64_e32 v[52:53], 0
	v_mov_b64_e32 v[54:55], 0
	v_mov_b64_e32 v[56:57], 0
	v_mov_b64_e32 v[58:59], 0
	v_mov_b64_e32 v[60:61], 0
	v_mov_b64_e32 v[62:63], 0
	v_mov_b64_e32 v[64:65], 0
	v_mov_b64_e32 v[66:67], 0
	v_mov_b64_e32 v[68:69], 0
	v_mov_b64_e32 v[70:71], 0
	v_mov_b64_e32 v[72:73], 0
	v_mov_b64_e32 v[74:75], 0
	v_mov_b64_e32 v[76:77], 0
	v_mov_b64_e32 v[78:79], 0
	v_mov_b64_e32 v[82:83], 0
	v_mov_b64_e32 v[84:85], 0
	v_mov_b64_e32 v[86:87], 0
	v_mov_b64_e32 v[88:89], 0
	v_mov_b64_e32 v[90:91], 0
	v_mov_b64_e32 v[92:93], 0
	v_mov_b64_e32 v[94:95], 0
	v_mov_b64_e32 v[96:97], 0
	v_mov_b64_e32 v[98:99], 0
	v_mov_b64_e32 v[100:101], 0
	v_mov_b64_e32 v[102:103], 0
	v_mov_b64_e32 v[104:105], 0
	v_mov_b64_e32 v[106:107], 0
	v_mov_b64_e32 v[108:109], 0
	v_mov_b64_e32 v[110:111], 0
	v_mov_b64_e32 v[112:113], 0
	v_mov_b64_e32 v[114:115], 0
	v_mov_b64_e32 v[116:117], 0
	v_mov_b64_e32 v[118:119], 0
	v_mov_b64_e32 v[120:121], 0
	v_mov_b64_e32 v[122:123], 0
	v_mov_b64_e32 v[124:125], 0
	v_mov_b64_e32 v[126:127], 0
	v_mov_b64_e32 v[128:129], 0
	v_readfirstlane_b32 s0, v167
	s_nop 3
	s_cmpk_lt_u32 s0, 0x100
	s_cbranch_scc1 .Lprio_k2
	s_setprio 1
.Lprio_k2:
.LBB0_853:
	s_add_u32 s0, s2, 0xfffc0080
	s_addc_u32 s1, s3, -1
	s_add_i32 s12, 0, 0x10000
	s_cmp_eq_u32 s68, 12
	s_cselect_b32 s67, s34, s1
	s_cselect_b32 s66, s35, s0
	v_add_u32_e32 v130, s12, v163
	s_cselect_b32 s45, s51, s61
	s_cselect_b32 s44, s53, s58
	s_add_i32 s15, 0, 0x14000
	ds_read_b128 v[182:185], v130
	ds_read_b128 v[186:189], v130 offset:1024
	ds_read_b128 v[190:193], v130 offset:2048
	ds_read_b128 v[194:197], v130 offset:3072
	v_add_u32_e32 v130, s15, v163
	ds_read_b128 v[198:201], v130
	ds_read_b128 v[202:205], v130 offset:1024
	ds_read_b128 v[206:209], v130 offset:2048
	ds_read_b128 v[210:213], v130 offset:3072
	v_lshl_add_u64 v[172:173], s[2:3], 0, v[152:153]
	s_add_i32 m0, s24, 0xc000
	ds_read_b128 v[214:217], v165
	ds_read_b128 v[218:221], v165 offset:1024
	ds_read_b128 v[222:225], v165 offset:2048
	ds_read_b128 v[226:229], v165 offset:3072
	ds_read_b128 v[230:233], v165 offset:4096
	ds_read_b128 v[234:237], v165 offset:5120
	ds_read_b128 v[238:241], v165 offset:6144
	ds_read_b128 v[242:245], v165 offset:7168
	global_load_lds_dwordx4 v[172:173], off
	v_lshl_add_u64 v[172:173], s[2:3], 0, v[154:155]
	s_add_i32 m0, s24, 0xe000
	s_nop 0
	global_load_lds_dwordx4 v[172:173], off
	s_waitcnt vmcnt(8)
	s_waitcnt lgkmcnt(0)
	s_barrier
	s_waitcnt lgkmcnt(0)
	v_mfma_f32_16x16x32_bf16 v[126:129], v[182:185], v[214:217], v[126:129]
	v_mfma_f32_16x16x32_bf16 v[122:125], v[190:193], v[214:217], v[122:125]
	v_mfma_f32_16x16x32_bf16 v[114:117], v[182:185], v[222:225], v[114:117]
	v_mfma_f32_16x16x32_bf16 v[106:109], v[190:193], v[222:225], v[106:109]
	v_mfma_f32_16x16x32_bf16 v[98:101], v[182:185], v[230:233], v[98:101]
	v_mfma_f32_16x16x32_bf16 v[90:93], v[190:193], v[230:233], v[90:93]
	v_mfma_f32_16x16x32_bf16 v[82:85], v[182:185], v[238:241], v[82:85]
	v_mfma_f32_16x16x32_bf16 v[72:75], v[190:193], v[238:241], v[72:75]
	v_mfma_f32_16x16x32_bf16 v[126:129], v[186:189], v[218:221], v[126:129]
	v_mfma_f32_16x16x32_bf16 v[122:125], v[194:197], v[218:221], v[122:125]
	v_mfma_f32_16x16x32_bf16 v[114:117], v[186:189], v[226:229], v[114:117]
	v_mfma_f32_16x16x32_bf16 v[106:109], v[194:197], v[226:229], v[106:109]
	v_mfma_f32_16x16x32_bf16 v[98:101], v[186:189], v[234:237], v[98:101]
	v_mfma_f32_16x16x32_bf16 v[90:93], v[194:197], v[234:237], v[90:93]
	v_mfma_f32_16x16x32_bf16 v[82:85], v[186:189], v[242:245], v[82:85]
	v_mfma_f32_16x16x32_bf16 v[72:75], v[194:197], v[242:245], v[72:75]
	v_mfma_f32_16x16x32_bf16 v[118:121], v[198:201], v[214:217], v[118:121]
	v_mfma_f32_16x16x32_bf16 v[110:113], v[206:209], v[214:217], v[110:113]
	v_mfma_f32_16x16x32_bf16 v[102:105], v[198:201], v[222:225], v[102:105]
	v_mfma_f32_16x16x32_bf16 v[94:97], v[206:209], v[222:225], v[94:97]
	v_mfma_f32_16x16x32_bf16 v[86:89], v[198:201], v[230:233], v[86:89]
	v_mfma_f32_16x16x32_bf16 v[76:79], v[206:209], v[230:233], v[76:79]
	v_mfma_f32_16x16x32_bf16 v[68:71], v[198:201], v[238:241], v[68:71]
	v_mfma_f32_16x16x32_bf16 v[64:67], v[206:209], v[238:241], v[64:67]
	v_mfma_f32_16x16x32_bf16 v[118:121], v[202:205], v[218:221], v[118:121]
	v_mfma_f32_16x16x32_bf16 v[110:113], v[210:213], v[218:221], v[110:113]
	v_mfma_f32_16x16x32_bf16 v[102:105], v[202:205], v[226:229], v[102:105]
	v_mfma_f32_16x16x32_bf16 v[94:97], v[210:213], v[226:229], v[94:97]
	v_mfma_f32_16x16x32_bf16 v[86:89], v[202:205], v[234:237], v[86:89]
	v_mfma_f32_16x16x32_bf16 v[76:79], v[210:213], v[234:237], v[76:79]
	v_mfma_f32_16x16x32_bf16 v[68:71], v[202:205], v[242:245], v[68:71]
	v_mfma_f32_16x16x32_bf16 v[64:67], v[210:213], v[242:245], v[64:67]
	s_barrier
; #define PG8_STAGE(bufoff, gbase, voff) do { _Pragma("unroll") for (int _i = 0; _i < 2; ++_i) \
;         __builtin_amdgcn_global_load_lds((const unsigned*)((const char*)(gbase) + (voff)[_i]), (LAS unsigned*)(lds + (bufoff) + ldsw + _i * 8192), 16, 0, 0); } while (0)
; #define PG8_LDA(dst, b, h) do { _Pragma("unroll") for (int m = 0; m < 4; ++m) _Pragma("unroll") for (int k = 0; k < 2; ++k) dst[m][k] = *(const LAS bf16x8*)(lds + PG8_SA(b, h) + aoff + m * 2048 + k * 1024); } while (0)
; #define PG8_LDB(dst, b, h) do { _Pragma("unroll") for (int n = 0; n < 2; ++n) _Pragma("unroll") for (int k = 0; k < 2; ++k) dst[n][k] = *(const LAS bf16x8*)(lds + PG8_SB(b, h) + boff + n * 2048 + k * 1024); } while (0)
; #define PG8_MMA(ai, bj, At, Bt) do { __builtin_amdgcn_s_setprio(1); _Pragma("unroll") for (int m = 0; m < 4; ++m) _Pragma("unroll") for (int n = 0; n < 2; ++n) _Pragma("unroll") for (int k = 0; k < 2; ++k) \
;         acc[ai][bj][m][n] = __builtin_amdgcn_mfma_f32_16x16x32_bf16(Bt[n][k], At[m][k], acc[ai][bj][m][n], 0, 0, 0); __builtin_amdgcn_s_setprio(0); } while (0)
; #define PG8_WAIT_V(n) asm volatile("s_waitcnt vmcnt(" #n ")" ::: "memory")
; #define PG8_WAIT_L(n) asm volatile("s_waitcnt lgkmcnt(" #n ")" ::: "memory")
; #define PG8_BAR __builtin_amdgcn_s_barrier()
; #define PG8_SCHED __builtin_amdgcn_sched_barrier(0)
; template <class Epi, bool ALIGN_EPI>
; __device__ __forceinline__ void gemm_phase(LAS unsigned char* lds, const Gemm g, const StaticOrder S, const Epi E) {
;     ...
;             PG8_LDA(At, 0, 1); PG8_STAGE(PG8_SB(0, 0), b2, voffB); PG8_STAGE(PG8_SB(0, 1), b2 + hstepB, voffB); PG8_STAGE(PG8_SA(0, 0), a2, voffA);
;             PG8_WAIT_V(8); PG8_WAIT_L(0); PG8_BAR; PG8_MMA(1, 0, At, B0); PG8_MMA(1, 1, At, B1); PG8_BAR; PG8_SCHED;
;             PG8_LDB(B0, 1, 0); PG8_LDB(B1, 1, 1); PG8_SCHED; PG8_LDA(At, 1, 0); PG8_STAGE(PG8_SA(0, 1), a2 + hstepA, voffA);
;             PG8_WAIT_V(8); PG8_WAIT_L(0); PG8_BAR; PG8_MMA(0, 0, At, B0); PG8_MMA(0, 1, At, B1); PG8_BAR; PG8_SCHED;
	s_add_i32 s0, s12, s23
	v_lshl_add_u64 v[172:173], s[44:45], 0, v[80:81]
	s_mov_b32 m0, s0
	ds_read_b128 v[214:217], v165 offset:16384
	ds_read_b128 v[218:221], v165 offset:17408
	ds_read_b128 v[222:225], v165 offset:18432
	ds_read_b128 v[226:229], v165 offset:19456
	ds_read_b128 v[230:233], v165 offset:20480
	ds_read_b128 v[234:237], v165 offset:21504
	ds_read_b128 v[238:241], v165 offset:22528
	ds_read_b128 v[242:245], v165 offset:23552
	global_load_lds_dwordx4 v[172:173], off
	s_add_i32 m0, s0, 0x2000
	s_add_u32 s0, s44, 0x40000
	v_lshl_add_u64 v[176:177], s[44:45], 0, v[136:137]
	s_addc_u32 s1, s45, 0
	s_add_i32 s12, s15, s23
	global_load_lds_dwordx4 v[176:177], off
	v_lshl_add_u64 v[178:179], s[0:1], 0, v[80:81]
	s_mov_b32 m0, s12
	v_lshl_add_u64 v[246:247], s[66:67], 0, v[138:139]
	global_load_lds_dwordx4 v[178:179], off
	v_lshl_add_u64 v[178:179], s[0:1], 0, v[136:137]
	s_add_i32 m0, s12, 0x2000
	s_nop 0
	global_load_lds_dwordx4 v[178:179], off
	v_lshl_add_u64 v[178:179], s[66:67], 0, v[140:141]
	s_mov_b32 m0, s24
	s_nop 0
	global_load_lds_dwordx4 v[178:179], off
	s_mov_b32 m0, s25
	s_nop 0
	global_load_lds_dwordx4 v[246:247], off
	s_waitcnt vmcnt(8)
	s_waitcnt lgkmcnt(0)
	s_barrier
	s_waitcnt lgkmcnt(0)
	v_mfma_f32_16x16x32_bf16 v[60:63], v[182:185], v[214:217], v[60:63]
	v_mfma_f32_16x16x32_bf16 v[56:59], v[190:193], v[214:217], v[56:59]
	v_mfma_f32_16x16x32_bf16 v[48:51], v[182:185], v[222:225], v[48:51]
	v_mfma_f32_16x16x32_bf16 v[40:43], v[190:193], v[222:225], v[40:43]
	v_mfma_f32_16x16x32_bf16 v[32:35], v[182:185], v[230:233], v[32:35]
	v_mfma_f32_16x16x32_bf16 v[24:27], v[190:193], v[230:233], v[24:27]
	v_mfma_f32_16x16x32_bf16 v[16:19], v[182:185], v[238:241], v[16:19]
	v_mfma_f32_16x16x32_bf16 v[8:11], v[190:193], v[238:241], v[8:11]
	v_mfma_f32_16x16x32_bf16 v[60:63], v[186:189], v[218:221], v[60:63]
	v_mfma_f32_16x16x32_bf16 v[56:59], v[194:197], v[218:221], v[56:59]
	v_mfma_f32_16x16x32_bf16 v[48:51], v[186:189], v[226:229], v[48:51]
	v_mfma_f32_16x16x32_bf16 v[40:43], v[194:197], v[226:229], v[40:43]
	v_mfma_f32_16x16x32_bf16 v[32:35], v[186:189], v[234:237], v[32:35]
	v_mfma_f32_16x16x32_bf16 v[24:27], v[194:197], v[234:237], v[24:27]
	v_mfma_f32_16x16x32_bf16 v[16:19], v[186:189], v[242:245], v[16:19]
	v_mfma_f32_16x16x32_bf16 v[8:11], v[194:197], v[242:245], v[8:11]
	v_mfma_f32_16x16x32_bf16 v[52:55], v[198:201], v[214:217], v[52:55]
	v_mfma_f32_16x16x32_bf16 v[44:47], v[206:209], v[214:217], v[44:47]
	v_mfma_f32_16x16x32_bf16 v[36:39], v[198:201], v[222:225], v[36:39]
	v_mfma_f32_16x16x32_bf16 v[28:31], v[206:209], v[222:225], v[28:31]
	v_mfma_f32_16x16x32_bf16 v[20:23], v[198:201], v[230:233], v[20:23]
	v_mfma_f32_16x16x32_bf16 v[12:15], v[206:209], v[230:233], v[12:15]
	v_mfma_f32_16x16x32_bf16 v[4:7], v[198:201], v[238:241], v[4:7]
	v_mfma_f32_16x16x32_bf16 v[0:3], v[206:209], v[238:241], v[0:3]
	v_mfma_f32_16x16x32_bf16 v[52:55], v[202:205], v[218:221], v[52:55]
	v_mfma_f32_16x16x32_bf16 v[44:47], v[210:213], v[218:221], v[44:47]
	v_mfma_f32_16x16x32_bf16 v[36:39], v[202:205], v[226:229], v[36:39]
	v_mfma_f32_16x16x32_bf16 v[28:31], v[210:213], v[226:229], v[28:31]
	v_mfma_f32_16x16x32_bf16 v[20:23], v[202:205], v[234:237], v[20:23]
	v_mfma_f32_16x16x32_bf16 v[12:15], v[210:213], v[234:237], v[12:15]
	v_mfma_f32_16x16x32_bf16 v[4:7], v[202:205], v[242:245], v[4:7]
	v_mfma_f32_16x16x32_bf16 v[0:3], v[210:213], v[242:245], v[0:3]
	s_barrier
	s_add_i32 s12, 0, 0x18000
	v_add_u32_e32 v130, s12, v163
	s_add_i32 s15, 0, 0x1c000
	ds_read_b128 v[182:185], v130
	ds_read_b128 v[186:189], v130 offset:1024
	ds_read_b128 v[190:193], v130 offset:2048
	ds_read_b128 v[194:197], v130 offset:3072
	v_add_u32_e32 v130, s15, v163
	ds_read_b128 v[198:201], v130
	ds_read_b128 v[202:205], v130 offset:1024
	ds_read_b128 v[206:209], v130 offset:2048
	ds_read_b128 v[210:213], v130 offset:3072
	s_add_u32 s0, s66, 0x40000
	s_addc_u32 s1, s67, 0
	s_mov_b32 m0, s26
	v_lshl_add_u64 v[248:249], s[0:1], 0, v[140:141]
	ds_read_b128 v[214:217], v165 offset:32768
	ds_read_b128 v[218:221], v165 offset:33792
	ds_read_b128 v[222:225], v165 offset:34816
	ds_read_b128 v[226:229], v165 offset:35840
	ds_read_b128 v[230:233], v165 offset:36864
	ds_read_b128 v[234:237], v165 offset:37888
	ds_read_b128 v[238:241], v165 offset:38912
	ds_read_b128 v[242:245], v165 offset:39936
	global_load_lds_dwordx4 v[248:249], off
	v_lshl_add_u64 v[248:249], s[0:1], 0, v[138:139]
	s_mov_b32 m0, s27
	s_nop 0
	global_load_lds_dwordx4 v[248:249], off
	s_waitcnt vmcnt(8)
	s_waitcnt lgkmcnt(0)
	s_barrier
; #define PG8_STAGE(bufoff, gbase, voff) do { _Pragma("unroll") for (int _i = 0; _i < 2; ++_i) \
;         __builtin_amdgcn_global_load_lds((const unsigned*)((const char*)(gbase) + (voff)[_i]), (LAS unsigned*)(lds + (bufoff) + ldsw + _i * 8192), 16, 0, 0); } while (0)
; #define PG8_LDA(dst, b, h) do { _Pragma("unroll") for (int m = 0; m < 4; ++m) _Pragma("unroll") for (int k = 0; k < 2; ++k) dst[m][k] = *(const LAS bf16x8*)(lds + PG8_SA(b, h) + aoff + m * 2048 + k * 1024); } while (0)
; #define PG8_MMA(ai, bj, At, Bt) do { __builtin_amdgcn_s_setprio(1); _Pragma("unroll") for (int m = 0; m < 4; ++m) _Pragma("unroll") for (int n = 0; n < 2; ++n) _Pragma("unroll") for (int k = 0; k < 2; ++k) \
;         acc[ai][bj][m][n] = __builtin_amdgcn_mfma_f32_16x16x32_bf16(Bt[n][k], At[m][k], acc[ai][bj][m][n], 0, 0, 0); __builtin_amdgcn_s_setprio(0); } while (0)
; #define PG8_WAIT_V(n) asm volatile("s_waitcnt vmcnt(" #n ")" ::: "memory")
; #define PG8_WAIT_L(n) asm volatile("s_waitcnt lgkmcnt(" #n ")" ::: "memory")
; #define PG8_BAR __builtin_amdgcn_s_barrier()
; #define PG8_SCHED __builtin_amdgcn_sched_barrier(0)
; template <class Epi, bool ALIGN_EPI>
; __device__ __forceinline__ void gemm_phase(LAS unsigned char* lds, const Gemm g, const StaticOrder S, const Epi E) {
;     ...
;             PG8_WAIT_V(8); PG8_WAIT_L(0); PG8_BAR; PG8_MMA(0, 0, At, B0); PG8_MMA(0, 1, At, B1); PG8_BAR; PG8_SCHED;
;             PG8_LDA(At, 1, 1); PG8_STAGE(PG8_SB(1, 0), b3, voffB); PG8_STAGE(PG8_SB(1, 1), b3 + hstepB, voffB); PG8_STAGE(PG8_SA(1, 0), a3, voffA);
;             PG8_WAIT_V(8); PG8_WAIT_L(0); PG8_BAR; PG8_MMA(1, 0, At, B0); PG8_MMA(1, 1, At, B1); PG8_BAR; PG8_SCHED;
;         }
;         if constexpr (ALIGN_EPI) { if (wr == 0) PG8_BAR; }
	s_waitcnt lgkmcnt(0)
	v_mfma_f32_16x16x32_bf16 v[126:129], v[182:185], v[214:217], v[126:129]
	v_mfma_f32_16x16x32_bf16 v[122:125], v[190:193], v[214:217], v[122:125]
	v_mfma_f32_16x16x32_bf16 v[114:117], v[182:185], v[222:225], v[114:117]
	v_mfma_f32_16x16x32_bf16 v[106:109], v[190:193], v[222:225], v[106:109]
	v_mfma_f32_16x16x32_bf16 v[98:101], v[182:185], v[230:233], v[98:101]
	v_mfma_f32_16x16x32_bf16 v[90:93], v[190:193], v[230:233], v[90:93]
	v_mfma_f32_16x16x32_bf16 v[82:85], v[182:185], v[238:241], v[82:85]
	v_mfma_f32_16x16x32_bf16 v[72:75], v[190:193], v[238:241], v[72:75]
	v_mfma_f32_16x16x32_bf16 v[126:129], v[186:189], v[218:221], v[126:129]
	v_mfma_f32_16x16x32_bf16 v[122:125], v[194:197], v[218:221], v[122:125]
	v_mfma_f32_16x16x32_bf16 v[114:117], v[186:189], v[226:229], v[114:117]
	v_mfma_f32_16x16x32_bf16 v[106:109], v[194:197], v[226:229], v[106:109]
	v_mfma_f32_16x16x32_bf16 v[98:101], v[186:189], v[234:237], v[98:101]
	v_mfma_f32_16x16x32_bf16 v[90:93], v[194:197], v[234:237], v[90:93]
	v_mfma_f32_16x16x32_bf16 v[82:85], v[186:189], v[242:245], v[82:85]
	v_mfma_f32_16x16x32_bf16 v[72:75], v[194:197], v[242:245], v[72:75]
	v_mfma_f32_16x16x32_bf16 v[118:121], v[198:201], v[214:217], v[118:121]
	v_mfma_f32_16x16x32_bf16 v[110:113], v[206:209], v[214:217], v[110:113]
	v_mfma_f32_16x16x32_bf16 v[102:105], v[198:201], v[222:225], v[102:105]
	v_mfma_f32_16x16x32_bf16 v[94:97], v[206:209], v[222:225], v[94:97]
	v_mfma_f32_16x16x32_bf16 v[86:89], v[198:201], v[230:233], v[86:89]
	v_mfma_f32_16x16x32_bf16 v[76:79], v[206:209], v[230:233], v[76:79]
	v_mfma_f32_16x16x32_bf16 v[68:71], v[198:201], v[238:241], v[68:71]
	v_mfma_f32_16x16x32_bf16 v[64:67], v[206:209], v[238:241], v[64:67]
	v_mfma_f32_16x16x32_bf16 v[118:121], v[202:205], v[218:221], v[118:121]
	v_mfma_f32_16x16x32_bf16 v[110:113], v[210:213], v[218:221], v[110:113]
	v_mfma_f32_16x16x32_bf16 v[102:105], v[202:205], v[226:229], v[102:105]
	v_mfma_f32_16x16x32_bf16 v[94:97], v[210:213], v[226:229], v[94:97]
	v_mfma_f32_16x16x32_bf16 v[86:89], v[202:205], v[234:237], v[86:89]
	v_mfma_f32_16x16x32_bf16 v[76:79], v[210:213], v[234:237], v[76:79]
	v_mfma_f32_16x16x32_bf16 v[68:71], v[202:205], v[242:245], v[68:71]
	v_mfma_f32_16x16x32_bf16 v[64:67], v[210:213], v[242:245], v[64:67]
	s_barrier
	s_add_i32 s0, s12, s23
	v_lshl_add_u64 v[172:173], v[172:173], 0, s[80:81]
	s_mov_b32 m0, s0
	ds_read_b128 v[214:217], v165 offset:49152
	ds_read_b128 v[218:221], v165 offset:50176
	ds_read_b128 v[222:225], v165 offset:51200
	ds_read_b128 v[226:229], v165 offset:52224
	ds_read_b128 v[230:233], v165 offset:53248
	ds_read_b128 v[234:237], v165 offset:54272
	ds_read_b128 v[238:241], v165 offset:55296
	ds_read_b128 v[242:245], v165 offset:56320
	global_load_lds_dwordx4 v[172:173], off
	s_add_i32 m0, s0, 0x2000
	s_add_u32 s0, s44, 0x40080
	v_lshl_add_u64 v[172:173], v[176:177], 0, s[80:81]
	s_addc_u32 s1, s45, 0
	s_add_i32 s12, s15, s23
	global_load_lds_dwordx4 v[172:173], off
	v_lshl_add_u64 v[172:173], s[0:1], 0, v[80:81]
	s_mov_b32 m0, s12
	s_nop 0
	global_load_lds_dwordx4 v[172:173], off
	v_lshl_add_u64 v[172:173], s[0:1], 0, v[136:137]
	s_add_i32 m0, s12, 0x2000
	s_nop 0
	global_load_lds_dwordx4 v[172:173], off
	v_lshl_add_u64 v[172:173], v[178:179], 0, s[80:81]
	s_mov_b32 m0, s29
	s_nop 0
	global_load_lds_dwordx4 v[172:173], off
	v_lshl_add_u64 v[172:173], v[246:247], 0, s[80:81]
	s_mov_b32 m0, s30
	s_nop 0
	global_load_lds_dwordx4 v[172:173], off
	s_waitcnt vmcnt(8)
	s_waitcnt lgkmcnt(0)
	s_barrier
	s_waitcnt lgkmcnt(0)
	v_mfma_f32_16x16x32_bf16 v[60:63], v[182:185], v[214:217], v[60:63]
	v_mfma_f32_16x16x32_bf16 v[56:59], v[190:193], v[214:217], v[56:59]
	v_mfma_f32_16x16x32_bf16 v[48:51], v[182:185], v[222:225], v[48:51]
	v_mfma_f32_16x16x32_bf16 v[40:43], v[190:193], v[222:225], v[40:43]
	v_mfma_f32_16x16x32_bf16 v[32:35], v[182:185], v[230:233], v[32:35]
	v_mfma_f32_16x16x32_bf16 v[24:27], v[190:193], v[230:233], v[24:27]
	v_mfma_f32_16x16x32_bf16 v[16:19], v[182:185], v[238:241], v[16:19]
	v_mfma_f32_16x16x32_bf16 v[8:11], v[190:193], v[238:241], v[8:11]
	v_mfma_f32_16x16x32_bf16 v[60:63], v[186:189], v[218:221], v[60:63]
	v_mfma_f32_16x16x32_bf16 v[56:59], v[194:197], v[218:221], v[56:59]
	v_mfma_f32_16x16x32_bf16 v[48:51], v[186:189], v[226:229], v[48:51]
	v_mfma_f32_16x16x32_bf16 v[40:43], v[194:197], v[226:229], v[40:43]
	v_mfma_f32_16x16x32_bf16 v[32:35], v[186:189], v[234:237], v[32:35]
	v_mfma_f32_16x16x32_bf16 v[24:27], v[194:197], v[234:237], v[24:27]
	v_mfma_f32_16x16x32_bf16 v[16:19], v[186:189], v[242:245], v[16:19]
	v_mfma_f32_16x16x32_bf16 v[8:11], v[194:197], v[242:245], v[8:11]
	v_mfma_f32_16x16x32_bf16 v[52:55], v[198:201], v[214:217], v[52:55]
	v_mfma_f32_16x16x32_bf16 v[44:47], v[206:209], v[214:217], v[44:47]
	v_mfma_f32_16x16x32_bf16 v[36:39], v[198:201], v[222:225], v[36:39]
	v_mfma_f32_16x16x32_bf16 v[28:31], v[206:209], v[222:225], v[28:31]
	v_mfma_f32_16x16x32_bf16 v[20:23], v[198:201], v[230:233], v[20:23]
	v_mfma_f32_16x16x32_bf16 v[12:15], v[206:209], v[230:233], v[12:15]
	v_mfma_f32_16x16x32_bf16 v[4:7], v[198:201], v[238:241], v[4:7]
	v_mfma_f32_16x16x32_bf16 v[0:3], v[206:209], v[238:241], v[0:3]
	v_mfma_f32_16x16x32_bf16 v[52:55], v[202:205], v[218:221], v[52:55]
	v_mfma_f32_16x16x32_bf16 v[44:47], v[210:213], v[218:221], v[44:47]
	v_mfma_f32_16x16x32_bf16 v[36:39], v[202:205], v[226:229], v[36:39]
	v_mfma_f32_16x16x32_bf16 v[28:31], v[210:213], v[226:229], v[28:31]
	v_mfma_f32_16x16x32_bf16 v[20:23], v[202:205], v[234:237], v[20:23]
	v_mfma_f32_16x16x32_bf16 v[12:15], v[210:213], v[234:237], v[12:15]
	v_mfma_f32_16x16x32_bf16 v[4:7], v[202:205], v[242:245], v[4:7]
	v_mfma_f32_16x16x32_bf16 v[0:3], v[210:213], v[242:245], v[0:3]
	s_barrier
	s_add_i32 s68, s68, 2
	s_add_u32 s2, s2, 0x100
	s_addc_u32 s3, s3, 0
	s_add_u32 s58, s58, 0x100
	s_addc_u32 s61, s61, 0
	s_cmp_gt_u32 s68, 13
	s_cbranch_scc0 .LBB0_853
	s_setprio 0
	s_and_b64 vcc, exec, s[48:49]
	s_cbranch_vccz .LBB0_856
	s_barrier

; #define PG8_STAGE(bufoff, gbase, voff) do { _Pragma("unroll") for (int _i = 0; _i < 2; ++_i) \
;         __builtin_amdgcn_global_load_lds((const unsigned*)((const char*)(gbase) + (voff)[_i]), (LAS unsigned*)(lds + (bufoff) + ldsw + _i * 8192), 16, 0, 0); } while (0)
; #define PG8_LDA(dst, b, h) do { _Pragma("unroll") for (int m = 0; m < 4; ++m) _Pragma("unroll") for (int k = 0; k < 2; ++k) dst[m][k] = *(const LAS bf16x8*)(lds + PG8_SA(b, h) + aoff + m * 2048 + k * 1024); } while (0)
; #define PG8_LDB(dst, b, h) do { _Pragma("unroll") for (int n = 0; n < 2; ++n) _Pragma("unroll") for (int k = 0; k < 2; ++k) dst[n][k] = *(const LAS bf16x8*)(lds + PG8_SB(b, h) + boff + n * 2048 + k * 1024); } while (0)
; #define PG8_MMA(ai, bj, At, Bt) do { __builtin_amdgcn_s_setprio(1); _Pragma("unroll") for (int m = 0; m < 4; ++m) _Pragma("unroll") for (int n = 0; n < 2; ++n) _Pragma("unroll") for (int k = 0; k < 2; ++k) \
;         acc[ai][bj][m][n] = __builtin_amdgcn_mfma_f32_16x16x32_bf16(Bt[n][k], At[m][k], acc[ai][bj][m][n], 0, 0, 0); __builtin_amdgcn_s_setprio(0); } while (0)
; #define PG8_WAIT_V(n) asm volatile("s_waitcnt vmcnt(" #n ")" ::: "memory")
; #define PG8_WAIT_L(n) asm volatile("s_waitcnt lgkmcnt(" #n ")" ::: "memory")
; #define PG8_BAR __builtin_amdgcn_s_barrier()
; #define PG8_SCHED __builtin_amdgcn_sched_barrier(0)
; template <class Epi, bool ALIGN_EPI>
; __device__ __forceinline__ void gemm_phase(LAS unsigned char* lds, const Gemm g, const StaticOrder S, const Epi E) {
;     ...
;             PG8_LDB(B0, 0, 0); PG8_LDB(B1, 0, 1); PG8_SCHED; PG8_LDA(At, 0, 0); PG8_STAGE(PG8_SA(1, 1), a1 + hstepA, voffA);
;             PG8_WAIT_V(8); PG8_WAIT_L(0); PG8_BAR; PG8_MMA(0, 0, At, B0); PG8_MMA(0, 1, At, B1); PG8_BAR; PG8_SCHED;
;             PG8_LDA(At, 0, 1); PG8_STAGE(PG8_SB(0, 0), b2, voffB); PG8_STAGE(PG8_SB(0, 1), b2 + hstepB, voffB); PG8_STAGE(PG8_SA(0, 0), a2, voffA);
;             PG8_WAIT_V(8); PG8_WAIT_L(0); PG8_BAR; PG8_MMA(1, 0, At, B0); PG8_MMA(1, 1, At, B1); PG8_BAR; PG8_SCHED;
;             PG8_LDB(B0, 1, 0); PG8_LDB(B1, 1, 1); PG8_SCHED; PG8_LDA(At, 1, 0); PG8_STAGE(PG8_SA(0, 1), a2 + hstepA, voffA);
.LBB0_1055:
	s_ashr_i32 s53, s52, 31
	s_lshl_b64 s[0:1], s[52:53], 18
	s_add_u32 s0, s4, s0
	s_addc_u32 s1, s5, s1
	s_lshl_b32 s3, s50, 8
	s_and_b32 s3, s3, 0x300
	s_add_u32 s54, s0, s3
	s_addc_u32 s55, s1, 0
	s_and_b64 s[0:1], s[42:43], exec
	s_cselect_b32 s71, s55, s69
	s_cselect_b32 s70, s54, s68
	s_ashr_i32 s51, s50, 31
	s_lshl_b64 s[0:1], s[50:51], 18
	v_readlane_b32 s12, v255, 26
	s_add_u32 s0, s12, s0
	v_readlane_b32 s12, v255, 27
	s_addc_u32 s1, s12, s1
	s_add_u32 s62, s0, s3
	s_addc_u32 s63, s1, 0
	s_add_u32 s0, s68, 0x20080
	s_addc_u32 s1, s69, 0
	s_add_u32 s68, s70, 0x20000
	s_addc_u32 s69, s71, 0
	s_add_i32 s3, 0, 0x10000
	s_and_b64 s[24:25], s[42:43], exec
	s_cselect_b32 s64, s62, s64
	s_cselect_b32 s65, s63, s65
	s_add_u32 s24, s64, 0x20000
	s_addc_u32 s25, s65, 0
	s_add_i32 s12, 0, 0x14000
	v_add_u32_e32 v12, s3, v152
	v_add_u32_e32 v28, s12, v152
	ds_read_b128 v[0:3], v12
	ds_read_b128 v[4:7], v12 offset:1024
	ds_read_b128 v[8:11], v12 offset:2048
	ds_read_b128 v[12:15], v12 offset:3072
	ds_read_b128 v[16:19], v28
	ds_read_b128 v[20:23], v28 offset:1024
	ds_read_b128 v[24:27], v28 offset:2048
	ds_read_b128 v[28:31], v28 offset:3072
	v_mov_b64_e32 v[132:133], 0x200
	v_lshl_add_u64 v[64:65], s[0:1], 0, v[136:137]
	s_add_i32 m0, s67, 0xc000
	ds_read_b128 v[32:35], v153
	ds_read_b128 v[36:39], v153 offset:1024
	ds_read_b128 v[40:43], v153 offset:2048
	ds_read_b128 v[44:47], v153 offset:3072
	ds_read_b128 v[48:51], v153 offset:4096
	ds_read_b128 v[52:55], v153 offset:5120
	ds_read_b128 v[56:59], v153 offset:6144
	ds_read_b128 v[60:63], v153 offset:7168
	global_load_lds_dwordx4 v[64:65], off
	v_lshl_add_u64 v[64:65], s[0:1], 0, v[138:139]
	s_add_i32 m0, s67, 0xe000
	s_nop 0
	global_load_lds_dwordx4 v[64:65], off
	s_waitcnt vmcnt(8)
	s_waitcnt lgkmcnt(0)
	s_barrier
	s_waitcnt lgkmcnt(0)
	v_mfma_f32_16x16x32_bf16 v[64:67], v[0:3], v[32:35], 0
	v_mfma_f32_16x16x32_bf16 v[68:71], v[8:11], v[32:35], 0
	v_mfma_f32_16x16x32_bf16 v[72:75], v[0:3], v[40:43], 0
	v_mfma_f32_16x16x32_bf16 v[76:79], v[8:11], v[40:43], 0
	v_mfma_f32_16x16x32_bf16 v[82:85], v[0:3], v[48:51], 0
	v_mfma_f32_16x16x32_bf16 v[86:89], v[8:11], v[48:51], 0
	v_mfma_f32_16x16x32_bf16 v[90:93], v[0:3], v[56:59], 0
	v_mfma_f32_16x16x32_bf16 v[94:97], v[8:11], v[56:59], 0
	v_mfma_f32_16x16x32_bf16 v[64:67], v[4:7], v[36:39], v[64:67]
	v_mfma_f32_16x16x32_bf16 v[68:71], v[12:15], v[36:39], v[68:71]
	v_mfma_f32_16x16x32_bf16 v[72:75], v[4:7], v[44:47], v[72:75]
	v_mfma_f32_16x16x32_bf16 v[76:79], v[12:15], v[44:47], v[76:79]
	v_mfma_f32_16x16x32_bf16 v[82:85], v[4:7], v[52:55], v[82:85]
	v_mfma_f32_16x16x32_bf16 v[86:89], v[12:15], v[52:55], v[86:89]
	v_mfma_f32_16x16x32_bf16 v[90:93], v[4:7], v[60:63], v[90:93]
	v_mfma_f32_16x16x32_bf16 v[98:101], v[12:15], v[60:63], v[94:97]
	v_mfma_f32_16x16x32_bf16 v[94:97], v[16:19], v[32:35], 0
	v_mfma_f32_16x16x32_bf16 v[32:35], v[24:27], v[32:35], 0
	v_mfma_f32_16x16x32_bf16 v[106:109], v[20:23], v[36:39], v[94:97]
	v_mfma_f32_16x16x32_bf16 v[32:35], v[28:31], v[36:39], v[32:35]
	v_mfma_f32_16x16x32_bf16 v[36:39], v[16:19], v[40:43], 0
	v_mfma_f32_16x16x32_bf16 v[40:43], v[24:27], v[40:43], 0
	v_mfma_f32_16x16x32_bf16 v[36:39], v[20:23], v[44:47], v[36:39]
	v_mfma_f32_16x16x32_bf16 v[40:43], v[28:31], v[44:47], v[40:43]
	v_mfma_f32_16x16x32_bf16 v[44:47], v[16:19], v[48:51], 0
	v_mfma_f32_16x16x32_bf16 v[48:51], v[24:27], v[48:51], 0
	v_mfma_f32_16x16x32_bf16 v[44:47], v[20:23], v[52:55], v[44:47]
	v_mfma_f32_16x16x32_bf16 v[48:51], v[28:31], v[52:55], v[48:51]
	v_mfma_f32_16x16x32_bf16 v[52:55], v[16:19], v[56:59], 0
	v_mfma_f32_16x16x32_bf16 v[56:59], v[24:27], v[56:59], 0
	v_mfma_f32_16x16x32_bf16 v[52:55], v[20:23], v[60:63], v[52:55]
	v_mfma_f32_16x16x32_bf16 v[56:59], v[28:31], v[60:63], v[56:59]
	s_barrier
	s_add_i32 s0, s3, s61
	v_lshl_add_u64 v[172:173], s[64:65], 0, v[80:81]
	s_mov_b32 m0, s0
	ds_read_b128 v[60:63], v153 offset:16384
	ds_read_b128 v[94:97], v153 offset:17408
	ds_read_b128 v[102:105], v153 offset:18432
	ds_read_b128 v[110:113], v153 offset:19456
	ds_read_b128 v[114:117], v153 offset:20480
	ds_read_b128 v[118:121], v153 offset:21504
	ds_read_b128 v[122:125], v153 offset:22528
	ds_read_b128 v[126:129], v153 offset:23552
	global_load_lds_dwordx4 v[172:173], off
	v_lshl_add_u64 v[134:135], s[64:65], 0, v[140:141]
	s_add_i32 m0, s0, 0x2000
	s_add_i32 s0, s12, s61
	global_load_lds_dwordx4 v[134:135], off
	v_lshl_add_u64 v[142:143], s[24:25], 0, v[80:81]
	s_mov_b32 m0, s0
	v_lshl_add_u64 v[250:251], s[70:71], 0, v[136:137]
	global_load_lds_dwordx4 v[142:143], off
	v_lshl_add_u64 v[142:143], s[24:25], 0, v[140:141]
	s_add_i32 m0, s0, 0x2000
	v_lshl_add_u64 v[130:131], s[70:71], 0, v[138:139]
	global_load_lds_dwordx4 v[142:143], off
	s_mov_b32 m0, s67
	s_nop 0
	global_load_lds_dwordx4 v[250:251], off
	s_mov_b32 m0, s72
	s_nop 0
	global_load_lds_dwordx4 v[130:131], off
	s_waitcnt vmcnt(8)
	s_waitcnt lgkmcnt(0)
	s_barrier
; #define PG8_STAGE(bufoff, gbase, voff) do { _Pragma("unroll") for (int _i = 0; _i < 2; ++_i) \
;         __builtin_amdgcn_global_load_lds((const unsigned*)((const char*)(gbase) + (voff)[_i]), (LAS unsigned*)(lds + (bufoff) + ldsw + _i * 8192), 16, 0, 0); } while (0)
; #define PG8_LDA(dst, b, h) do { _Pragma("unroll") for (int m = 0; m < 4; ++m) _Pragma("unroll") for (int k = 0; k < 2; ++k) dst[m][k] = *(const LAS bf16x8*)(lds + PG8_SA(b, h) + aoff + m * 2048 + k * 1024); } while (0)
; #define PG8_LDB(dst, b, h) do { _Pragma("unroll") for (int n = 0; n < 2; ++n) _Pragma("unroll") for (int k = 0; k < 2; ++k) dst[n][k] = *(const LAS bf16x8*)(lds + PG8_SB(b, h) + boff + n * 2048 + k * 1024); } while (0)
; #define PG8_MMA(ai, bj, At, Bt) do { __builtin_amdgcn_s_setprio(1); _Pragma("unroll") for (int m = 0; m < 4; ++m) _Pragma("unroll") for (int n = 0; n < 2; ++n) _Pragma("unroll") for (int k = 0; k < 2; ++k) \
;         acc[ai][bj][m][n] = __builtin_amdgcn_mfma_f32_16x16x32_bf16(Bt[n][k], At[m][k], acc[ai][bj][m][n], 0, 0, 0); __builtin_amdgcn_s_setprio(0); } while (0)
; #define PG8_WAIT_V(n) asm volatile("s_waitcnt vmcnt(" #n ")" ::: "memory")
; #define PG8_WAIT_L(n) asm volatile("s_waitcnt lgkmcnt(" #n ")" ::: "memory")
; #define PG8_BAR __builtin_amdgcn_s_barrier()
; #define PG8_SCHED __builtin_amdgcn_sched_barrier(0)
; template <class Epi, bool ALIGN_EPI>
; __device__ __forceinline__ void gemm_phase(LAS unsigned char* lds, const Gemm g, const StaticOrder S, const Epi E) {
;     ...
;             PG8_WAIT_V(8); PG8_WAIT_L(0); PG8_BAR; PG8_MMA(1, 0, At, B0); PG8_MMA(1, 1, At, B1); PG8_BAR; PG8_SCHED;
;             PG8_LDB(B0, 1, 0); PG8_LDB(B1, 1, 1); PG8_SCHED; PG8_LDA(At, 1, 0); PG8_STAGE(PG8_SA(0, 1), a2 + hstepA, voffA);
;             PG8_WAIT_V(8); PG8_WAIT_L(0); PG8_BAR; PG8_MMA(0, 0, At, B0); PG8_MMA(0, 1, At, B1); PG8_BAR; PG8_SCHED;
	s_waitcnt lgkmcnt(0)
	v_mfma_f32_16x16x32_bf16 v[142:145], v[0:3], v[60:63], 0
	v_mfma_f32_16x16x32_bf16 v[154:157], v[0:3], v[102:105], 0
	v_mfma_f32_16x16x32_bf16 v[162:165], v[0:3], v[114:117], 0
	v_mfma_f32_16x16x32_bf16 v[0:3], v[0:3], v[122:125], 0
	v_mfma_f32_16x16x32_bf16 v[142:145], v[4:7], v[94:97], v[142:145]
	v_mfma_f32_16x16x32_bf16 v[154:157], v[4:7], v[110:113], v[154:157]
	v_mfma_f32_16x16x32_bf16 v[162:165], v[4:7], v[118:121], v[162:165]
	v_mfma_f32_16x16x32_bf16 v[0:3], v[4:7], v[126:129], v[0:3]
	v_mfma_f32_16x16x32_bf16 v[4:7], v[8:11], v[122:125], 0
	v_mfma_f32_16x16x32_bf16 v[146:149], v[8:11], v[60:63], 0
	v_mfma_f32_16x16x32_bf16 v[158:161], v[8:11], v[102:105], 0
	v_mfma_f32_16x16x32_bf16 v[182:185], v[8:11], v[114:117], 0
	v_mfma_f32_16x16x32_bf16 v[4:7], v[12:15], v[126:129], v[4:7]
	v_mfma_f32_16x16x32_bf16 v[146:149], v[12:15], v[94:97], v[146:149]
	v_mfma_f32_16x16x32_bf16 v[158:161], v[12:15], v[110:113], v[158:161]
	v_mfma_f32_16x16x32_bf16 v[182:185], v[12:15], v[118:121], v[182:185]
	v_mfma_f32_16x16x32_bf16 v[12:15], v[24:27], v[60:63], 0
	v_mfma_f32_16x16x32_bf16 v[186:189], v[28:31], v[94:97], v[12:15]
	v_mfma_f32_16x16x32_bf16 v[12:15], v[16:19], v[102:105], 0
	v_mfma_f32_16x16x32_bf16 v[190:193], v[20:23], v[110:113], v[12:15]
	v_mfma_f32_16x16x32_bf16 v[12:15], v[24:27], v[102:105], 0
	v_mfma_f32_16x16x32_bf16 v[194:197], v[28:31], v[110:113], v[12:15]
	v_mfma_f32_16x16x32_bf16 v[12:15], v[16:19], v[114:117], 0
	v_mfma_f32_16x16x32_bf16 v[198:201], v[20:23], v[118:121], v[12:15]
	v_mfma_f32_16x16x32_bf16 v[12:15], v[24:27], v[114:117], 0
	v_mfma_f32_16x16x32_bf16 v[8:11], v[16:19], v[60:63], 0
	v_mfma_f32_16x16x32_bf16 v[202:205], v[28:31], v[118:121], v[12:15]
	v_mfma_f32_16x16x32_bf16 v[12:15], v[16:19], v[122:125], 0
	v_mfma_f32_16x16x32_bf16 v[8:11], v[20:23], v[94:97], v[8:11]
	v_mfma_f32_16x16x32_bf16 v[206:209], v[20:23], v[126:129], v[12:15]
	v_mfma_f32_16x16x32_bf16 v[12:15], v[24:27], v[122:125], 0
	v_mfma_f32_16x16x32_bf16 v[210:213], v[28:31], v[126:129], v[12:15]
	s_barrier
	s_add_i32 s0, 0, 0x18000
	v_add_u32_e32 v20, s0, v152
	s_add_i32 s3, 0, 0x1c000
	s_nop 1
	ds_read_b128 v[12:15], v20
	ds_read_b128 v[16:19], v20 offset:1024
	ds_read_b128 v[24:27], v20 offset:2048
	ds_read_b128 v[214:217], v20 offset:3072
	v_add_u32_e32 v20, s3, v152
	ds_read_b128 v[218:221], v20
	ds_read_b128 v[222:225], v20 offset:1024
	ds_read_b128 v[226:229], v20 offset:2048
	ds_read_b128 v[230:233], v20 offset:3072
	s_mov_b32 m0, s73
	v_lshl_add_u64 v[94:95], s[68:69], 0, v[136:137]
	ds_read_b128 v[20:23], v153 offset:32768
	ds_read_b128 v[28:31], v153 offset:33792
	ds_read_b128 v[60:63], v153 offset:34816
	ds_read_b128 v[234:237], v153 offset:35840
	ds_read_b128 v[238:241], v153 offset:36864
	ds_read_b128 v[242:245], v153 offset:37888
	ds_read_b128 v[246:249], v153 offset:38912
	ds_read_b128 v[168:171], v153 offset:39936
	global_load_lds_dwordx4 v[94:95], off
	v_lshl_add_u64 v[94:95], s[68:69], 0, v[138:139]
	s_mov_b32 m0, s74
	s_nop 0
	global_load_lds_dwordx4 v[94:95], off
	s_waitcnt vmcnt(8)
	s_waitcnt lgkmcnt(0)
	s_barrier
	s_waitcnt lgkmcnt(0)
	v_mfma_f32_16x16x32_bf16 v[64:67], v[12:15], v[20:23], v[64:67]
	v_mfma_f32_16x16x32_bf16 v[126:129], v[16:19], v[28:31], v[64:67]
	v_mfma_f32_16x16x32_bf16 v[64:67], v[24:27], v[20:23], v[68:71]
	v_mfma_f32_16x16x32_bf16 v[118:121], v[214:217], v[28:31], v[64:67]
	v_mfma_f32_16x16x32_bf16 v[64:67], v[12:15], v[60:63], v[72:75]
	v_mfma_f32_16x16x32_bf16 v[110:113], v[16:19], v[234:237], v[64:67]
	v_mfma_f32_16x16x32_bf16 v[64:67], v[24:27], v[60:63], v[76:79]
	v_mfma_f32_16x16x32_bf16 v[102:105], v[214:217], v[234:237], v[64:67]
	v_mfma_f32_16x16x32_bf16 v[64:67], v[12:15], v[238:241], v[82:85]
	v_mfma_f32_16x16x32_bf16 v[94:97], v[16:19], v[242:245], v[64:67]
	v_mfma_f32_16x16x32_bf16 v[64:67], v[24:27], v[238:241], v[86:89]
	v_mfma_f32_16x16x32_bf16 v[86:89], v[214:217], v[242:245], v[64:67]
	v_mfma_f32_16x16x32_bf16 v[64:67], v[12:15], v[246:249], v[90:93]
	v_mfma_f32_16x16x32_bf16 v[76:79], v[16:19], v[168:171], v[64:67]
	v_mfma_f32_16x16x32_bf16 v[64:67], v[24:27], v[246:249], v[98:101]
	v_mfma_f32_16x16x32_bf16 v[68:71], v[214:217], v[168:171], v[64:67]
	v_mfma_f32_16x16x32_bf16 v[64:67], v[218:221], v[20:23], v[106:109]
	v_mfma_f32_16x16x32_bf16 v[20:23], v[226:229], v[20:23], v[32:35]
	v_mfma_f32_16x16x32_bf16 v[114:117], v[230:233], v[28:31], v[20:23]
	v_mfma_f32_16x16x32_bf16 v[20:23], v[218:221], v[60:63], v[36:39]
	v_mfma_f32_16x16x32_bf16 v[106:109], v[222:225], v[234:237], v[20:23]
	v_mfma_f32_16x16x32_bf16 v[20:23], v[226:229], v[60:63], v[40:43]
	v_mfma_f32_16x16x32_bf16 v[98:101], v[230:233], v[234:237], v[20:23]
	v_mfma_f32_16x16x32_bf16 v[20:23], v[218:221], v[238:241], v[44:47]
	v_mfma_f32_16x16x32_bf16 v[90:93], v[222:225], v[242:245], v[20:23]
	v_mfma_f32_16x16x32_bf16 v[20:23], v[226:229], v[238:241], v[48:51]
	v_mfma_f32_16x16x32_bf16 v[82:85], v[230:233], v[242:245], v[20:23]
	v_mfma_f32_16x16x32_bf16 v[20:23], v[218:221], v[246:249], v[52:55]
	v_mfma_f32_16x16x32_bf16 v[72:75], v[222:225], v[168:171], v[20:23]
	v_mfma_f32_16x16x32_bf16 v[20:23], v[226:229], v[246:249], v[56:59]
	v_mfma_f32_16x16x32_bf16 v[122:125], v[222:225], v[28:31], v[64:67]
	v_mfma_f32_16x16x32_bf16 v[64:67], v[230:233], v[168:171], v[20:23]
	s_barrier
; #define PG8_STAGE(bufoff, gbase, voff) do { _Pragma("unroll") for (int _i = 0; _i < 2; ++_i) \
;         __builtin_amdgcn_global_load_lds((const unsigned*)((const char*)(gbase) + (voff)[_i]), (LAS unsigned*)(lds + (bufoff) + ldsw + _i * 8192), 16, 0, 0); } while (0)
; #define PG8_LDA(dst, b, h) do { _Pragma("unroll") for (int m = 0; m < 4; ++m) _Pragma("unroll") for (int k = 0; k < 2; ++k) dst[m][k] = *(const LAS bf16x8*)(lds + PG8_SA(b, h) + aoff + m * 2048 + k * 1024); } while (0)
; #define PG8_MMA(ai, bj, At, Bt) do { __builtin_amdgcn_s_setprio(1); _Pragma("unroll") for (int m = 0; m < 4; ++m) _Pragma("unroll") for (int n = 0; n < 2; ++n) _Pragma("unroll") for (int k = 0; k < 2; ++k) \
;         acc[ai][bj][m][n] = __builtin_amdgcn_mfma_f32_16x16x32_bf16(Bt[n][k], At[m][k], acc[ai][bj][m][n], 0, 0, 0); __builtin_amdgcn_s_setprio(0); } while (0)
; #define PG8_WAIT_V(n) asm volatile("s_waitcnt vmcnt(" #n ")" ::: "memory")
; #define PG8_WAIT_L(n) asm volatile("s_waitcnt lgkmcnt(" #n ")" ::: "memory")
; #define PG8_BAR __builtin_amdgcn_s_barrier()
; #define PG8_SCHED __builtin_amdgcn_sched_barrier(0)
; template <class Epi, bool ALIGN_EPI>
; __device__ __forceinline__ void gemm_phase(LAS unsigned char* lds, const Gemm g, const StaticOrder S, const Epi E) {
;     ...
;             PG8_LDA(At, 1, 1); PG8_STAGE(PG8_SB(1, 0), b3, voffB); PG8_STAGE(PG8_SB(1, 1), b3 + hstepB, voffB); PG8_STAGE(PG8_SA(1, 0), a3, voffA);
;             PG8_WAIT_V(8); PG8_WAIT_L(0); PG8_BAR; PG8_MMA(1, 0, At, B0); PG8_MMA(1, 1, At, B1); PG8_BAR; PG8_SCHED;
;         }
;         if constexpr (ALIGN_EPI) { if (wr == 0) PG8_BAR; }
	s_add_i32 s0, s0, s61
	s_nop 2
	v_lshl_add_u64 v[20:21], v[172:173], 0, s[80:81]
	s_mov_b32 m0, s0
	ds_read_b128 v[32:35], v153 offset:49152
	ds_read_b128 v[40:43], v153 offset:50176
	ds_read_b128 v[168:171], v153 offset:51200
	ds_read_b128 v[234:237], v153 offset:52224
	ds_read_b128 v[238:241], v153 offset:53248
	ds_read_b128 v[242:245], v153 offset:54272
	ds_read_b128 v[246:249], v153 offset:55296
	ds_read_b128 v[176:179], v153 offset:56320
	global_load_lds_dwordx4 v[20:21], off
	s_add_i32 m0, s0, 0x2000
	s_add_u32 s0, s64, 0x20080
	v_lshl_add_u64 v[20:21], v[134:135], 0, s[80:81]
	s_addc_u32 s1, s65, 0
	s_add_i32 s3, s3, s61
	global_load_lds_dwordx4 v[20:21], off
	v_lshl_add_u64 v[20:21], s[0:1], 0, v[80:81]
	s_mov_b32 m0, s3
	s_nop 0
	global_load_lds_dwordx4 v[20:21], off
	v_lshl_add_u64 v[20:21], s[0:1], 0, v[140:141]
	s_add_i32 m0, s3, 0x2000
	s_nop 0
	global_load_lds_dwordx4 v[20:21], off
	v_lshl_add_u64 v[20:21], v[250:251], 0, s[80:81]
	s_mov_b32 m0, s41
	s_nop 0
	global_load_lds_dwordx4 v[20:21], off
	v_lshl_add_u64 v[20:21], v[130:131], 0, s[80:81]
	s_mov_b32 m0, s22
	s_nop 0
	global_load_lds_dwordx4 v[20:21], off
	s_waitcnt vmcnt(8)
	s_waitcnt lgkmcnt(0)
	s_barrier
	s_waitcnt lgkmcnt(0)
	v_mfma_f32_16x16x32_bf16 v[20:23], v[12:15], v[32:35], v[142:145]
	v_mfma_f32_16x16x32_bf16 v[60:63], v[16:19], v[40:43], v[20:23]
	v_mfma_f32_16x16x32_bf16 v[20:23], v[24:27], v[32:35], v[146:149]
	v_mfma_f32_16x16x32_bf16 v[52:55], v[214:217], v[40:43], v[20:23]
	v_mfma_f32_16x16x32_bf16 v[20:23], v[12:15], v[168:171], v[154:157]
	v_mfma_f32_16x16x32_bf16 v[44:47], v[16:19], v[234:237], v[20:23]
	v_mfma_f32_16x16x32_bf16 v[20:23], v[24:27], v[168:171], v[158:161]
	v_mfma_f32_16x16x32_bf16 v[36:39], v[214:217], v[234:237], v[20:23]
	v_mfma_f32_16x16x32_bf16 v[20:23], v[12:15], v[238:241], v[162:165]
	v_mfma_f32_16x16x32_bf16 v[0:3], v[12:15], v[246:249], v[0:3]
	v_mfma_f32_16x16x32_bf16 v[28:31], v[16:19], v[242:245], v[20:23]
	v_mfma_f32_16x16x32_bf16 v[20:23], v[24:27], v[238:241], v[182:185]
	v_mfma_f32_16x16x32_bf16 v[12:15], v[16:19], v[176:179], v[0:3]
	v_mfma_f32_16x16x32_bf16 v[0:3], v[24:27], v[246:249], v[4:7]
	v_mfma_f32_16x16x32_bf16 v[20:23], v[214:217], v[242:245], v[20:23]
	v_mfma_f32_16x16x32_bf16 v[4:7], v[214:217], v[176:179], v[0:3]
	v_mfma_f32_16x16x32_bf16 v[0:3], v[218:221], v[32:35], v[8:11]
	v_mfma_f32_16x16x32_bf16 v[56:59], v[222:225], v[40:43], v[0:3]
	v_mfma_f32_16x16x32_bf16 v[0:3], v[226:229], v[32:35], v[186:189]
	v_mfma_f32_16x16x32_bf16 v[48:51], v[230:233], v[40:43], v[0:3]
	v_mfma_f32_16x16x32_bf16 v[0:3], v[218:221], v[168:171], v[190:193]
	v_mfma_f32_16x16x32_bf16 v[40:43], v[222:225], v[234:237], v[0:3]
	v_mfma_f32_16x16x32_bf16 v[0:3], v[226:229], v[168:171], v[194:197]
	v_mfma_f32_16x16x32_bf16 v[32:35], v[230:233], v[234:237], v[0:3]
	v_mfma_f32_16x16x32_bf16 v[0:3], v[218:221], v[238:241], v[198:201]
	v_mfma_f32_16x16x32_bf16 v[24:27], v[222:225], v[242:245], v[0:3]
	v_mfma_f32_16x16x32_bf16 v[0:3], v[226:229], v[238:241], v[202:205]
	v_mfma_f32_16x16x32_bf16 v[16:19], v[230:233], v[242:245], v[0:3]
	v_mfma_f32_16x16x32_bf16 v[0:3], v[218:221], v[246:249], v[206:209]
	v_mfma_f32_16x16x32_bf16 v[8:11], v[222:225], v[176:179], v[0:3]
	v_mfma_f32_16x16x32_bf16 v[0:3], v[226:229], v[246:249], v[210:213]
	v_mfma_f32_16x16x32_bf16 v[0:3], v[230:233], v[176:179], v[0:3]
	s_barrier
	s_andn2_b64 vcc, exec, s[46:47]
	s_cbranch_vccnz .LBB0_1057
	s_barrier

; #define PG8_STAGE(bufoff, gbase, voff) do { _Pragma("unroll") for (int _i = 0; _i < 2; ++_i) \
;         __builtin_amdgcn_global_load_lds((const unsigned*)((const char*)(gbase) + (voff)[_i]), (LAS unsigned*)(lds + (bufoff) + ldsw + _i * 8192), 16, 0, 0); } while (0)
; #define PG8_LDA(dst, b, h) do { _Pragma("unroll") for (int m = 0; m < 4; ++m) _Pragma("unroll") for (int k = 0; k < 2; ++k) dst[m][k] = *(const LAS bf16x8*)(lds + PG8_SA(b, h) + aoff + m * 2048 + k * 1024); } while (0)
; #define PG8_LDB(dst, b, h) do { _Pragma("unroll") for (int n = 0; n < 2; ++n) _Pragma("unroll") for (int k = 0; k < 2; ++k) dst[n][k] = *(const LAS bf16x8*)(lds + PG8_SB(b, h) + boff + n * 2048 + k * 1024); } while (0)
; #define PG8_MMA(ai, bj, At, Bt) do { __builtin_amdgcn_s_setprio(1); _Pragma("unroll") for (int m = 0; m < 4; ++m) _Pragma("unroll") for (int n = 0; n < 2; ++n) _Pragma("unroll") for (int k = 0; k < 2; ++k) \
;         acc[ai][bj][m][n] = __builtin_amdgcn_mfma_f32_16x16x32_bf16(Bt[n][k], At[m][k], acc[ai][bj][m][n], 0, 0, 0); __builtin_amdgcn_s_setprio(0); } while (0)
; #define PG8_WAIT_V(n) asm volatile("s_waitcnt vmcnt(" #n ")" ::: "memory")
; #define PG8_WAIT_L(n) asm volatile("s_waitcnt lgkmcnt(" #n ")" ::: "memory")
; #define PG8_BAR __builtin_amdgcn_s_barrier()
; #define PG8_SCHED __builtin_amdgcn_sched_barrier(0)
; template <class Epi, bool ALIGN_EPI>
; __device__ __forceinline__ void gemm_phase(LAS unsigned char* lds, const Gemm g, const StaticOrder S, const Epi E) {
;     ...
;             const bool last = (t == nt - 2);
;             const char* a1 = cA + (size_t)(t + 1) * kstep;
;             const char* a2 = last ? nA : cA + (size_t)(t + 2) * kstep; const char* b2 = last ? nB : cB + (size_t)(t + 2) * kstep;
;             const char* a3 = a2 + kstep; const char* b3 = b2 + kstep;
;             PG8_LDB(B0, 0, 0); PG8_LDB(B1, 0, 1); PG8_SCHED; PG8_LDA(At, 0, 0); PG8_STAGE(PG8_SA(1, 1), a1 + hstepA, voffA);
;             PG8_WAIT_V(8); PG8_WAIT_L(0); PG8_BAR; PG8_MMA(0, 0, At, B0); PG8_MMA(0, 1, At, B1); PG8_BAR; PG8_SCHED;
;     ...
; #pragma unroll
;         for (int a = 0; a < 2; ++a)
; #pragma unroll
;             for (int b = 0; b < 2; ++b)
; #pragma unroll
;                 for (int m = 0; m < 4; ++m)
; #pragma unroll
;                     for (int n = 0; n < 2; ++n) acc[a][b][m][n] = (f32x4){0.f, 0.f, 0.f, 0.f};
;         cur = nxt; cA = nA; cB = nB; ++ui;
.LBB0_1430:
	s_ashr_i32 s49, s48, 31
	s_lshl_b64 s[0:1], s[48:49], 19
	v_readlane_b32 s12, v255, 29
	s_add_u32 s52, s12, s0
	v_readlane_b32 s0, v255, 30
	s_addc_u32 s53, s0, s1
	s_and_b64 s[0:1], s[44:45], exec
	s_cselect_b32 s34, s53, s65
	s_cselect_b32 s35, s52, s64
	s_add_u32 s49, s64, 0x100
	v_mov_b32_e32 v0, 0
	s_addc_u32 s55, s65, 0
	s_mov_b32 s71, -2
	v_mov_b32_e32 v1, 0
	v_mov_b64_e32 v[2:3], 0
	v_mov_b64_e32 v[4:5], 0
	v_mov_b64_e32 v[6:7], 0
	v_mov_b64_e32 v[8:9], 0
	v_mov_b64_e32 v[10:11], 0
	v_mov_b64_e32 v[12:13], 0
	v_mov_b64_e32 v[14:15], 0
	v_mov_b64_e32 v[16:17], 0
	v_mov_b64_e32 v[18:19], 0
	v_mov_b64_e32 v[20:21], 0
	v_mov_b64_e32 v[22:23], 0
	v_mov_b64_e32 v[24:25], 0
	v_mov_b64_e32 v[26:27], 0
	v_mov_b64_e32 v[28:29], 0
	v_mov_b64_e32 v[30:31], 0
	v_mov_b64_e32 v[32:33], 0
	v_mov_b64_e32 v[34:35], 0
	v_mov_b64_e32 v[36:37], 0
	v_mov_b64_e32 v[38:39], 0
	v_mov_b64_e32 v[40:41], 0
	v_mov_b64_e32 v[42:43], 0
	v_mov_b64_e32 v[44:45], 0
	v_mov_b64_e32 v[46:47], 0
	v_mov_b64_e32 v[48:49], 0
	v_mov_b64_e32 v[50:51], 0
	v_mov_b64_e32 v[52:53], 0
	v_mov_b64_e32 v[54:55], 0
	v_mov_b64_e32 v[56:57], 0
	v_mov_b64_e32 v[58:59], 0
	v_mov_b64_e32 v[60:61], 0
	v_mov_b64_e32 v[62:63], 0
	v_mov_b64_e32 v[64:65], 0
	v_mov_b64_e32 v[66:67], 0
	v_mov_b64_e32 v[68:69], 0
	v_mov_b64_e32 v[70:71], 0
	v_mov_b64_e32 v[72:73], 0
	v_mov_b64_e32 v[74:75], 0
	v_mov_b64_e32 v[76:77], 0
	v_mov_b64_e32 v[78:79], 0
	v_mov_b64_e32 v[82:83], 0
	v_mov_b64_e32 v[84:85], 0
	v_mov_b64_e32 v[86:87], 0
	v_mov_b64_e32 v[88:89], 0
	v_mov_b64_e32 v[90:91], 0
	v_mov_b64_e32 v[92:93], 0
	v_mov_b64_e32 v[94:95], 0
	v_mov_b64_e32 v[96:97], 0
	v_mov_b64_e32 v[98:99], 0
	v_mov_b64_e32 v[100:101], 0
	v_mov_b64_e32 v[102:103], 0
	v_mov_b64_e32 v[104:105], 0
	v_mov_b64_e32 v[106:107], 0
	v_mov_b64_e32 v[108:109], 0
	v_mov_b64_e32 v[110:111], 0
	v_mov_b64_e32 v[112:113], 0
	v_mov_b64_e32 v[114:115], 0
	v_mov_b64_e32 v[116:117], 0
	v_mov_b64_e32 v[118:119], 0
	v_mov_b64_e32 v[120:121], 0
	v_mov_b64_e32 v[122:123], 0
	v_mov_b64_e32 v[124:125], 0
	v_mov_b64_e32 v[126:127], 0
	v_mov_b64_e32 v[128:129], 0
	v_readfirstlane_b32 s0, v167
	s_nop 3
	s_cmpk_lt_u32 s0, 0x100
	s_cbranch_scc1 .Lprio_k3
	s_setprio 1
.Lprio_k3:
.LBB0_1431:
	s_add_u32 s44, s62, 0x100
	s_addc_u32 s45, s63, 0
	s_add_i32 s0, 0, 0x10000
	s_cmp_eq_u32 s71, 12
	s_cselect_b32 s67, s51, s45
	s_cselect_b32 s66, s50, s44
	v_add_u32_e32 v130, s0, v152
	s_cselect_b32 s65, s34, s55
	s_cselect_b32 s64, s35, s49
	s_add_i32 s12, 0, 0x14000
	ds_read_b128 v[146:149], v130
	ds_read_b128 v[154:157], v130 offset:1024
	ds_read_b128 v[158:161], v130 offset:2048
	ds_read_b128 v[162:165], v130 offset:3072
	v_add_u32_e32 v130, s12, v152
	ds_read_b128 v[168:171], v130
	ds_read_b128 v[176:179], v130 offset:1024
	ds_read_b128 v[182:185], v130 offset:2048
	ds_read_b128 v[186:189], v130 offset:3072
	v_lshl_add_u64 v[130:131], s[62:63], 0, v[142:143]
	s_add_i32 m0, s27, 0xc000
	ds_read_b128 v[190:193], v153
	ds_read_b128 v[194:197], v153 offset:1024
	ds_read_b128 v[198:201], v153 offset:2048
	ds_read_b128 v[202:205], v153 offset:3072
	ds_read_b128 v[206:209], v153 offset:4096
	ds_read_b128 v[210:213], v153 offset:5120
	ds_read_b128 v[214:217], v153 offset:6144
	ds_read_b128 v[218:221], v153 offset:7168
	global_load_lds_dwordx4 v[130:131], off
	v_lshl_add_u64 v[130:131], s[62:63], 0, v[144:145]
	s_add_i32 m0, s27, 0xe000
	s_nop 0
	global_load_lds_dwordx4 v[130:131], off
	s_waitcnt vmcnt(8)
	s_waitcnt lgkmcnt(0)
	s_barrier
	s_waitcnt lgkmcnt(0)
	v_mfma_f32_16x16x32_bf16 v[126:129], v[146:149], v[190:193], v[126:129]
	v_mfma_f32_16x16x32_bf16 v[122:125], v[158:161], v[190:193], v[122:125]
	v_mfma_f32_16x16x32_bf16 v[110:113], v[146:149], v[198:201], v[110:113]
	v_mfma_f32_16x16x32_bf16 v[106:109], v[158:161], v[198:201], v[106:109]
	v_mfma_f32_16x16x32_bf16 v[94:97], v[146:149], v[206:209], v[94:97]
	v_mfma_f32_16x16x32_bf16 v[90:93], v[158:161], v[206:209], v[90:93]
	v_mfma_f32_16x16x32_bf16 v[76:79], v[146:149], v[214:217], v[76:79]
	v_mfma_f32_16x16x32_bf16 v[72:75], v[158:161], v[214:217], v[72:75]
	v_mfma_f32_16x16x32_bf16 v[126:129], v[154:157], v[194:197], v[126:129]
	v_mfma_f32_16x16x32_bf16 v[122:125], v[162:165], v[194:197], v[122:125]
	v_mfma_f32_16x16x32_bf16 v[110:113], v[154:157], v[202:205], v[110:113]
	v_mfma_f32_16x16x32_bf16 v[106:109], v[162:165], v[202:205], v[106:109]
	v_mfma_f32_16x16x32_bf16 v[94:97], v[154:157], v[210:213], v[94:97]
	v_mfma_f32_16x16x32_bf16 v[90:93], v[162:165], v[210:213], v[90:93]
	v_mfma_f32_16x16x32_bf16 v[76:79], v[154:157], v[218:221], v[76:79]
	v_mfma_f32_16x16x32_bf16 v[72:75], v[162:165], v[218:221], v[72:75]
	v_mfma_f32_16x16x32_bf16 v[118:121], v[168:171], v[190:193], v[118:121]
	v_mfma_f32_16x16x32_bf16 v[114:117], v[182:185], v[190:193], v[114:117]
	v_mfma_f32_16x16x32_bf16 v[102:105], v[168:171], v[198:201], v[102:105]
	v_mfma_f32_16x16x32_bf16 v[98:101], v[182:185], v[198:201], v[98:101]
	v_mfma_f32_16x16x32_bf16 v[86:89], v[168:171], v[206:209], v[86:89]
	v_mfma_f32_16x16x32_bf16 v[82:85], v[182:185], v[206:209], v[82:85]
	v_mfma_f32_16x16x32_bf16 v[68:71], v[168:171], v[214:217], v[68:71]
	v_mfma_f32_16x16x32_bf16 v[64:67], v[182:185], v[214:217], v[64:67]
	v_mfma_f32_16x16x32_bf16 v[118:121], v[176:179], v[194:197], v[118:121]
	v_mfma_f32_16x16x32_bf16 v[114:117], v[186:189], v[194:197], v[114:117]
	v_mfma_f32_16x16x32_bf16 v[102:105], v[176:179], v[202:205], v[102:105]
	v_mfma_f32_16x16x32_bf16 v[98:101], v[186:189], v[202:205], v[98:101]
	v_mfma_f32_16x16x32_bf16 v[86:89], v[176:179], v[210:213], v[86:89]
	v_mfma_f32_16x16x32_bf16 v[82:85], v[186:189], v[210:213], v[82:85]
	v_mfma_f32_16x16x32_bf16 v[68:71], v[176:179], v[218:221], v[68:71]
	v_mfma_f32_16x16x32_bf16 v[64:67], v[186:189], v[218:221], v[64:67]
	s_barrier
; #define PG8_STAGE(bufoff, gbase, voff) do { _Pragma("unroll") for (int _i = 0; _i < 2; ++_i) \
;         __builtin_amdgcn_global_load_lds((const unsigned*)((const char*)(gbase) + (voff)[_i]), (LAS unsigned*)(lds + (bufoff) + ldsw + _i * 8192), 16, 0, 0); } while (0)
; #define PG8_LDA(dst, b, h) do { _Pragma("unroll") for (int m = 0; m < 4; ++m) _Pragma("unroll") for (int k = 0; k < 2; ++k) dst[m][k] = *(const LAS bf16x8*)(lds + PG8_SA(b, h) + aoff + m * 2048 + k * 1024); } while (0)
; #define PG8_LDB(dst, b, h) do { _Pragma("unroll") for (int n = 0; n < 2; ++n) _Pragma("unroll") for (int k = 0; k < 2; ++k) dst[n][k] = *(const LAS bf16x8*)(lds + PG8_SB(b, h) + boff + n * 2048 + k * 1024); } while (0)
; #define PG8_MMA(ai, bj, At, Bt) do { __builtin_amdgcn_s_setprio(1); _Pragma("unroll") for (int m = 0; m < 4; ++m) _Pragma("unroll") for (int n = 0; n < 2; ++n) _Pragma("unroll") for (int k = 0; k < 2; ++k) \
;         acc[ai][bj][m][n] = __builtin_amdgcn_mfma_f32_16x16x32_bf16(Bt[n][k], At[m][k], acc[ai][bj][m][n], 0, 0, 0); __builtin_amdgcn_s_setprio(0); } while (0)
; #define PG8_WAIT_V(n) asm volatile("s_waitcnt vmcnt(" #n ")" ::: "memory")
; #define PG8_WAIT_L(n) asm volatile("s_waitcnt lgkmcnt(" #n ")" ::: "memory")
; #define PG8_BAR __builtin_amdgcn_s_barrier()
; #define PG8_SCHED __builtin_amdgcn_sched_barrier(0)
; template <class Epi, bool ALIGN_EPI>
; __device__ __forceinline__ void gemm_phase(LAS unsigned char* lds, const Gemm g, const StaticOrder S, const Epi E) {
;     ...
;             PG8_LDA(At, 0, 1); PG8_STAGE(PG8_SB(0, 0), b2, voffB); PG8_STAGE(PG8_SB(0, 1), b2 + hstepB, voffB); PG8_STAGE(PG8_SA(0, 0), a2, voffA);
;             PG8_WAIT_V(8); PG8_WAIT_L(0); PG8_BAR; PG8_MMA(1, 0, At, B0); PG8_MMA(1, 1, At, B1); PG8_BAR; PG8_SCHED;
;             PG8_LDB(B0, 1, 0); PG8_LDB(B1, 1, 1); PG8_SCHED; PG8_LDA(At, 1, 0); PG8_STAGE(PG8_SA(0, 1), a2 + hstepA, voffA);
;             PG8_WAIT_V(8); PG8_WAIT_L(0); PG8_BAR; PG8_MMA(0, 0, At, B0); PG8_MMA(0, 1, At, B1); PG8_BAR; PG8_SCHED;
	s_add_i32 s0, s0, s26
	v_lshl_add_u64 v[130:131], s[64:65], 0, v[80:81]
	s_mov_b32 m0, s0
	ds_read_b128 v[190:193], v153 offset:16384
	ds_read_b128 v[194:197], v153 offset:17408
	ds_read_b128 v[198:201], v153 offset:18432
	ds_read_b128 v[202:205], v153 offset:19456
	ds_read_b128 v[206:209], v153 offset:20480
	ds_read_b128 v[210:213], v153 offset:21504
	ds_read_b128 v[214:217], v153 offset:22528
	ds_read_b128 v[218:221], v153 offset:23552
	global_load_lds_dwordx4 v[130:131], off
	s_add_i32 m0, s0, 0x2000
	s_add_u32 s0, s64, 0x40000
	v_lshl_add_u64 v[134:135], s[64:65], 0, v[140:141]
	s_addc_u32 s1, s65, 0
	s_add_i32 s12, s12, s26
	global_load_lds_dwordx4 v[134:135], off
	v_lshl_add_u64 v[172:173], s[0:1], 0, v[80:81]
	s_mov_b32 m0, s12
	v_lshl_add_u64 v[222:223], s[66:67], 0, v[138:139]
	global_load_lds_dwordx4 v[172:173], off
	v_lshl_add_u64 v[172:173], s[0:1], 0, v[140:141]
	s_add_i32 m0, s12, 0x2000
	s_nop 0
	global_load_lds_dwordx4 v[172:173], off
	v_lshl_add_u64 v[172:173], s[66:67], 0, v[136:137]
	s_mov_b32 m0, s27
	s_nop 0
	global_load_lds_dwordx4 v[172:173], off
	s_mov_b32 m0, s28
	s_nop 0
	global_load_lds_dwordx4 v[222:223], off
	s_waitcnt vmcnt(8)
	s_waitcnt lgkmcnt(0)
	s_barrier
	s_waitcnt lgkmcnt(0)
	v_mfma_f32_16x16x32_bf16 v[60:63], v[146:149], v[190:193], v[60:63]
	v_mfma_f32_16x16x32_bf16 v[56:59], v[158:161], v[190:193], v[56:59]
	v_mfma_f32_16x16x32_bf16 v[44:47], v[146:149], v[198:201], v[44:47]
	v_mfma_f32_16x16x32_bf16 v[40:43], v[158:161], v[198:201], v[40:43]
	v_mfma_f32_16x16x32_bf16 v[28:31], v[146:149], v[206:209], v[28:31]
	v_mfma_f32_16x16x32_bf16 v[24:27], v[158:161], v[206:209], v[24:27]
	v_mfma_f32_16x16x32_bf16 v[12:15], v[146:149], v[214:217], v[12:15]
	v_mfma_f32_16x16x32_bf16 v[8:11], v[158:161], v[214:217], v[8:11]
	v_mfma_f32_16x16x32_bf16 v[60:63], v[154:157], v[194:197], v[60:63]
	v_mfma_f32_16x16x32_bf16 v[56:59], v[162:165], v[194:197], v[56:59]
	v_mfma_f32_16x16x32_bf16 v[44:47], v[154:157], v[202:205], v[44:47]
	v_mfma_f32_16x16x32_bf16 v[40:43], v[162:165], v[202:205], v[40:43]
	v_mfma_f32_16x16x32_bf16 v[28:31], v[154:157], v[210:213], v[28:31]
	v_mfma_f32_16x16x32_bf16 v[24:27], v[162:165], v[210:213], v[24:27]
	v_mfma_f32_16x16x32_bf16 v[12:15], v[154:157], v[218:221], v[12:15]
	v_mfma_f32_16x16x32_bf16 v[8:11], v[162:165], v[218:221], v[8:11]
	v_mfma_f32_16x16x32_bf16 v[52:55], v[168:171], v[190:193], v[52:55]
	v_mfma_f32_16x16x32_bf16 v[48:51], v[182:185], v[190:193], v[48:51]
	v_mfma_f32_16x16x32_bf16 v[36:39], v[168:171], v[198:201], v[36:39]
	v_mfma_f32_16x16x32_bf16 v[32:35], v[182:185], v[198:201], v[32:35]
	v_mfma_f32_16x16x32_bf16 v[20:23], v[168:171], v[206:209], v[20:23]
	v_mfma_f32_16x16x32_bf16 v[16:19], v[182:185], v[206:209], v[16:19]
	v_mfma_f32_16x16x32_bf16 v[4:7], v[168:171], v[214:217], v[4:7]
	v_mfma_f32_16x16x32_bf16 v[0:3], v[182:185], v[214:217], v[0:3]
	v_mfma_f32_16x16x32_bf16 v[52:55], v[176:179], v[194:197], v[52:55]
	v_mfma_f32_16x16x32_bf16 v[48:51], v[186:189], v[194:197], v[48:51]
	v_mfma_f32_16x16x32_bf16 v[36:39], v[176:179], v[202:205], v[36:39]
	v_mfma_f32_16x16x32_bf16 v[32:35], v[186:189], v[202:205], v[32:35]
	v_mfma_f32_16x16x32_bf16 v[20:23], v[176:179], v[210:213], v[20:23]
	v_mfma_f32_16x16x32_bf16 v[16:19], v[186:189], v[210:213], v[16:19]
	v_mfma_f32_16x16x32_bf16 v[4:7], v[176:179], v[218:221], v[4:7]
	v_mfma_f32_16x16x32_bf16 v[0:3], v[186:189], v[218:221], v[0:3]
	s_barrier
	s_add_i32 s12, 0, 0x18000
	s_add_i32 s15, 0, 0x1c000
	v_add_u32_e32 v162, s12, v152
	v_add_u32_e32 v166, s15, v152
	ds_read_b128 v[146:149], v162
	ds_read_b128 v[154:157], v162 offset:1024
	ds_read_b128 v[158:161], v162 offset:2048
	ds_read_b128 v[162:165], v162 offset:3072
	ds_read_b128 v[168:171], v166
	ds_read_b128 v[176:179], v166 offset:1024
	ds_read_b128 v[182:185], v166 offset:2048
	ds_read_b128 v[186:189], v166 offset:3072
	s_add_u32 s0, s66, 0xb0000
	s_addc_u32 s1, s67, 0
	s_mov_b32 m0, s29
	v_lshl_add_u64 v[224:225], s[0:1], 0, v[136:137]
	ds_read_b128 v[190:193], v153 offset:32768
	ds_read_b128 v[194:197], v153 offset:33792
	ds_read_b128 v[198:201], v153 offset:34816
	ds_read_b128 v[202:205], v153 offset:35840
	ds_read_b128 v[206:209], v153 offset:36864
	ds_read_b128 v[210:213], v153 offset:37888
	ds_read_b128 v[214:217], v153 offset:38912
	ds_read_b128 v[218:221], v153 offset:39936
	global_load_lds_dwordx4 v[224:225], off
	v_lshl_add_u64 v[224:225], s[0:1], 0, v[138:139]
	s_mov_b32 m0, s30
	s_nop 0
	global_load_lds_dwordx4 v[224:225], off
	s_waitcnt vmcnt(8)
	s_waitcnt lgkmcnt(0)
	s_barrier
; #define PG8_STAGE(bufoff, gbase, voff) do { _Pragma("unroll") for (int _i = 0; _i < 2; ++_i) \
;         __builtin_amdgcn_global_load_lds((const unsigned*)((const char*)(gbase) + (voff)[_i]), (LAS unsigned*)(lds + (bufoff) + ldsw + _i * 8192), 16, 0, 0); } while (0)
; #define PG8_LDA(dst, b, h) do { _Pragma("unroll") for (int m = 0; m < 4; ++m) _Pragma("unroll") for (int k = 0; k < 2; ++k) dst[m][k] = *(const LAS bf16x8*)(lds + PG8_SA(b, h) + aoff + m * 2048 + k * 1024); } while (0)
; #define PG8_MMA(ai, bj, At, Bt) do { __builtin_amdgcn_s_setprio(1); _Pragma("unroll") for (int m = 0; m < 4; ++m) _Pragma("unroll") for (int n = 0; n < 2; ++n) _Pragma("unroll") for (int k = 0; k < 2; ++k) \
;         acc[ai][bj][m][n] = __builtin_amdgcn_mfma_f32_16x16x32_bf16(Bt[n][k], At[m][k], acc[ai][bj][m][n], 0, 0, 0); __builtin_amdgcn_s_setprio(0); } while (0)
; #define PG8_WAIT_V(n) asm volatile("s_waitcnt vmcnt(" #n ")" ::: "memory")
; #define PG8_WAIT_L(n) asm volatile("s_waitcnt lgkmcnt(" #n ")" ::: "memory")
; #define PG8_BAR __builtin_amdgcn_s_barrier()
; #define PG8_SCHED __builtin_amdgcn_sched_barrier(0)
; template <class Epi, bool ALIGN_EPI>
; __device__ __forceinline__ void gemm_phase(LAS unsigned char* lds, const Gemm g, const StaticOrder S, const Epi E) {
;     ...
;             PG8_WAIT_V(8); PG8_WAIT_L(0); PG8_BAR; PG8_MMA(0, 0, At, B0); PG8_MMA(0, 1, At, B1); PG8_BAR; PG8_SCHED;
;             PG8_LDA(At, 1, 1); PG8_STAGE(PG8_SB(1, 0), b3, voffB); PG8_STAGE(PG8_SB(1, 1), b3 + hstepB, voffB); PG8_STAGE(PG8_SA(1, 0), a3, voffA);
;             PG8_WAIT_V(8); PG8_WAIT_L(0); PG8_BAR; PG8_MMA(1, 0, At, B0); PG8_MMA(1, 1, At, B1); PG8_BAR; PG8_SCHED;
;         }
;         if constexpr (ALIGN_EPI) { if (wr == 0) PG8_BAR; }
	s_waitcnt lgkmcnt(0)
	v_mfma_f32_16x16x32_bf16 v[126:129], v[146:149], v[190:193], v[126:129]
	v_mfma_f32_16x16x32_bf16 v[122:125], v[158:161], v[190:193], v[122:125]
	v_mfma_f32_16x16x32_bf16 v[110:113], v[146:149], v[198:201], v[110:113]
	v_mfma_f32_16x16x32_bf16 v[106:109], v[158:161], v[198:201], v[106:109]
	v_mfma_f32_16x16x32_bf16 v[94:97], v[146:149], v[206:209], v[94:97]
	v_mfma_f32_16x16x32_bf16 v[90:93], v[158:161], v[206:209], v[90:93]
	v_mfma_f32_16x16x32_bf16 v[76:79], v[146:149], v[214:217], v[76:79]
	v_mfma_f32_16x16x32_bf16 v[72:75], v[158:161], v[214:217], v[72:75]
	v_mfma_f32_16x16x32_bf16 v[126:129], v[154:157], v[194:197], v[126:129]
	v_mfma_f32_16x16x32_bf16 v[122:125], v[162:165], v[194:197], v[122:125]
	v_mfma_f32_16x16x32_bf16 v[110:113], v[154:157], v[202:205], v[110:113]
	v_mfma_f32_16x16x32_bf16 v[106:109], v[162:165], v[202:205], v[106:109]
	v_mfma_f32_16x16x32_bf16 v[94:97], v[154:157], v[210:213], v[94:97]
	v_mfma_f32_16x16x32_bf16 v[90:93], v[162:165], v[210:213], v[90:93]
	v_mfma_f32_16x16x32_bf16 v[76:79], v[154:157], v[218:221], v[76:79]
	v_mfma_f32_16x16x32_bf16 v[72:75], v[162:165], v[218:221], v[72:75]
	v_mfma_f32_16x16x32_bf16 v[118:121], v[168:171], v[190:193], v[118:121]
	v_mfma_f32_16x16x32_bf16 v[114:117], v[182:185], v[190:193], v[114:117]
	v_mfma_f32_16x16x32_bf16 v[102:105], v[168:171], v[198:201], v[102:105]
	v_mfma_f32_16x16x32_bf16 v[98:101], v[182:185], v[198:201], v[98:101]
	v_mfma_f32_16x16x32_bf16 v[86:89], v[168:171], v[206:209], v[86:89]
	v_mfma_f32_16x16x32_bf16 v[82:85], v[182:185], v[206:209], v[82:85]
	v_mfma_f32_16x16x32_bf16 v[68:71], v[168:171], v[214:217], v[68:71]
	v_mfma_f32_16x16x32_bf16 v[64:67], v[182:185], v[214:217], v[64:67]
	v_mfma_f32_16x16x32_bf16 v[118:121], v[176:179], v[194:197], v[118:121]
	v_mfma_f32_16x16x32_bf16 v[114:117], v[186:189], v[194:197], v[114:117]
	v_mfma_f32_16x16x32_bf16 v[102:105], v[176:179], v[202:205], v[102:105]
	v_mfma_f32_16x16x32_bf16 v[98:101], v[186:189], v[202:205], v[98:101]
	v_mfma_f32_16x16x32_bf16 v[86:89], v[176:179], v[210:213], v[86:89]
	v_mfma_f32_16x16x32_bf16 v[82:85], v[186:189], v[210:213], v[82:85]
	v_mfma_f32_16x16x32_bf16 v[68:71], v[176:179], v[218:221], v[68:71]
	v_mfma_f32_16x16x32_bf16 v[64:67], v[186:189], v[218:221], v[64:67]
	s_barrier
	s_add_i32 s0, s12, s26
	v_lshl_add_u64 v[130:131], v[130:131], 0, s[80:81]
	s_mov_b32 m0, s0
	ds_read_b128 v[190:193], v153 offset:49152
	ds_read_b128 v[194:197], v153 offset:50176
	ds_read_b128 v[198:201], v153 offset:51200
	ds_read_b128 v[202:205], v153 offset:52224
	ds_read_b128 v[206:209], v153 offset:53248
	ds_read_b128 v[210:213], v153 offset:54272
	ds_read_b128 v[214:217], v153 offset:55296
	ds_read_b128 v[218:221], v153 offset:56320
	global_load_lds_dwordx4 v[130:131], off
	s_add_i32 m0, s0, 0x2000
	s_add_u32 s0, s64, 0x40080
	v_lshl_add_u64 v[130:131], v[134:135], 0, s[80:81]
	s_addc_u32 s1, s65, 0
	s_add_i32 s12, s15, s26
	global_load_lds_dwordx4 v[130:131], off
	v_lshl_add_u64 v[130:131], s[0:1], 0, v[80:81]
	s_mov_b32 m0, s12
	s_nop 0
	global_load_lds_dwordx4 v[130:131], off
	v_lshl_add_u64 v[130:131], s[0:1], 0, v[140:141]
	s_add_i32 m0, s12, 0x2000
	s_nop 0
	global_load_lds_dwordx4 v[130:131], off
	v_lshl_add_u64 v[130:131], v[172:173], 0, s[80:81]
	s_mov_b32 m0, s61
	s_nop 0
	global_load_lds_dwordx4 v[130:131], off
	v_lshl_add_u64 v[130:131], v[222:223], 0, s[80:81]
	s_mov_b32 m0, s68
	s_nop 0
	global_load_lds_dwordx4 v[130:131], off
	s_waitcnt vmcnt(8)
	s_waitcnt lgkmcnt(0)
	s_barrier
	s_waitcnt lgkmcnt(0)
	v_mfma_f32_16x16x32_bf16 v[60:63], v[146:149], v[190:193], v[60:63]
	v_mfma_f32_16x16x32_bf16 v[56:59], v[158:161], v[190:193], v[56:59]
	v_mfma_f32_16x16x32_bf16 v[44:47], v[146:149], v[198:201], v[44:47]
	v_mfma_f32_16x16x32_bf16 v[40:43], v[158:161], v[198:201], v[40:43]
	v_mfma_f32_16x16x32_bf16 v[28:31], v[146:149], v[206:209], v[28:31]
	v_mfma_f32_16x16x32_bf16 v[24:27], v[158:161], v[206:209], v[24:27]
	v_mfma_f32_16x16x32_bf16 v[12:15], v[146:149], v[214:217], v[12:15]
	v_mfma_f32_16x16x32_bf16 v[8:11], v[158:161], v[214:217], v[8:11]
	v_mfma_f32_16x16x32_bf16 v[60:63], v[154:157], v[194:197], v[60:63]
	v_mfma_f32_16x16x32_bf16 v[56:59], v[162:165], v[194:197], v[56:59]
	v_mfma_f32_16x16x32_bf16 v[44:47], v[154:157], v[202:205], v[44:47]
	v_mfma_f32_16x16x32_bf16 v[40:43], v[162:165], v[202:205], v[40:43]
	v_mfma_f32_16x16x32_bf16 v[28:31], v[154:157], v[210:213], v[28:31]
	v_mfma_f32_16x16x32_bf16 v[24:27], v[162:165], v[210:213], v[24:27]
	v_mfma_f32_16x16x32_bf16 v[12:15], v[154:157], v[218:221], v[12:15]
	v_mfma_f32_16x16x32_bf16 v[8:11], v[162:165], v[218:221], v[8:11]
	v_mfma_f32_16x16x32_bf16 v[52:55], v[168:171], v[190:193], v[52:55]
	v_mfma_f32_16x16x32_bf16 v[48:51], v[182:185], v[190:193], v[48:51]
	v_mfma_f32_16x16x32_bf16 v[36:39], v[168:171], v[198:201], v[36:39]
	v_mfma_f32_16x16x32_bf16 v[32:35], v[182:185], v[198:201], v[32:35]
	v_mfma_f32_16x16x32_bf16 v[20:23], v[168:171], v[206:209], v[20:23]
	v_mfma_f32_16x16x32_bf16 v[16:19], v[182:185], v[206:209], v[16:19]
	v_mfma_f32_16x16x32_bf16 v[4:7], v[168:171], v[214:217], v[4:7]
	v_mfma_f32_16x16x32_bf16 v[0:3], v[182:185], v[214:217], v[0:3]
	v_mfma_f32_16x16x32_bf16 v[52:55], v[176:179], v[194:197], v[52:55]
	v_mfma_f32_16x16x32_bf16 v[48:51], v[186:189], v[194:197], v[48:51]
	v_mfma_f32_16x16x32_bf16 v[36:39], v[176:179], v[202:205], v[36:39]
	v_mfma_f32_16x16x32_bf16 v[32:35], v[186:189], v[202:205], v[32:35]
	v_mfma_f32_16x16x32_bf16 v[20:23], v[176:179], v[210:213], v[20:23]
	v_mfma_f32_16x16x32_bf16 v[16:19], v[186:189], v[210:213], v[16:19]
	v_mfma_f32_16x16x32_bf16 v[4:7], v[176:179], v[218:221], v[4:7]
	v_mfma_f32_16x16x32_bf16 v[0:3], v[186:189], v[218:221], v[0:3]
	s_barrier
	s_add_i32 s71, s71, 2
	s_add_u32 s49, s49, 0x100
	s_addc_u32 s55, s55, 0
	s_cmp_gt_u32 s71, 13
	s_mov_b64 s[62:63], s[44:45]
	s_cbranch_scc0 .LBB0_1431
	s_setprio 0
	s_and_b64 vcc, exec, s[46:47]
	s_cbranch_vccz .LBB0_1434
	s_barrier

; #define PG8_STAGE(bufoff, gbase, voff) do { _Pragma("unroll") for (int _i = 0; _i < 2; ++_i) \
;         __builtin_amdgcn_global_load_lds((const unsigned*)((const char*)(gbase) + (voff)[_i]), (LAS unsigned*)(lds + (bufoff) + ldsw + _i * 8192), 16, 0, 0); } while (0)
; #define PG8_LDA(dst, b, h) do { _Pragma("unroll") for (int m = 0; m < 4; ++m) _Pragma("unroll") for (int k = 0; k < 2; ++k) dst[m][k] = *(const LAS bf16x8*)(lds + PG8_SA(b, h) + aoff + m * 2048 + k * 1024); } while (0)
; #define PG8_LDB(dst, b, h) do { _Pragma("unroll") for (int n = 0; n < 2; ++n) _Pragma("unroll") for (int k = 0; k < 2; ++k) dst[n][k] = *(const LAS bf16x8*)(lds + PG8_SB(b, h) + boff + n * 2048 + k * 1024); } while (0)
; #define PG8_MMA(ai, bj, At, Bt) do { __builtin_amdgcn_s_setprio(1); _Pragma("unroll") for (int m = 0; m < 4; ++m) _Pragma("unroll") for (int n = 0; n < 2; ++n) _Pragma("unroll") for (int k = 0; k < 2; ++k) \
;         acc[ai][bj][m][n] = __builtin_amdgcn_mfma_f32_16x16x32_bf16(Bt[n][k], At[m][k], acc[ai][bj][m][n], 0, 0, 0); __builtin_amdgcn_s_setprio(0); } while (0)
; #define PG8_WAIT_V(n) asm volatile("s_waitcnt vmcnt(" #n ")" ::: "memory")
; #define PG8_WAIT_L(n) asm volatile("s_waitcnt lgkmcnt(" #n ")" ::: "memory")
; #define PG8_BAR __builtin_amdgcn_s_barrier()
; #define PG8_SCHED __builtin_amdgcn_sched_barrier(0)
; template <class Epi, bool ALIGN_EPI>
; __device__ __forceinline__ void gemm_phase(LAS unsigned char* lds, const Gemm g, const StaticOrder S, const Epi E) {
;     ...
;             const bool last = (t == nt - 2);
;             const char* a1 = cA + (size_t)(t + 1) * kstep;
;             const char* a2 = last ? nA : cA + (size_t)(t + 2) * kstep; const char* b2 = last ? nB : cB + (size_t)(t + 2) * kstep;
;             const char* a3 = a2 + kstep; const char* b3 = b2 + kstep;
;             PG8_LDB(B0, 0, 0); PG8_LDB(B1, 0, 1); PG8_SCHED; PG8_LDA(At, 0, 0); PG8_STAGE(PG8_SA(1, 1), a1 + hstepA, voffA);
;             PG8_WAIT_V(8); PG8_WAIT_L(0); PG8_BAR; PG8_MMA(0, 0, At, B0); PG8_MMA(0, 1, At, B1); PG8_BAR; PG8_SCHED;
;     ...
; #pragma unroll
;         for (int a = 0; a < 2; ++a)
; #pragma unroll
;             for (int b = 0; b < 2; ++b)
; #pragma unroll
;                 for (int m = 0; m < 4; ++m)
; #pragma unroll
;                     for (int n = 0; n < 2; ++n) acc[a][b][m][n] = (f32x4){0.f, 0.f, 0.f, 0.f};
;         cur = nxt; cA = nA; cB = nB; ++ui;
.LBB0_1554:
	s_ashr_i32 s51, s50, 31
	s_lshl_b64 s[0:1], s[50:51], 19
	s_add_u32 s54, s94, s0
	s_addc_u32 s55, s95, s1
	s_and_b64 s[0:1], s[40:41], exec
	s_cselect_b32 s34, s55, s65
	s_cselect_b32 s35, s54, s64
	s_ashr_i32 s49, s48, 31
	s_lshl_b64 s[0:1], s[48:49], 19
	v_readlane_b32 s2, v255, 31
	s_add_u32 s62, s2, s0
	v_readlane_b32 s0, v255, 32
	s_addc_u32 s63, s0, s1
	s_and_b64 s[0:1], s[40:41], exec
	s_cselect_b32 s49, s63, s43
	s_cselect_b32 s51, s62, s42
	s_add_u32 s2, s64, 0x40080
	s_addc_u32 s3, s65, 0
	s_add_u32 s66, s42, 0x100
	v_mov_b32_e32 v0, 0
	s_addc_u32 s67, s43, 0
	s_mov_b32 s68, -2
	v_mov_b32_e32 v1, 0
	v_mov_b64_e32 v[2:3], 0
	v_mov_b64_e32 v[4:5], 0
	v_mov_b64_e32 v[6:7], 0
	v_mov_b64_e32 v[8:9], 0
	v_mov_b64_e32 v[10:11], 0
	v_mov_b64_e32 v[12:13], 0
	v_mov_b64_e32 v[14:15], 0
	v_mov_b64_e32 v[16:17], 0
	v_mov_b64_e32 v[18:19], 0
	v_mov_b64_e32 v[20:21], 0
	v_mov_b64_e32 v[22:23], 0
	v_mov_b64_e32 v[24:25], 0
	v_mov_b64_e32 v[26:27], 0
	v_mov_b64_e32 v[28:29], 0
	v_mov_b64_e32 v[30:31], 0
	v_mov_b64_e32 v[32:33], 0
	v_mov_b64_e32 v[34:35], 0
	v_mov_b64_e32 v[36:37], 0
	v_mov_b64_e32 v[38:39], 0
	v_mov_b64_e32 v[40:41], 0
	v_mov_b64_e32 v[42:43], 0
	v_mov_b64_e32 v[44:45], 0
	v_mov_b64_e32 v[46:47], 0
	v_mov_b64_e32 v[48:49], 0
	v_mov_b64_e32 v[50:51], 0
	v_mov_b64_e32 v[52:53], 0
	v_mov_b64_e32 v[54:55], 0
	v_mov_b64_e32 v[56:57], 0
	v_mov_b64_e32 v[58:59], 0
	v_mov_b64_e32 v[60:61], 0
	v_mov_b64_e32 v[62:63], 0
	v_mov_b64_e32 v[64:65], 0
	v_mov_b64_e32 v[66:67], 0
	v_mov_b64_e32 v[68:69], 0
	v_mov_b64_e32 v[70:71], 0
	v_mov_b64_e32 v[72:73], 0
	v_mov_b64_e32 v[74:75], 0
	v_mov_b64_e32 v[76:77], 0
	v_mov_b64_e32 v[78:79], 0
	v_mov_b64_e32 v[82:83], 0
	v_mov_b64_e32 v[84:85], 0
	v_mov_b64_e32 v[86:87], 0
	v_mov_b64_e32 v[88:89], 0
	v_mov_b64_e32 v[90:91], 0
	v_mov_b64_e32 v[92:93], 0
	v_mov_b64_e32 v[94:95], 0
	v_mov_b64_e32 v[96:97], 0
	v_mov_b64_e32 v[98:99], 0
	v_mov_b64_e32 v[100:101], 0
	v_mov_b64_e32 v[102:103], 0
	v_mov_b64_e32 v[104:105], 0
	v_mov_b64_e32 v[106:107], 0
	v_mov_b64_e32 v[108:109], 0
	v_mov_b64_e32 v[110:111], 0
	v_mov_b64_e32 v[112:113], 0
	v_mov_b64_e32 v[114:115], 0
	v_mov_b64_e32 v[116:117], 0
	v_mov_b64_e32 v[118:119], 0
	v_mov_b64_e32 v[120:121], 0
	v_mov_b64_e32 v[122:123], 0
	v_mov_b64_e32 v[124:125], 0
	v_mov_b64_e32 v[126:127], 0
	v_mov_b64_e32 v[128:129], 0
	v_readfirstlane_b32 s0, v167
	s_nop 3
	s_cmpk_lt_u32 s0, 0x100
	s_cbranch_scc1 .Lprio_k4
	s_setprio 1
.Lprio_k4:
.LBB0_1555:
	s_add_u32 s0, s2, 0xfffc0080
	s_addc_u32 s1, s3, -1
	s_add_i32 s12, 0, 0x10000
	s_cmp_eq_u32 s68, 12
	s_cselect_b32 s65, s34, s1
	s_cselect_b32 s64, s35, s0
	v_add_u32_e32 v130, s12, v163
	s_cselect_b32 s43, s49, s67
	s_cselect_b32 s42, s51, s66
	s_add_i32 s15, 0, 0x14000
	ds_read_b128 v[182:185], v130
	ds_read_b128 v[186:189], v130 offset:1024
	ds_read_b128 v[190:193], v130 offset:2048
	ds_read_b128 v[194:197], v130 offset:3072
	v_add_u32_e32 v130, s15, v163
	ds_read_b128 v[198:201], v130
	ds_read_b128 v[202:205], v130 offset:1024
	ds_read_b128 v[206:209], v130 offset:2048
	ds_read_b128 v[210:213], v130 offset:3072
	v_lshl_add_u64 v[172:173], s[2:3], 0, v[152:153]
	s_add_i32 m0, s24, 0xc000
	ds_read_b128 v[214:217], v165
	ds_read_b128 v[218:221], v165 offset:1024
	ds_read_b128 v[222:225], v165 offset:2048
	ds_read_b128 v[226:229], v165 offset:3072
	ds_read_b128 v[230:233], v165 offset:4096
	ds_read_b128 v[234:237], v165 offset:5120
	ds_read_b128 v[238:241], v165 offset:6144
	ds_read_b128 v[242:245], v165 offset:7168
	global_load_lds_dwordx4 v[172:173], off
	v_lshl_add_u64 v[172:173], s[2:3], 0, v[154:155]
	s_add_i32 m0, s24, 0xe000
	s_nop 0
	global_load_lds_dwordx4 v[172:173], off
	s_waitcnt vmcnt(8)
	s_waitcnt lgkmcnt(0)
	s_barrier
	s_waitcnt lgkmcnt(0)
	v_mfma_f32_16x16x32_bf16 v[126:129], v[182:185], v[214:217], v[126:129]
	v_mfma_f32_16x16x32_bf16 v[122:125], v[190:193], v[214:217], v[122:125]
	v_mfma_f32_16x16x32_bf16 v[114:117], v[182:185], v[222:225], v[114:117]
	v_mfma_f32_16x16x32_bf16 v[106:109], v[190:193], v[222:225], v[106:109]
	v_mfma_f32_16x16x32_bf16 v[98:101], v[182:185], v[230:233], v[98:101]
	v_mfma_f32_16x16x32_bf16 v[90:93], v[190:193], v[230:233], v[90:93]
	v_mfma_f32_16x16x32_bf16 v[82:85], v[182:185], v[238:241], v[82:85]
	v_mfma_f32_16x16x32_bf16 v[72:75], v[190:193], v[238:241], v[72:75]
	v_mfma_f32_16x16x32_bf16 v[126:129], v[186:189], v[218:221], v[126:129]
	v_mfma_f32_16x16x32_bf16 v[122:125], v[194:197], v[218:221], v[122:125]
	v_mfma_f32_16x16x32_bf16 v[114:117], v[186:189], v[226:229], v[114:117]
	v_mfma_f32_16x16x32_bf16 v[106:109], v[194:197], v[226:229], v[106:109]
	v_mfma_f32_16x16x32_bf16 v[98:101], v[186:189], v[234:237], v[98:101]
	v_mfma_f32_16x16x32_bf16 v[90:93], v[194:197], v[234:237], v[90:93]
	v_mfma_f32_16x16x32_bf16 v[82:85], v[186:189], v[242:245], v[82:85]
	v_mfma_f32_16x16x32_bf16 v[72:75], v[194:197], v[242:245], v[72:75]
	v_mfma_f32_16x16x32_bf16 v[118:121], v[198:201], v[214:217], v[118:121]
	v_mfma_f32_16x16x32_bf16 v[110:113], v[206:209], v[214:217], v[110:113]
	v_mfma_f32_16x16x32_bf16 v[102:105], v[198:201], v[222:225], v[102:105]
	v_mfma_f32_16x16x32_bf16 v[94:97], v[206:209], v[222:225], v[94:97]
	v_mfma_f32_16x16x32_bf16 v[86:89], v[198:201], v[230:233], v[86:89]
	v_mfma_f32_16x16x32_bf16 v[76:79], v[206:209], v[230:233], v[76:79]
	v_mfma_f32_16x16x32_bf16 v[68:71], v[198:201], v[238:241], v[68:71]
	v_mfma_f32_16x16x32_bf16 v[64:67], v[206:209], v[238:241], v[64:67]
	v_mfma_f32_16x16x32_bf16 v[118:121], v[202:205], v[218:221], v[118:121]
	v_mfma_f32_16x16x32_bf16 v[110:113], v[210:213], v[218:221], v[110:113]
	v_mfma_f32_16x16x32_bf16 v[102:105], v[202:205], v[226:229], v[102:105]
	v_mfma_f32_16x16x32_bf16 v[94:97], v[210:213], v[226:229], v[94:97]
	v_mfma_f32_16x16x32_bf16 v[86:89], v[202:205], v[234:237], v[86:89]
	v_mfma_f32_16x16x32_bf16 v[76:79], v[210:213], v[234:237], v[76:79]
	v_mfma_f32_16x16x32_bf16 v[68:71], v[202:205], v[242:245], v[68:71]
	v_mfma_f32_16x16x32_bf16 v[64:67], v[210:213], v[242:245], v[64:67]
	s_barrier
; #define PG8_STAGE(bufoff, gbase, voff) do { _Pragma("unroll") for (int _i = 0; _i < 2; ++_i) \
;         __builtin_amdgcn_global_load_lds((const unsigned*)((const char*)(gbase) + (voff)[_i]), (LAS unsigned*)(lds + (bufoff) + ldsw + _i * 8192), 16, 0, 0); } while (0)
; #define PG8_LDA(dst, b, h) do { _Pragma("unroll") for (int m = 0; m < 4; ++m) _Pragma("unroll") for (int k = 0; k < 2; ++k) dst[m][k] = *(const LAS bf16x8*)(lds + PG8_SA(b, h) + aoff + m * 2048 + k * 1024); } while (0)
; #define PG8_LDB(dst, b, h) do { _Pragma("unroll") for (int n = 0; n < 2; ++n) _Pragma("unroll") for (int k = 0; k < 2; ++k) dst[n][k] = *(const LAS bf16x8*)(lds + PG8_SB(b, h) + boff + n * 2048 + k * 1024); } while (0)
; #define PG8_MMA(ai, bj, At, Bt) do { __builtin_amdgcn_s_setprio(1); _Pragma("unroll") for (int m = 0; m < 4; ++m) _Pragma("unroll") for (int n = 0; n < 2; ++n) _Pragma("unroll") for (int k = 0; k < 2; ++k) \
;         acc[ai][bj][m][n] = __builtin_amdgcn_mfma_f32_16x16x32_bf16(Bt[n][k], At[m][k], acc[ai][bj][m][n], 0, 0, 0); __builtin_amdgcn_s_setprio(0); } while (0)
; #define PG8_WAIT_V(n) asm volatile("s_waitcnt vmcnt(" #n ")" ::: "memory")
; #define PG8_WAIT_L(n) asm volatile("s_waitcnt lgkmcnt(" #n ")" ::: "memory")
; #define PG8_BAR __builtin_amdgcn_s_barrier()
; #define PG8_SCHED __builtin_amdgcn_sched_barrier(0)
; template <class Epi, bool ALIGN_EPI>
; __device__ __forceinline__ void gemm_phase(LAS unsigned char* lds, const Gemm g, const StaticOrder S, const Epi E) {
;     ...
;             PG8_LDA(At, 0, 1); PG8_STAGE(PG8_SB(0, 0), b2, voffB); PG8_STAGE(PG8_SB(0, 1), b2 + hstepB, voffB); PG8_STAGE(PG8_SA(0, 0), a2, voffA);
;             PG8_WAIT_V(8); PG8_WAIT_L(0); PG8_BAR; PG8_MMA(1, 0, At, B0); PG8_MMA(1, 1, At, B1); PG8_BAR; PG8_SCHED;
;             PG8_LDB(B0, 1, 0); PG8_LDB(B1, 1, 1); PG8_SCHED; PG8_LDA(At, 1, 0); PG8_STAGE(PG8_SA(0, 1), a2 + hstepA, voffA);
;             PG8_WAIT_V(8); PG8_WAIT_L(0); PG8_BAR; PG8_MMA(0, 0, At, B0); PG8_MMA(0, 1, At, B1); PG8_BAR; PG8_SCHED;
	s_add_i32 s0, s12, s23
	v_lshl_add_u64 v[172:173], s[42:43], 0, v[80:81]
	s_mov_b32 m0, s0
	ds_read_b128 v[214:217], v165 offset:16384
	ds_read_b128 v[218:221], v165 offset:17408
	ds_read_b128 v[222:225], v165 offset:18432
	ds_read_b128 v[226:229], v165 offset:19456
	ds_read_b128 v[230:233], v165 offset:20480
	ds_read_b128 v[234:237], v165 offset:21504
	ds_read_b128 v[238:241], v165 offset:22528
	ds_read_b128 v[242:245], v165 offset:23552
	global_load_lds_dwordx4 v[172:173], off
	s_add_i32 m0, s0, 0x2000
	s_add_u32 s0, s42, 0x40000
	v_lshl_add_u64 v[176:177], s[42:43], 0, v[136:137]
	s_addc_u32 s1, s43, 0
	s_add_i32 s12, s15, s23
	global_load_lds_dwordx4 v[176:177], off
	v_lshl_add_u64 v[178:179], s[0:1], 0, v[80:81]
	s_mov_b32 m0, s12
	v_lshl_add_u64 v[246:247], s[64:65], 0, v[138:139]
	global_load_lds_dwordx4 v[178:179], off
	v_lshl_add_u64 v[178:179], s[0:1], 0, v[136:137]
	s_add_i32 m0, s12, 0x2000
	s_nop 0
	global_load_lds_dwordx4 v[178:179], off
	v_lshl_add_u64 v[178:179], s[64:65], 0, v[140:141]
	s_mov_b32 m0, s24
	s_nop 0
	global_load_lds_dwordx4 v[178:179], off
	s_mov_b32 m0, s25
	s_nop 0
	global_load_lds_dwordx4 v[246:247], off
	s_waitcnt vmcnt(8)
	s_waitcnt lgkmcnt(0)
	s_barrier
	s_waitcnt lgkmcnt(0)
	v_mfma_f32_16x16x32_bf16 v[60:63], v[182:185], v[214:217], v[60:63]
	v_mfma_f32_16x16x32_bf16 v[56:59], v[190:193], v[214:217], v[56:59]
	v_mfma_f32_16x16x32_bf16 v[48:51], v[182:185], v[222:225], v[48:51]
	v_mfma_f32_16x16x32_bf16 v[40:43], v[190:193], v[222:225], v[40:43]
	v_mfma_f32_16x16x32_bf16 v[32:35], v[182:185], v[230:233], v[32:35]
	v_mfma_f32_16x16x32_bf16 v[24:27], v[190:193], v[230:233], v[24:27]
	v_mfma_f32_16x16x32_bf16 v[16:19], v[182:185], v[238:241], v[16:19]
	v_mfma_f32_16x16x32_bf16 v[8:11], v[190:193], v[238:241], v[8:11]
	v_mfma_f32_16x16x32_bf16 v[60:63], v[186:189], v[218:221], v[60:63]
	v_mfma_f32_16x16x32_bf16 v[56:59], v[194:197], v[218:221], v[56:59]
	v_mfma_f32_16x16x32_bf16 v[48:51], v[186:189], v[226:229], v[48:51]
	v_mfma_f32_16x16x32_bf16 v[40:43], v[194:197], v[226:229], v[40:43]
	v_mfma_f32_16x16x32_bf16 v[32:35], v[186:189], v[234:237], v[32:35]
	v_mfma_f32_16x16x32_bf16 v[24:27], v[194:197], v[234:237], v[24:27]
	v_mfma_f32_16x16x32_bf16 v[16:19], v[186:189], v[242:245], v[16:19]
	v_mfma_f32_16x16x32_bf16 v[8:11], v[194:197], v[242:245], v[8:11]
	v_mfma_f32_16x16x32_bf16 v[52:55], v[198:201], v[214:217], v[52:55]
	v_mfma_f32_16x16x32_bf16 v[44:47], v[206:209], v[214:217], v[44:47]
	v_mfma_f32_16x16x32_bf16 v[36:39], v[198:201], v[222:225], v[36:39]
	v_mfma_f32_16x16x32_bf16 v[28:31], v[206:209], v[222:225], v[28:31]
	v_mfma_f32_16x16x32_bf16 v[20:23], v[198:201], v[230:233], v[20:23]
	v_mfma_f32_16x16x32_bf16 v[12:15], v[206:209], v[230:233], v[12:15]
	v_mfma_f32_16x16x32_bf16 v[4:7], v[198:201], v[238:241], v[4:7]
	v_mfma_f32_16x16x32_bf16 v[0:3], v[206:209], v[238:241], v[0:3]
	v_mfma_f32_16x16x32_bf16 v[52:55], v[202:205], v[218:221], v[52:55]
	v_mfma_f32_16x16x32_bf16 v[44:47], v[210:213], v[218:221], v[44:47]
	v_mfma_f32_16x16x32_bf16 v[36:39], v[202:205], v[226:229], v[36:39]
	v_mfma_f32_16x16x32_bf16 v[28:31], v[210:213], v[226:229], v[28:31]
	v_mfma_f32_16x16x32_bf16 v[20:23], v[202:205], v[234:237], v[20:23]
	v_mfma_f32_16x16x32_bf16 v[12:15], v[210:213], v[234:237], v[12:15]
	v_mfma_f32_16x16x32_bf16 v[4:7], v[202:205], v[242:245], v[4:7]
	v_mfma_f32_16x16x32_bf16 v[0:3], v[210:213], v[242:245], v[0:3]
	s_barrier
	s_add_i32 s12, 0, 0x18000
	v_add_u32_e32 v130, s12, v163
	s_add_i32 s15, 0, 0x1c000
	ds_read_b128 v[182:185], v130
	ds_read_b128 v[186:189], v130 offset:1024
	ds_read_b128 v[190:193], v130 offset:2048
	ds_read_b128 v[194:197], v130 offset:3072
	v_add_u32_e32 v130, s15, v163
	ds_read_b128 v[198:201], v130
	ds_read_b128 v[202:205], v130 offset:1024
	ds_read_b128 v[206:209], v130 offset:2048
	ds_read_b128 v[210:213], v130 offset:3072
	s_add_u32 s0, s64, 0x40000
	s_addc_u32 s1, s65, 0
	s_mov_b32 m0, s26
	v_lshl_add_u64 v[248:249], s[0:1], 0, v[140:141]
	ds_read_b128 v[214:217], v165 offset:32768
	ds_read_b128 v[218:221], v165 offset:33792
	ds_read_b128 v[222:225], v165 offset:34816
	ds_read_b128 v[226:229], v165 offset:35840
	ds_read_b128 v[230:233], v165 offset:36864
	ds_read_b128 v[234:237], v165 offset:37888
	ds_read_b128 v[238:241], v165 offset:38912
	ds_read_b128 v[242:245], v165 offset:39936
	global_load_lds_dwordx4 v[248:249], off
	v_lshl_add_u64 v[248:249], s[0:1], 0, v[138:139]
	s_mov_b32 m0, s27
	s_nop 0
	global_load_lds_dwordx4 v[248:249], off
	s_waitcnt vmcnt(8)
	s_waitcnt lgkmcnt(0)
	s_barrier
; #define PG8_STAGE(bufoff, gbase, voff) do { _Pragma("unroll") for (int _i = 0; _i < 2; ++_i) \
;         __builtin_amdgcn_global_load_lds((const unsigned*)((const char*)(gbase) + (voff)[_i]), (LAS unsigned*)(lds + (bufoff) + ldsw + _i * 8192), 16, 0, 0); } while (0)
; #define PG8_LDA(dst, b, h) do { _Pragma("unroll") for (int m = 0; m < 4; ++m) _Pragma("unroll") for (int k = 0; k < 2; ++k) dst[m][k] = *(const LAS bf16x8*)(lds + PG8_SA(b, h) + aoff + m * 2048 + k * 1024); } while (0)
; #define PG8_MMA(ai, bj, At, Bt) do { __builtin_amdgcn_s_setprio(1); _Pragma("unroll") for (int m = 0; m < 4; ++m) _Pragma("unroll") for (int n = 0; n < 2; ++n) _Pragma("unroll") for (int k = 0; k < 2; ++k) \
;         acc[ai][bj][m][n] = __builtin_amdgcn_mfma_f32_16x16x32_bf16(Bt[n][k], At[m][k], acc[ai][bj][m][n], 0, 0, 0); __builtin_amdgcn_s_setprio(0); } while (0)
; #define PG8_WAIT_V(n) asm volatile("s_waitcnt vmcnt(" #n ")" ::: "memory")
; #define PG8_WAIT_L(n) asm volatile("s_waitcnt lgkmcnt(" #n ")" ::: "memory")
; #define PG8_BAR __builtin_amdgcn_s_barrier()
; #define PG8_SCHED __builtin_amdgcn_sched_barrier(0)
; template <class Epi, bool ALIGN_EPI>
; __device__ __forceinline__ void gemm_phase(LAS unsigned char* lds, const Gemm g, const StaticOrder S, const Epi E) {
;     ...
;             PG8_WAIT_V(8); PG8_WAIT_L(0); PG8_BAR; PG8_MMA(0, 0, At, B0); PG8_MMA(0, 1, At, B1); PG8_BAR; PG8_SCHED;
;             PG8_LDA(At, 1, 1); PG8_STAGE(PG8_SB(1, 0), b3, voffB); PG8_STAGE(PG8_SB(1, 1), b3 + hstepB, voffB); PG8_STAGE(PG8_SA(1, 0), a3, voffA);
;             PG8_WAIT_V(8); PG8_WAIT_L(0); PG8_BAR; PG8_MMA(1, 0, At, B0); PG8_MMA(1, 1, At, B1); PG8_BAR; PG8_SCHED;
;         }
;         if constexpr (ALIGN_EPI) { if (wr == 0) PG8_BAR; }
	s_waitcnt lgkmcnt(0)
	v_mfma_f32_16x16x32_bf16 v[126:129], v[182:185], v[214:217], v[126:129]
	v_mfma_f32_16x16x32_bf16 v[122:125], v[190:193], v[214:217], v[122:125]
	v_mfma_f32_16x16x32_bf16 v[114:117], v[182:185], v[222:225], v[114:117]
	v_mfma_f32_16x16x32_bf16 v[106:109], v[190:193], v[222:225], v[106:109]
	v_mfma_f32_16x16x32_bf16 v[98:101], v[182:185], v[230:233], v[98:101]
	v_mfma_f32_16x16x32_bf16 v[90:93], v[190:193], v[230:233], v[90:93]
	v_mfma_f32_16x16x32_bf16 v[82:85], v[182:185], v[238:241], v[82:85]
	v_mfma_f32_16x16x32_bf16 v[72:75], v[190:193], v[238:241], v[72:75]
	v_mfma_f32_16x16x32_bf16 v[126:129], v[186:189], v[218:221], v[126:129]
	v_mfma_f32_16x16x32_bf16 v[122:125], v[194:197], v[218:221], v[122:125]
	v_mfma_f32_16x16x32_bf16 v[114:117], v[186:189], v[226:229], v[114:117]
	v_mfma_f32_16x16x32_bf16 v[106:109], v[194:197], v[226:229], v[106:109]
	v_mfma_f32_16x16x32_bf16 v[98:101], v[186:189], v[234:237], v[98:101]
	v_mfma_f32_16x16x32_bf16 v[90:93], v[194:197], v[234:237], v[90:93]
	v_mfma_f32_16x16x32_bf16 v[82:85], v[186:189], v[242:245], v[82:85]
	v_mfma_f32_16x16x32_bf16 v[72:75], v[194:197], v[242:245], v[72:75]
	v_mfma_f32_16x16x32_bf16 v[118:121], v[198:201], v[214:217], v[118:121]
	v_mfma_f32_16x16x32_bf16 v[110:113], v[206:209], v[214:217], v[110:113]
	v_mfma_f32_16x16x32_bf16 v[102:105], v[198:201], v[222:225], v[102:105]
	v_mfma_f32_16x16x32_bf16 v[94:97], v[206:209], v[222:225], v[94:97]
	v_mfma_f32_16x16x32_bf16 v[86:89], v[198:201], v[230:233], v[86:89]
	v_mfma_f32_16x16x32_bf16 v[76:79], v[206:209], v[230:233], v[76:79]
	v_mfma_f32_16x16x32_bf16 v[68:71], v[198:201], v[238:241], v[68:71]
	v_mfma_f32_16x16x32_bf16 v[64:67], v[206:209], v[238:241], v[64:67]
	v_mfma_f32_16x16x32_bf16 v[118:121], v[202:205], v[218:221], v[118:121]
	v_mfma_f32_16x16x32_bf16 v[110:113], v[210:213], v[218:221], v[110:113]
	v_mfma_f32_16x16x32_bf16 v[102:105], v[202:205], v[226:229], v[102:105]
	v_mfma_f32_16x16x32_bf16 v[94:97], v[210:213], v[226:229], v[94:97]
	v_mfma_f32_16x16x32_bf16 v[86:89], v[202:205], v[234:237], v[86:89]
	v_mfma_f32_16x16x32_bf16 v[76:79], v[210:213], v[234:237], v[76:79]
	v_mfma_f32_16x16x32_bf16 v[68:71], v[202:205], v[242:245], v[68:71]
	v_mfma_f32_16x16x32_bf16 v[64:67], v[210:213], v[242:245], v[64:67]
	s_barrier
	s_add_i32 s0, s12, s23
	v_lshl_add_u64 v[172:173], v[172:173], 0, s[80:81]
	s_mov_b32 m0, s0
	ds_read_b128 v[214:217], v165 offset:49152
	ds_read_b128 v[218:221], v165 offset:50176
	ds_read_b128 v[222:225], v165 offset:51200
	ds_read_b128 v[226:229], v165 offset:52224
	ds_read_b128 v[230:233], v165 offset:53248
	ds_read_b128 v[234:237], v165 offset:54272
	ds_read_b128 v[238:241], v165 offset:55296
	ds_read_b128 v[242:245], v165 offset:56320
	global_load_lds_dwordx4 v[172:173], off
	s_add_i32 m0, s0, 0x2000
	s_add_u32 s0, s42, 0x40080
	v_lshl_add_u64 v[172:173], v[176:177], 0, s[80:81]
	s_addc_u32 s1, s43, 0
	s_add_i32 s12, s15, s23
	global_load_lds_dwordx4 v[172:173], off
	v_lshl_add_u64 v[172:173], s[0:1], 0, v[80:81]
	s_mov_b32 m0, s12
	s_nop 0
	global_load_lds_dwordx4 v[172:173], off
	v_lshl_add_u64 v[172:173], s[0:1], 0, v[136:137]
	s_add_i32 m0, s12, 0x2000
	s_nop 0
	global_load_lds_dwordx4 v[172:173], off
	v_lshl_add_u64 v[172:173], v[178:179], 0, s[80:81]
	s_mov_b32 m0, s29
	s_nop 0
	global_load_lds_dwordx4 v[172:173], off
	v_lshl_add_u64 v[172:173], v[246:247], 0, s[80:81]
	s_mov_b32 m0, s30
	s_nop 0
	global_load_lds_dwordx4 v[172:173], off
	s_waitcnt vmcnt(8)
	s_waitcnt lgkmcnt(0)
	s_barrier
	s_waitcnt lgkmcnt(0)
	v_mfma_f32_16x16x32_bf16 v[60:63], v[182:185], v[214:217], v[60:63]
	v_mfma_f32_16x16x32_bf16 v[56:59], v[190:193], v[214:217], v[56:59]
	v_mfma_f32_16x16x32_bf16 v[48:51], v[182:185], v[222:225], v[48:51]
	v_mfma_f32_16x16x32_bf16 v[40:43], v[190:193], v[222:225], v[40:43]
	v_mfma_f32_16x16x32_bf16 v[32:35], v[182:185], v[230:233], v[32:35]
	v_mfma_f32_16x16x32_bf16 v[24:27], v[190:193], v[230:233], v[24:27]
	v_mfma_f32_16x16x32_bf16 v[16:19], v[182:185], v[238:241], v[16:19]
	v_mfma_f32_16x16x32_bf16 v[8:11], v[190:193], v[238:241], v[8:11]
	v_mfma_f32_16x16x32_bf16 v[60:63], v[186:189], v[218:221], v[60:63]
	v_mfma_f32_16x16x32_bf16 v[56:59], v[194:197], v[218:221], v[56:59]
	v_mfma_f32_16x16x32_bf16 v[48:51], v[186:189], v[226:229], v[48:51]
	v_mfma_f32_16x16x32_bf16 v[40:43], v[194:197], v[226:229], v[40:43]
	v_mfma_f32_16x16x32_bf16 v[32:35], v[186:189], v[234:237], v[32:35]
	v_mfma_f32_16x16x32_bf16 v[24:27], v[194:197], v[234:237], v[24:27]
	v_mfma_f32_16x16x32_bf16 v[16:19], v[186:189], v[242:245], v[16:19]
	v_mfma_f32_16x16x32_bf16 v[8:11], v[194:197], v[242:245], v[8:11]
	v_mfma_f32_16x16x32_bf16 v[52:55], v[198:201], v[214:217], v[52:55]
	v_mfma_f32_16x16x32_bf16 v[44:47], v[206:209], v[214:217], v[44:47]
	v_mfma_f32_16x16x32_bf16 v[36:39], v[198:201], v[222:225], v[36:39]
	v_mfma_f32_16x16x32_bf16 v[28:31], v[206:209], v[222:225], v[28:31]
	v_mfma_f32_16x16x32_bf16 v[20:23], v[198:201], v[230:233], v[20:23]
	v_mfma_f32_16x16x32_bf16 v[12:15], v[206:209], v[230:233], v[12:15]
	v_mfma_f32_16x16x32_bf16 v[4:7], v[198:201], v[238:241], v[4:7]
	v_mfma_f32_16x16x32_bf16 v[0:3], v[206:209], v[238:241], v[0:3]
	v_mfma_f32_16x16x32_bf16 v[52:55], v[202:205], v[218:221], v[52:55]
	v_mfma_f32_16x16x32_bf16 v[44:47], v[210:213], v[218:221], v[44:47]
	v_mfma_f32_16x16x32_bf16 v[36:39], v[202:205], v[226:229], v[36:39]
	v_mfma_f32_16x16x32_bf16 v[28:31], v[210:213], v[226:229], v[28:31]
	v_mfma_f32_16x16x32_bf16 v[20:23], v[202:205], v[234:237], v[20:23]
	v_mfma_f32_16x16x32_bf16 v[12:15], v[210:213], v[234:237], v[12:15]
	v_mfma_f32_16x16x32_bf16 v[4:7], v[202:205], v[242:245], v[4:7]
	v_mfma_f32_16x16x32_bf16 v[0:3], v[210:213], v[242:245], v[0:3]
	s_barrier
	s_add_i32 s68, s68, 2
	s_add_u32 s2, s2, 0x100
	s_addc_u32 s3, s3, 0
	s_add_u32 s66, s66, 0x100
	s_addc_u32 s67, s67, 0
	s_cmp_gt_u32 s68, 13
	s_cbranch_scc0 .LBB0_1555
	s_setprio 0
	s_and_b64 vcc, exec, s[46:47]
	s_cbranch_vccz .LBB0_1558
	s_barrier

; #define PG8_STAGE(bufoff, gbase, voff) do { _Pragma("unroll") for (int _i = 0; _i < 2; ++_i) \
;         __builtin_amdgcn_global_load_lds((const unsigned*)((const char*)(gbase) + (voff)[_i]), (LAS unsigned*)(lds + (bufoff) + ldsw + _i * 8192), 16, 0, 0); } while (0)
; #define PG8_LDA(dst, b, h) do { _Pragma("unroll") for (int m = 0; m < 4; ++m) _Pragma("unroll") for (int k = 0; k < 2; ++k) dst[m][k] = *(const LAS bf16x8*)(lds + PG8_SA(b, h) + aoff + m * 2048 + k * 1024); } while (0)
; #define PG8_LDB(dst, b, h) do { _Pragma("unroll") for (int n = 0; n < 2; ++n) _Pragma("unroll") for (int k = 0; k < 2; ++k) dst[n][k] = *(const LAS bf16x8*)(lds + PG8_SB(b, h) + boff + n * 2048 + k * 1024); } while (0)
; #define PG8_MMA(ai, bj, At, Bt) do { __builtin_amdgcn_s_setprio(1); _Pragma("unroll") for (int m = 0; m < 4; ++m) _Pragma("unroll") for (int n = 0; n < 2; ++n) _Pragma("unroll") for (int k = 0; k < 2; ++k) \
;         acc[ai][bj][m][n] = __builtin_amdgcn_mfma_f32_16x16x32_bf16(Bt[n][k], At[m][k], acc[ai][bj][m][n], 0, 0, 0); __builtin_amdgcn_s_setprio(0); } while (0)
; #define PG8_WAIT_V(n) asm volatile("s_waitcnt vmcnt(" #n ")" ::: "memory")
; #define PG8_WAIT_L(n) asm volatile("s_waitcnt lgkmcnt(" #n ")" ::: "memory")
; #define PG8_BAR __builtin_amdgcn_s_barrier()
; #define PG8_SCHED __builtin_amdgcn_sched_barrier(0)
; template <class Epi, bool ALIGN_EPI>
; __device__ __forceinline__ void gemm_phase(LAS unsigned char* lds, const Gemm g, const StaticOrder S, const Epi E) {
;     ...
;             const bool last = (t == nt - 2);
;             const char* a1 = cA + (size_t)(t + 1) * kstep;
;             const char* a2 = last ? nA : cA + (size_t)(t + 2) * kstep; const char* b2 = last ? nB : cB + (size_t)(t + 2) * kstep;
;             const char* a3 = a2 + kstep; const char* b3 = b2 + kstep;
;             PG8_LDB(B0, 0, 0); PG8_LDB(B1, 0, 1); PG8_SCHED; PG8_LDA(At, 0, 0); PG8_STAGE(PG8_SA(1, 1), a1 + hstepA, voffA);
;             PG8_WAIT_V(8); PG8_WAIT_L(0); PG8_BAR; PG8_MMA(0, 0, At, B0); PG8_MMA(0, 1, At, B1); PG8_BAR; PG8_SCHED;
;     ...
; #pragma unroll
;         for (int a = 0; a < 2; ++a)
; #pragma unroll
;             for (int b = 0; b < 2; ++b)
; #pragma unroll
;                 for (int m = 0; m < 4; ++m)
; #pragma unroll
;                     for (int n = 0; n < 2; ++n) acc[a][b][m][n] = (f32x4){0.f, 0.f, 0.f, 0.f};
;         cur = nxt; cA = nA; cB = nB; ++ui;
.LBB0_1756:
	s_add_u32 s26, s50, 0x100
	v_mov_b32_e32 v0, 0
	s_addc_u32 s27, s51, 0
	s_mov_b32 s28, -2
	v_mov_b32_e32 v1, 0
	v_mov_b64_e32 v[2:3], 0
	v_mov_b64_e32 v[4:5], 0
	v_mov_b64_e32 v[6:7], 0
	v_mov_b64_e32 v[8:9], 0
	v_mov_b64_e32 v[10:11], 0
	v_mov_b64_e32 v[12:13], 0
	v_mov_b64_e32 v[14:15], 0
	v_mov_b64_e32 v[16:17], 0
	v_mov_b64_e32 v[18:19], 0
	v_mov_b64_e32 v[20:21], 0
	v_mov_b64_e32 v[22:23], 0
	v_mov_b64_e32 v[24:25], 0
	v_mov_b64_e32 v[26:27], 0
	v_mov_b64_e32 v[28:29], 0
	v_mov_b64_e32 v[30:31], 0
	v_mov_b64_e32 v[32:33], 0
	v_mov_b64_e32 v[34:35], 0
	v_mov_b64_e32 v[36:37], 0
	v_mov_b64_e32 v[38:39], 0
	v_mov_b64_e32 v[40:41], 0
	v_mov_b64_e32 v[42:43], 0
	v_mov_b64_e32 v[44:45], 0
	v_mov_b64_e32 v[46:47], 0
	v_mov_b64_e32 v[48:49], 0
	v_mov_b64_e32 v[50:51], 0
	v_mov_b64_e32 v[52:53], 0
	v_mov_b64_e32 v[54:55], 0
	v_mov_b64_e32 v[56:57], 0
	v_mov_b64_e32 v[58:59], 0
	v_mov_b64_e32 v[60:61], 0
	v_mov_b64_e32 v[62:63], 0
	v_mov_b64_e32 v[64:65], 0
	v_mov_b64_e32 v[66:67], 0
	v_mov_b64_e32 v[68:69], 0
	v_mov_b64_e32 v[70:71], 0
	v_mov_b64_e32 v[72:73], 0
	v_mov_b64_e32 v[74:75], 0
	v_mov_b64_e32 v[76:77], 0
	v_mov_b64_e32 v[78:79], 0
	v_mov_b64_e32 v[82:83], 0
	v_mov_b64_e32 v[84:85], 0
	v_mov_b64_e32 v[86:87], 0
	v_mov_b64_e32 v[88:89], 0
	v_mov_b64_e32 v[90:91], 0
	v_mov_b64_e32 v[92:93], 0
	v_mov_b64_e32 v[94:95], 0
	v_mov_b64_e32 v[96:97], 0
	v_mov_b64_e32 v[98:99], 0
	v_mov_b64_e32 v[100:101], 0
	v_mov_b64_e32 v[102:103], 0
	v_mov_b64_e32 v[104:105], 0
	v_mov_b64_e32 v[106:107], 0
	v_mov_b64_e32 v[108:109], 0
	v_mov_b64_e32 v[110:111], 0
	v_mov_b64_e32 v[112:113], 0
	v_mov_b64_e32 v[114:115], 0
	v_mov_b64_e32 v[116:117], 0
	v_mov_b64_e32 v[118:119], 0
	v_mov_b64_e32 v[120:121], 0
	v_mov_b64_e32 v[122:123], 0
	v_mov_b64_e32 v[124:125], 0
	v_mov_b64_e32 v[126:127], 0
	v_mov_b64_e32 v[128:129], 0
	v_readfirstlane_b32 s0, v167
	s_nop 3
	s_cmpk_lt_u32 s0, 0x100
	s_cbranch_scc1 .Lprio_k5
	s_setprio 1
.Lprio_k5:
.LBB0_1757:
	s_add_u32 s50, s48, 0x100
	s_addc_u32 s51, s49, 0
	s_add_i32 s0, 0, 0x10000
	s_cmp_eq_u32 s28, 2
	s_cselect_b32 s55, s43, s51
	s_cselect_b32 s54, s42, s50
	v_add_u32_e32 v80, s0, v156
	s_cselect_b32 s53, s47, s27
	s_cselect_b32 s52, s46, s26
	s_add_i32 s12, 0, 0x14000
	ds_read_b128 v[148:151], v80
	ds_read_b128 v[158:161], v80 offset:1024
	ds_read_b128 v[162:165], v80 offset:2048
	ds_read_b128 v[182:185], v80 offset:3072
	v_add_u32_e32 v80, s12, v156
	ds_read_b128 v[186:189], v80
	ds_read_b128 v[190:193], v80 offset:1024
	ds_read_b128 v[194:197], v80 offset:2048
	ds_read_b128 v[198:201], v80 offset:3072
	v_lshl_add_u64 v[152:153], s[48:49], 0, v[144:145]
	s_add_i32 m0, s62, 0xc000
	ds_read_b128 v[202:205], v157
	ds_read_b128 v[206:209], v157 offset:1024
	ds_read_b128 v[210:213], v157 offset:2048
	ds_read_b128 v[214:217], v157 offset:3072
	ds_read_b128 v[218:221], v157 offset:4096
	ds_read_b128 v[222:225], v157 offset:5120
	ds_read_b128 v[226:229], v157 offset:6144
	ds_read_b128 v[230:233], v157 offset:7168
	global_load_lds_dwordx4 v[152:153], off
	v_lshl_add_u64 v[152:153], s[48:49], 0, v[146:147]
	s_add_i32 m0, s62, 0xe000
	s_nop 0
	global_load_lds_dwordx4 v[152:153], off
	s_waitcnt vmcnt(8)
	s_waitcnt lgkmcnt(0)
	s_barrier
	s_waitcnt lgkmcnt(0)
	v_mfma_f32_16x16x32_bf16 v[126:129], v[148:151], v[202:205], v[126:129]
	v_mfma_f32_16x16x32_bf16 v[122:125], v[162:165], v[202:205], v[122:125]
	v_mfma_f32_16x16x32_bf16 v[118:121], v[148:151], v[210:213], v[118:121]
	v_mfma_f32_16x16x32_bf16 v[114:117], v[162:165], v[210:213], v[114:117]
	v_mfma_f32_16x16x32_bf16 v[110:113], v[148:151], v[218:221], v[110:113]
	v_mfma_f32_16x16x32_bf16 v[106:109], v[162:165], v[218:221], v[106:109]
	v_mfma_f32_16x16x32_bf16 v[102:105], v[148:151], v[226:229], v[102:105]
	v_mfma_f32_16x16x32_bf16 v[98:101], v[162:165], v[226:229], v[98:101]
	v_mfma_f32_16x16x32_bf16 v[126:129], v[158:161], v[206:209], v[126:129]
	v_mfma_f32_16x16x32_bf16 v[122:125], v[182:185], v[206:209], v[122:125]
	v_mfma_f32_16x16x32_bf16 v[118:121], v[158:161], v[214:217], v[118:121]
	v_mfma_f32_16x16x32_bf16 v[114:117], v[182:185], v[214:217], v[114:117]
	v_mfma_f32_16x16x32_bf16 v[110:113], v[158:161], v[222:225], v[110:113]
	v_mfma_f32_16x16x32_bf16 v[106:109], v[182:185], v[222:225], v[106:109]
	v_mfma_f32_16x16x32_bf16 v[102:105], v[158:161], v[230:233], v[102:105]
	v_mfma_f32_16x16x32_bf16 v[98:101], v[182:185], v[230:233], v[98:101]
	v_mfma_f32_16x16x32_bf16 v[60:63], v[186:189], v[202:205], v[60:63]
	v_mfma_f32_16x16x32_bf16 v[56:59], v[194:197], v[202:205], v[56:59]
	v_mfma_f32_16x16x32_bf16 v[52:55], v[186:189], v[210:213], v[52:55]
	v_mfma_f32_16x16x32_bf16 v[48:51], v[194:197], v[210:213], v[48:51]
	v_mfma_f32_16x16x32_bf16 v[44:47], v[186:189], v[218:221], v[44:47]
	v_mfma_f32_16x16x32_bf16 v[40:43], v[194:197], v[218:221], v[40:43]
	v_mfma_f32_16x16x32_bf16 v[36:39], v[186:189], v[226:229], v[36:39]
	v_mfma_f32_16x16x32_bf16 v[32:35], v[194:197], v[226:229], v[32:35]
	v_mfma_f32_16x16x32_bf16 v[60:63], v[190:193], v[206:209], v[60:63]
	v_mfma_f32_16x16x32_bf16 v[56:59], v[198:201], v[206:209], v[56:59]
	v_mfma_f32_16x16x32_bf16 v[52:55], v[190:193], v[214:217], v[52:55]
	v_mfma_f32_16x16x32_bf16 v[48:51], v[198:201], v[214:217], v[48:51]
	v_mfma_f32_16x16x32_bf16 v[44:47], v[190:193], v[222:225], v[44:47]
	v_mfma_f32_16x16x32_bf16 v[40:43], v[198:201], v[222:225], v[40:43]
	v_mfma_f32_16x16x32_bf16 v[36:39], v[190:193], v[230:233], v[36:39]
	v_mfma_f32_16x16x32_bf16 v[32:35], v[198:201], v[230:233], v[32:35]
	s_barrier
; #define PG8_STAGE(bufoff, gbase, voff) do { _Pragma("unroll") for (int _i = 0; _i < 2; ++_i) \
;         __builtin_amdgcn_global_load_lds((const unsigned*)((const char*)(gbase) + (voff)[_i]), (LAS unsigned*)(lds + (bufoff) + ldsw + _i * 8192), 16, 0, 0); } while (0)
; #define PG8_LDA(dst, b, h) do { _Pragma("unroll") for (int m = 0; m < 4; ++m) _Pragma("unroll") for (int k = 0; k < 2; ++k) dst[m][k] = *(const LAS bf16x8*)(lds + PG8_SA(b, h) + aoff + m * 2048 + k * 1024); } while (0)
; #define PG8_LDB(dst, b, h) do { _Pragma("unroll") for (int n = 0; n < 2; ++n) _Pragma("unroll") for (int k = 0; k < 2; ++k) dst[n][k] = *(const LAS bf16x8*)(lds + PG8_SB(b, h) + boff + n * 2048 + k * 1024); } while (0)
; #define PG8_MMA(ai, bj, At, Bt) do { __builtin_amdgcn_s_setprio(1); _Pragma("unroll") for (int m = 0; m < 4; ++m) _Pragma("unroll") for (int n = 0; n < 2; ++n) _Pragma("unroll") for (int k = 0; k < 2; ++k) \
;         acc[ai][bj][m][n] = __builtin_amdgcn_mfma_f32_16x16x32_bf16(Bt[n][k], At[m][k], acc[ai][bj][m][n], 0, 0, 0); __builtin_amdgcn_s_setprio(0); } while (0)
; #define PG8_WAIT_V(n) asm volatile("s_waitcnt vmcnt(" #n ")" ::: "memory")
; #define PG8_WAIT_L(n) asm volatile("s_waitcnt lgkmcnt(" #n ")" ::: "memory")
; #define PG8_BAR __builtin_amdgcn_s_barrier()
; #define PG8_SCHED __builtin_amdgcn_sched_barrier(0)
; template <class Epi, bool ALIGN_EPI>
; __device__ __forceinline__ void gemm_phase(LAS unsigned char* lds, const Gemm g, const StaticOrder S, const Epi E) {
;     ...
;             PG8_LDA(At, 0, 1); PG8_STAGE(PG8_SB(0, 0), b2, voffB); PG8_STAGE(PG8_SB(0, 1), b2 + hstepB, voffB); PG8_STAGE(PG8_SA(0, 0), a2, voffA);
;             PG8_WAIT_V(8); PG8_WAIT_L(0); PG8_BAR; PG8_MMA(1, 0, At, B0); PG8_MMA(1, 1, At, B1); PG8_BAR; PG8_SCHED;
;             PG8_LDB(B0, 1, 0); PG8_LDB(B1, 1, 1); PG8_SCHED; PG8_LDA(At, 1, 0); PG8_STAGE(PG8_SA(0, 1), a2 + hstepA, voffA);
;             PG8_WAIT_V(8); PG8_WAIT_L(0); PG8_BAR; PG8_MMA(0, 0, At, B0); PG8_MMA(0, 1, At, B1); PG8_BAR; PG8_SCHED;
	s_add_i32 s0, s0, s61
	v_lshl_add_u64 v[152:153], s[52:53], 0, v[138:139]
	s_mov_b32 m0, s0
	ds_read_b128 v[202:205], v157 offset:16384
	ds_read_b128 v[206:209], v157 offset:17408
	ds_read_b128 v[210:213], v157 offset:18432
	ds_read_b128 v[214:217], v157 offset:19456
	ds_read_b128 v[218:221], v157 offset:20480
	ds_read_b128 v[222:225], v157 offset:21504
	ds_read_b128 v[226:229], v157 offset:22528
	ds_read_b128 v[230:233], v157 offset:23552
	global_load_lds_dwordx4 v[152:153], off
	s_add_i32 m0, s0, 0x2000
	s_add_u32 s0, s52, 0x18000
	v_lshl_add_u64 v[168:169], s[52:53], 0, v[142:143]
	s_addc_u32 s1, s53, 0
	s_add_i32 s12, s12, s61
	global_load_lds_dwordx4 v[168:169], off
	v_lshl_add_u64 v[170:171], s[0:1], 0, v[138:139]
	s_mov_b32 m0, s12
	v_lshl_add_u64 v[172:173], s[54:55], 0, v[140:141]
	global_load_lds_dwordx4 v[170:171], off
	v_lshl_add_u64 v[170:171], s[0:1], 0, v[142:143]
	s_add_i32 m0, s12, 0x2000
	s_nop 0
	global_load_lds_dwordx4 v[170:171], off
	v_lshl_add_u64 v[170:171], s[54:55], 0, v[136:137]
	s_mov_b32 m0, s62
	s_nop 0
	global_load_lds_dwordx4 v[170:171], off
	s_mov_b32 m0, s63
	s_nop 0
	global_load_lds_dwordx4 v[172:173], off
	s_waitcnt vmcnt(8)
	s_waitcnt lgkmcnt(0)
	s_barrier
	s_waitcnt lgkmcnt(0)
	v_mfma_f32_16x16x32_bf16 v[94:97], v[148:151], v[202:205], v[94:97]
	v_mfma_f32_16x16x32_bf16 v[90:93], v[162:165], v[202:205], v[90:93]
	v_mfma_f32_16x16x32_bf16 v[86:89], v[148:151], v[210:213], v[86:89]
	v_mfma_f32_16x16x32_bf16 v[82:85], v[162:165], v[210:213], v[82:85]
	v_mfma_f32_16x16x32_bf16 v[76:79], v[148:151], v[218:221], v[76:79]
	v_mfma_f32_16x16x32_bf16 v[72:75], v[162:165], v[218:221], v[72:75]
	v_mfma_f32_16x16x32_bf16 v[68:71], v[148:151], v[226:229], v[68:71]
	v_mfma_f32_16x16x32_bf16 v[64:67], v[162:165], v[226:229], v[64:67]
	v_mfma_f32_16x16x32_bf16 v[94:97], v[158:161], v[206:209], v[94:97]
	v_mfma_f32_16x16x32_bf16 v[90:93], v[182:185], v[206:209], v[90:93]
	v_mfma_f32_16x16x32_bf16 v[86:89], v[158:161], v[214:217], v[86:89]
	v_mfma_f32_16x16x32_bf16 v[82:85], v[182:185], v[214:217], v[82:85]
	v_mfma_f32_16x16x32_bf16 v[76:79], v[158:161], v[222:225], v[76:79]
	v_mfma_f32_16x16x32_bf16 v[72:75], v[182:185], v[222:225], v[72:75]
	v_mfma_f32_16x16x32_bf16 v[68:71], v[158:161], v[230:233], v[68:71]
	v_mfma_f32_16x16x32_bf16 v[64:67], v[182:185], v[230:233], v[64:67]
	v_mfma_f32_16x16x32_bf16 v[28:31], v[186:189], v[202:205], v[28:31]
	v_mfma_f32_16x16x32_bf16 v[24:27], v[194:197], v[202:205], v[24:27]
	v_mfma_f32_16x16x32_bf16 v[20:23], v[186:189], v[210:213], v[20:23]
	v_mfma_f32_16x16x32_bf16 v[16:19], v[194:197], v[210:213], v[16:19]
	v_mfma_f32_16x16x32_bf16 v[12:15], v[186:189], v[218:221], v[12:15]
	v_mfma_f32_16x16x32_bf16 v[8:11], v[194:197], v[218:221], v[8:11]
	v_mfma_f32_16x16x32_bf16 v[4:7], v[186:189], v[226:229], v[4:7]
	v_mfma_f32_16x16x32_bf16 v[0:3], v[194:197], v[226:229], v[0:3]
	v_mfma_f32_16x16x32_bf16 v[28:31], v[190:193], v[206:209], v[28:31]
	v_mfma_f32_16x16x32_bf16 v[24:27], v[198:201], v[206:209], v[24:27]
	v_mfma_f32_16x16x32_bf16 v[20:23], v[190:193], v[214:217], v[20:23]
	v_mfma_f32_16x16x32_bf16 v[16:19], v[198:201], v[214:217], v[16:19]
	v_mfma_f32_16x16x32_bf16 v[12:15], v[190:193], v[222:225], v[12:15]
	v_mfma_f32_16x16x32_bf16 v[8:11], v[198:201], v[222:225], v[8:11]
	v_mfma_f32_16x16x32_bf16 v[4:7], v[190:193], v[230:233], v[4:7]
	v_mfma_f32_16x16x32_bf16 v[0:3], v[198:201], v[230:233], v[0:3]
	s_barrier
	s_add_i32 s12, 0, 0x18000
	v_add_u32_e32 v80, s12, v156
	s_add_i32 s15, 0, 0x1c000
	ds_read_b128 v[148:151], v80
	ds_read_b128 v[158:161], v80 offset:1024
	ds_read_b128 v[162:165], v80 offset:2048
	ds_read_b128 v[182:185], v80 offset:3072
	v_add_u32_e32 v80, s15, v156
	ds_read_b128 v[186:189], v80
	ds_read_b128 v[190:193], v80 offset:1024
	ds_read_b128 v[194:197], v80 offset:2048
	ds_read_b128 v[198:201], v80 offset:3072
	s_add_u32 s0, s54, 0xb0000
	s_addc_u32 s1, s55, 0
	s_mov_b32 m0, s64
	v_lshl_add_u64 v[176:177], s[0:1], 0, v[136:137]
	ds_read_b128 v[202:205], v157 offset:32768
	ds_read_b128 v[206:209], v157 offset:33792
	ds_read_b128 v[210:213], v157 offset:34816
	ds_read_b128 v[214:217], v157 offset:35840
	ds_read_b128 v[218:221], v157 offset:36864
	ds_read_b128 v[222:225], v157 offset:37888
	ds_read_b128 v[226:229], v157 offset:38912
	ds_read_b128 v[230:233], v157 offset:39936
	global_load_lds_dwordx4 v[176:177], off
	v_lshl_add_u64 v[176:177], s[0:1], 0, v[140:141]
	s_mov_b32 m0, s65
	s_nop 0
	global_load_lds_dwordx4 v[176:177], off
	s_waitcnt vmcnt(8)
	s_waitcnt lgkmcnt(0)
	s_barrier
; #define PG8_STAGE(bufoff, gbase, voff) do { _Pragma("unroll") for (int _i = 0; _i < 2; ++_i) \
;         __builtin_amdgcn_global_load_lds((const unsigned*)((const char*)(gbase) + (voff)[_i]), (LAS unsigned*)(lds + (bufoff) + ldsw + _i * 8192), 16, 0, 0); } while (0)
; #define PG8_LDA(dst, b, h) do { _Pragma("unroll") for (int m = 0; m < 4; ++m) _Pragma("unroll") for (int k = 0; k < 2; ++k) dst[m][k] = *(const LAS bf16x8*)(lds + PG8_SA(b, h) + aoff + m * 2048 + k * 1024); } while (0)
; #define PG8_MMA(ai, bj, At, Bt) do { __builtin_amdgcn_s_setprio(1); _Pragma("unroll") for (int m = 0; m < 4; ++m) _Pragma("unroll") for (int n = 0; n < 2; ++n) _Pragma("unroll") for (int k = 0; k < 2; ++k) \
;         acc[ai][bj][m][n] = __builtin_amdgcn_mfma_f32_16x16x32_bf16(Bt[n][k], At[m][k], acc[ai][bj][m][n], 0, 0, 0); __builtin_amdgcn_s_setprio(0); } while (0)
; #define PG8_WAIT_V(n) asm volatile("s_waitcnt vmcnt(" #n ")" ::: "memory")
; #define PG8_WAIT_L(n) asm volatile("s_waitcnt lgkmcnt(" #n ")" ::: "memory")
; #define PG8_BAR __builtin_amdgcn_s_barrier()
; #define PG8_SCHED __builtin_amdgcn_sched_barrier(0)
; template <class Epi, bool ALIGN_EPI>
; __device__ __forceinline__ void gemm_phase(LAS unsigned char* lds, const Gemm g, const StaticOrder S, const Epi E) {
;     ...
;             PG8_WAIT_V(8); PG8_WAIT_L(0); PG8_BAR; PG8_MMA(0, 0, At, B0); PG8_MMA(0, 1, At, B1); PG8_BAR; PG8_SCHED;
;             PG8_LDA(At, 1, 1); PG8_STAGE(PG8_SB(1, 0), b3, voffB); PG8_STAGE(PG8_SB(1, 1), b3 + hstepB, voffB); PG8_STAGE(PG8_SA(1, 0), a3, voffA);
;             PG8_WAIT_V(8); PG8_WAIT_L(0); PG8_BAR; PG8_MMA(1, 0, At, B0); PG8_MMA(1, 1, At, B1); PG8_BAR; PG8_SCHED;
;         }
;         if constexpr (ALIGN_EPI) { if (wr == 0) PG8_BAR; }
	s_waitcnt lgkmcnt(0)
	v_mfma_f32_16x16x32_bf16 v[126:129], v[148:151], v[202:205], v[126:129]
	v_mfma_f32_16x16x32_bf16 v[122:125], v[162:165], v[202:205], v[122:125]
	v_mfma_f32_16x16x32_bf16 v[118:121], v[148:151], v[210:213], v[118:121]
	v_mfma_f32_16x16x32_bf16 v[114:117], v[162:165], v[210:213], v[114:117]
	v_mfma_f32_16x16x32_bf16 v[110:113], v[148:151], v[218:221], v[110:113]
	v_mfma_f32_16x16x32_bf16 v[106:109], v[162:165], v[218:221], v[106:109]
	v_mfma_f32_16x16x32_bf16 v[102:105], v[148:151], v[226:229], v[102:105]
	v_mfma_f32_16x16x32_bf16 v[98:101], v[162:165], v[226:229], v[98:101]
	v_mfma_f32_16x16x32_bf16 v[126:129], v[158:161], v[206:209], v[126:129]
	v_mfma_f32_16x16x32_bf16 v[122:125], v[182:185], v[206:209], v[122:125]
	v_mfma_f32_16x16x32_bf16 v[118:121], v[158:161], v[214:217], v[118:121]
	v_mfma_f32_16x16x32_bf16 v[114:117], v[182:185], v[214:217], v[114:117]
	v_mfma_f32_16x16x32_bf16 v[110:113], v[158:161], v[222:225], v[110:113]
	v_mfma_f32_16x16x32_bf16 v[106:109], v[182:185], v[222:225], v[106:109]
	v_mfma_f32_16x16x32_bf16 v[102:105], v[158:161], v[230:233], v[102:105]
	v_mfma_f32_16x16x32_bf16 v[98:101], v[182:185], v[230:233], v[98:101]
	v_mfma_f32_16x16x32_bf16 v[60:63], v[186:189], v[202:205], v[60:63]
	v_mfma_f32_16x16x32_bf16 v[56:59], v[194:197], v[202:205], v[56:59]
	v_mfma_f32_16x16x32_bf16 v[52:55], v[186:189], v[210:213], v[52:55]
	v_mfma_f32_16x16x32_bf16 v[48:51], v[194:197], v[210:213], v[48:51]
	v_mfma_f32_16x16x32_bf16 v[44:47], v[186:189], v[218:221], v[44:47]
	v_mfma_f32_16x16x32_bf16 v[40:43], v[194:197], v[218:221], v[40:43]
	v_mfma_f32_16x16x32_bf16 v[36:39], v[186:189], v[226:229], v[36:39]
	v_mfma_f32_16x16x32_bf16 v[32:35], v[194:197], v[226:229], v[32:35]
	v_mfma_f32_16x16x32_bf16 v[60:63], v[190:193], v[206:209], v[60:63]
	v_mfma_f32_16x16x32_bf16 v[56:59], v[198:201], v[206:209], v[56:59]
	v_mfma_f32_16x16x32_bf16 v[52:55], v[190:193], v[214:217], v[52:55]
	v_mfma_f32_16x16x32_bf16 v[48:51], v[198:201], v[214:217], v[48:51]
	v_mfma_f32_16x16x32_bf16 v[44:47], v[190:193], v[222:225], v[44:47]
	v_mfma_f32_16x16x32_bf16 v[40:43], v[198:201], v[222:225], v[40:43]
	v_mfma_f32_16x16x32_bf16 v[36:39], v[190:193], v[230:233], v[36:39]
	v_mfma_f32_16x16x32_bf16 v[32:35], v[198:201], v[230:233], v[32:35]
	s_barrier
	s_add_i32 s0, s12, s61
	v_lshl_add_u64 v[152:153], v[152:153], 0, s[80:81]
	s_mov_b32 m0, s0
	ds_read_b128 v[202:205], v157 offset:49152
	ds_read_b128 v[206:209], v157 offset:50176
	ds_read_b128 v[210:213], v157 offset:51200
	ds_read_b128 v[214:217], v157 offset:52224
	ds_read_b128 v[218:221], v157 offset:53248
	ds_read_b128 v[222:225], v157 offset:54272
	ds_read_b128 v[226:229], v157 offset:55296
	ds_read_b128 v[230:233], v157 offset:56320
	global_load_lds_dwordx4 v[152:153], off
	s_add_i32 m0, s0, 0x2000
	s_add_u32 s0, s52, 0x18080
	v_lshl_add_u64 v[152:153], v[168:169], 0, s[80:81]
	s_addc_u32 s1, s53, 0
	s_add_i32 s12, s15, s61
	global_load_lds_dwordx4 v[152:153], off
	v_lshl_add_u64 v[152:153], s[0:1], 0, v[138:139]
	s_mov_b32 m0, s12
	s_nop 0
	global_load_lds_dwordx4 v[152:153], off
	v_lshl_add_u64 v[152:153], s[0:1], 0, v[142:143]
	s_add_i32 m0, s12, 0x2000
	s_nop 0
	global_load_lds_dwordx4 v[152:153], off
	v_lshl_add_u64 v[152:153], v[170:171], 0, s[80:81]
	s_mov_b32 m0, s68
	s_nop 0
	global_load_lds_dwordx4 v[152:153], off
	v_lshl_add_u64 v[152:153], v[172:173], 0, s[80:81]
	s_mov_b32 m0, s69
	s_nop 0
	global_load_lds_dwordx4 v[152:153], off
	s_waitcnt vmcnt(8)
	s_waitcnt lgkmcnt(0)
	s_barrier
	s_waitcnt lgkmcnt(0)
	v_mfma_f32_16x16x32_bf16 v[94:97], v[148:151], v[202:205], v[94:97]
	v_mfma_f32_16x16x32_bf16 v[90:93], v[162:165], v[202:205], v[90:93]
	v_mfma_f32_16x16x32_bf16 v[86:89], v[148:151], v[210:213], v[86:89]
	v_mfma_f32_16x16x32_bf16 v[82:85], v[162:165], v[210:213], v[82:85]
	v_mfma_f32_16x16x32_bf16 v[76:79], v[148:151], v[218:221], v[76:79]
	v_mfma_f32_16x16x32_bf16 v[72:75], v[162:165], v[218:221], v[72:75]
	v_mfma_f32_16x16x32_bf16 v[68:71], v[148:151], v[226:229], v[68:71]
	v_mfma_f32_16x16x32_bf16 v[64:67], v[162:165], v[226:229], v[64:67]
	v_mfma_f32_16x16x32_bf16 v[94:97], v[158:161], v[206:209], v[94:97]
	v_mfma_f32_16x16x32_bf16 v[90:93], v[182:185], v[206:209], v[90:93]
	v_mfma_f32_16x16x32_bf16 v[86:89], v[158:161], v[214:217], v[86:89]
	v_mfma_f32_16x16x32_bf16 v[82:85], v[182:185], v[214:217], v[82:85]
	v_mfma_f32_16x16x32_bf16 v[76:79], v[158:161], v[222:225], v[76:79]
	v_mfma_f32_16x16x32_bf16 v[72:75], v[182:185], v[222:225], v[72:75]
	v_mfma_f32_16x16x32_bf16 v[68:71], v[158:161], v[230:233], v[68:71]
	v_mfma_f32_16x16x32_bf16 v[64:67], v[182:185], v[230:233], v[64:67]
	v_mfma_f32_16x16x32_bf16 v[28:31], v[186:189], v[202:205], v[28:31]
	v_mfma_f32_16x16x32_bf16 v[24:27], v[194:197], v[202:205], v[24:27]
	v_mfma_f32_16x16x32_bf16 v[20:23], v[186:189], v[210:213], v[20:23]
	v_mfma_f32_16x16x32_bf16 v[16:19], v[194:197], v[210:213], v[16:19]
	v_mfma_f32_16x16x32_bf16 v[12:15], v[186:189], v[218:221], v[12:15]
	v_mfma_f32_16x16x32_bf16 v[8:11], v[194:197], v[218:221], v[8:11]
	v_mfma_f32_16x16x32_bf16 v[4:7], v[186:189], v[226:229], v[4:7]
	v_mfma_f32_16x16x32_bf16 v[0:3], v[194:197], v[226:229], v[0:3]
	v_mfma_f32_16x16x32_bf16 v[28:31], v[190:193], v[206:209], v[28:31]
	v_mfma_f32_16x16x32_bf16 v[24:27], v[198:201], v[206:209], v[24:27]
	v_mfma_f32_16x16x32_bf16 v[20:23], v[190:193], v[214:217], v[20:23]
	v_mfma_f32_16x16x32_bf16 v[16:19], v[198:201], v[214:217], v[16:19]
	v_mfma_f32_16x16x32_bf16 v[12:15], v[190:193], v[222:225], v[12:15]
	v_mfma_f32_16x16x32_bf16 v[8:11], v[198:201], v[222:225], v[8:11]
	v_mfma_f32_16x16x32_bf16 v[4:7], v[190:193], v[230:233], v[4:7]
	v_mfma_f32_16x16x32_bf16 v[0:3], v[198:201], v[230:233], v[0:3]
	s_barrier
	s_add_i32 s28, s28, 2
	s_add_u32 s26, s26, 0x100
	s_addc_u32 s27, s27, 0
	s_cmp_gt_u32 s28, 3
	s_mov_b64 s[48:49], s[50:51]
	s_cbranch_scc0 .LBB0_1757
	s_setprio 0
	s_and_b64 vcc, exec, s[44:45]
	s_cbranch_vccz .LBB0_1760
	s_barrier

; #define PG8_STAGE(bufoff, gbase, voff) do { _Pragma("unroll") for (int _i = 0; _i < 2; ++_i) \
;         __builtin_amdgcn_global_load_lds((const unsigned*)((const char*)(gbase) + (voff)[_i]), (LAS unsigned*)(lds + (bufoff) + ldsw + _i * 8192), 16, 0, 0); } while (0)
; #define PG8_LDA(dst, b, h) do { _Pragma("unroll") for (int m = 0; m < 4; ++m) _Pragma("unroll") for (int k = 0; k < 2; ++k) dst[m][k] = *(const LAS bf16x8*)(lds + PG8_SA(b, h) + aoff + m * 2048 + k * 1024); } while (0)
; #define PG8_LDB(dst, b, h) do { _Pragma("unroll") for (int n = 0; n < 2; ++n) _Pragma("unroll") for (int k = 0; k < 2; ++k) dst[n][k] = *(const LAS bf16x8*)(lds + PG8_SB(b, h) + boff + n * 2048 + k * 1024); } while (0)
; #define PG8_MMA(ai, bj, At, Bt) do { __builtin_amdgcn_s_setprio(1); _Pragma("unroll") for (int m = 0; m < 4; ++m) _Pragma("unroll") for (int n = 0; n < 2; ++n) _Pragma("unroll") for (int k = 0; k < 2; ++k) \
;         acc[ai][bj][m][n] = __builtin_amdgcn_mfma_f32_16x16x32_bf16(Bt[n][k], At[m][k], acc[ai][bj][m][n], 0, 0, 0); __builtin_amdgcn_s_setprio(0); } while (0)
; template <class Epi, bool ALIGN_EPI>
; __device__ __forceinline__ void gemm_phase(LAS unsigned char* lds, const Gemm g, const StaticOrder S, const Epi E) {
;     ...
;         const char* nA = has_next ? (const char*)g.A + (size_t)nxt.pm * tstepA + PG8_KOFS(nxt) : cA; const char* nB = has_next ? (const char*)g.Bt + (size_t)nxt.pn * tstepB + PG8_KOFS(nxt) : cB;
; #pragma unroll 1
;         for (int t = 0; t < nt; t += 2) {
;             const bool last = (t == nt - 2);
;             const char* a1 = cA + (size_t)(t + 1) * kstep;
;             const char* a2 = last ? nA : cA + (size_t)(t + 2) * kstep; const char* b2 = last ? nB : cB + (size_t)(t + 2) * kstep;
;             const char* a3 = a2 + kstep; const char* b3 = b2 + kstep;
;             PG8_LDB(B0, 0, 0); PG8_LDB(B1, 0, 1); PG8_SCHED; PG8_LDA(At, 0, 0); PG8_STAGE(PG8_SA(1, 1), a1 + hstepA, voffA);
;             PG8_WAIT_V(8); PG8_WAIT_L(0); PG8_BAR; PG8_MMA(0, 0, At, B0); PG8_MMA(0, 1, At, B1); PG8_BAR; PG8_SCHED;
;     ...
; #pragma unroll
;         for (int a = 0; a < 2; ++a)
; #pragma unroll
;             for (int b = 0; b < 2; ++b)
; #pragma unroll
;                 for (int m = 0; m < 4; ++m)
; #pragma unroll
;                     for (int n = 0; n < 2; ++n) acc[a][b][m][n] = (f32x4){0.f, 0.f, 0.f, 0.f};
;         cur = nxt; cA = nA; cB = nB; ++ui;
.LBB0_1814:
	s_ashr_i32 s47, s46, 31
	s_lshl_b64 s[0:1], s[46:47], 17
	v_readlane_b32 s12, v255, 37
	s_add_u32 s50, s12, s0
	v_readlane_b32 s0, v255, 38
	s_addc_u32 s51, s0, s1
	s_and_b64 s[0:1], s[42:43], exec
	v_mov_b32_e32 v0, 0
	s_cselect_b32 s47, s51, s53
	s_cselect_b32 s93, s50, s52
	s_mov_b64 s[64:65], 0
	s_mov_b64 s[42:43], -1
	s_mov_b64 s[62:63], 0
	v_mov_b32_e32 v1, 0
	v_mov_b64_e32 v[2:3], 0
	v_mov_b64_e32 v[4:5], 0
	v_mov_b64_e32 v[6:7], 0
	v_mov_b64_e32 v[8:9], 0
	v_mov_b64_e32 v[10:11], 0
	v_mov_b64_e32 v[12:13], 0
	v_mov_b64_e32 v[14:15], 0
	v_mov_b64_e32 v[16:17], 0
	v_mov_b64_e32 v[18:19], 0
	v_mov_b64_e32 v[20:21], 0
	v_mov_b64_e32 v[22:23], 0
	v_mov_b64_e32 v[24:25], 0
	v_mov_b64_e32 v[26:27], 0
	v_mov_b64_e32 v[28:29], 0
	v_mov_b64_e32 v[30:31], 0
	v_mov_b64_e32 v[32:33], 0
	v_mov_b64_e32 v[34:35], 0
	v_mov_b64_e32 v[36:37], 0
	v_mov_b64_e32 v[38:39], 0
	v_mov_b64_e32 v[40:41], 0
	v_mov_b64_e32 v[42:43], 0
	v_mov_b64_e32 v[44:45], 0
	v_mov_b64_e32 v[46:47], 0
	v_mov_b64_e32 v[48:49], 0
	v_mov_b64_e32 v[50:51], 0
	v_mov_b64_e32 v[52:53], 0
	v_mov_b64_e32 v[54:55], 0
	v_mov_b64_e32 v[56:57], 0
	v_mov_b64_e32 v[58:59], 0
	v_mov_b64_e32 v[60:61], 0
	v_mov_b64_e32 v[62:63], 0
	v_mov_b64_e32 v[64:65], 0
	v_mov_b64_e32 v[66:67], 0
	v_mov_b64_e32 v[68:69], 0
	v_mov_b64_e32 v[70:71], 0
	v_mov_b64_e32 v[72:73], 0
	v_mov_b64_e32 v[74:75], 0
	v_mov_b64_e32 v[76:77], 0
	v_mov_b64_e32 v[78:79], 0
	v_mov_b64_e32 v[82:83], 0
	v_mov_b64_e32 v[84:85], 0
	v_mov_b64_e32 v[86:87], 0
	v_mov_b64_e32 v[88:89], 0
	v_mov_b64_e32 v[90:91], 0
	v_mov_b64_e32 v[92:93], 0
	v_mov_b64_e32 v[94:95], 0
	v_mov_b64_e32 v[96:97], 0
	v_mov_b64_e32 v[98:99], 0
	v_mov_b64_e32 v[100:101], 0
	v_mov_b64_e32 v[102:103], 0
	v_mov_b64_e32 v[104:105], 0
	v_mov_b64_e32 v[106:107], 0
	v_mov_b64_e32 v[108:109], 0
	v_mov_b64_e32 v[110:111], 0
	v_mov_b64_e32 v[112:113], 0
	v_mov_b64_e32 v[114:115], 0
	v_mov_b64_e32 v[116:117], 0
	v_mov_b64_e32 v[118:119], 0
	v_mov_b64_e32 v[120:121], 0
	v_mov_b64_e32 v[122:123], 0
	v_mov_b64_e32 v[124:125], 0
	v_mov_b64_e32 v[126:127], 0
	v_mov_b64_e32 v[128:129], 0
	v_readfirstlane_b32 s0, v167
	s_nop 3
	s_cmpk_lt_u32 s0, 0x100
	s_cbranch_scc1 .Lprio_k6
	s_setprio 1
.Lprio_k6:
.LBB0_1815:
	s_add_u32 s12, s54, s64
	s_addc_u32 s15, s55, s65
	s_add_u32 s16, s12, 0x100
	s_addc_u32 s18, s15, 0
	s_and_b64 s[0:1], s[62:63], exec
	s_cselect_b32 s67, s49, s18
	s_cselect_b32 s66, s48, s16
	s_add_u32 s0, s52, s64
	s_addc_u32 s1, s53, s65
	s_add_u32 s16, s0, 0x100
	s_addc_u32 s18, s1, 0
	s_add_i32 s83, 0, 0x10000
	s_and_b64 s[0:1], s[62:63], exec
	s_cselect_b32 s69, s47, s18
	s_cselect_b32 s68, s93, s16
	s_add_i32 s16, 0, 0x14000
	s_add_u32 s72, s12, 0xb0080
	s_addc_u32 s73, s15, 0
	s_add_i32 s0, s83, s24
	s_add_i32 m0, s21, 0xc000
	s_add_i32 s25, s21, 0xe000
	s_add_i32 s33, s0, 0x2000
	v_add_u32_e32 v130, s83, v146
	s_add_u32 s70, s68, 0x10000
	ds_read_b128 v[148:151], v130
	ds_read_b128 v[152:155], v130 offset:1024
	ds_read_b128 v[156:159], v130 offset:2048
	ds_read_b128 v[160:163], v130 offset:3072
	v_add_u32_e32 v130, s16, v146
	s_addc_u32 s71, s69, 0
	s_add_i32 s1, s16, s24
	ds_read_b128 v[182:185], v130
	ds_read_b128 v[186:189], v130 offset:1024
	ds_read_b128 v[190:193], v130 offset:2048
	ds_read_b128 v[194:197], v130 offset:3072
	s_add_i32 s82, s1, 0x2000
	s_add_i32 vcc_hi, 0, 0x18000
	s_add_i32 s12, 0, 0x1c000
	s_add_u32 s64, s66, 0xb0000
	s_addc_u32 s65, s67, 0
	s_add_i32 vcc_lo, vcc_hi, s24
	s_add_i32 s18, vcc_lo, 0x2000
	s_add_u32 s62, s68, 0x10080
	s_addc_u32 s63, s69, 0
	s_add_i32 s15, s12, s24
	s_add_i32 s16, s15, 0x2000
	v_lshl_add_u64 v[142:143], s[72:73], 0, v[136:137]
	ds_read_b128 v[198:201], v147
	ds_read_b128 v[202:205], v147 offset:1024
	ds_read_b128 v[206:209], v147 offset:2048
	ds_read_b128 v[210:213], v147 offset:3072
	ds_read_b128 v[214:217], v147 offset:4096
	ds_read_b128 v[218:221], v147 offset:5120
	ds_read_b128 v[222:225], v147 offset:6144
	ds_read_b128 v[226:229], v147 offset:7168
	global_load_lds_dwordx4 v[142:143], off
	v_lshl_add_u64 v[142:143], s[72:73], 0, v[138:139]
	s_mov_b32 m0, s25
	s_nop 0
	global_load_lds_dwordx4 v[142:143], off
	s_waitcnt vmcnt(8)
	s_waitcnt lgkmcnt(0)
	s_barrier
	s_waitcnt lgkmcnt(0)
	v_mfma_f32_16x16x32_bf16 v[126:129], v[148:151], v[198:201], v[126:129]
	v_mfma_f32_16x16x32_bf16 v[122:125], v[156:159], v[198:201], v[122:125]
	v_mfma_f32_16x16x32_bf16 v[118:121], v[148:151], v[206:209], v[118:121]
	v_mfma_f32_16x16x32_bf16 v[110:113], v[156:159], v[206:209], v[110:113]
	v_mfma_f32_16x16x32_bf16 v[102:105], v[148:151], v[214:217], v[102:105]
	v_mfma_f32_16x16x32_bf16 v[94:97], v[156:159], v[214:217], v[94:97]
	v_mfma_f32_16x16x32_bf16 v[86:89], v[148:151], v[222:225], v[86:89]
	v_mfma_f32_16x16x32_bf16 v[76:79], v[156:159], v[222:225], v[76:79]
	v_mfma_f32_16x16x32_bf16 v[126:129], v[152:155], v[202:205], v[126:129]
	v_mfma_f32_16x16x32_bf16 v[122:125], v[160:163], v[202:205], v[122:125]
	v_mfma_f32_16x16x32_bf16 v[118:121], v[152:155], v[210:213], v[118:121]
	v_mfma_f32_16x16x32_bf16 v[110:113], v[160:163], v[210:213], v[110:113]
	v_mfma_f32_16x16x32_bf16 v[102:105], v[152:155], v[218:221], v[102:105]
	v_mfma_f32_16x16x32_bf16 v[94:97], v[160:163], v[218:221], v[94:97]
	v_mfma_f32_16x16x32_bf16 v[86:89], v[152:155], v[226:229], v[86:89]
	v_mfma_f32_16x16x32_bf16 v[76:79], v[160:163], v[226:229], v[76:79]
	v_mfma_f32_16x16x32_bf16 v[114:117], v[182:185], v[198:201], v[114:117]
	v_mfma_f32_16x16x32_bf16 v[106:109], v[190:193], v[198:201], v[106:109]
	v_mfma_f32_16x16x32_bf16 v[98:101], v[182:185], v[206:209], v[98:101]
	v_mfma_f32_16x16x32_bf16 v[90:93], v[190:193], v[206:209], v[90:93]
	v_mfma_f32_16x16x32_bf16 v[82:85], v[182:185], v[214:217], v[82:85]
	v_mfma_f32_16x16x32_bf16 v[72:75], v[190:193], v[214:217], v[72:75]
	v_mfma_f32_16x16x32_bf16 v[68:71], v[182:185], v[222:225], v[68:71]
	v_mfma_f32_16x16x32_bf16 v[64:67], v[190:193], v[222:225], v[64:67]
	v_mfma_f32_16x16x32_bf16 v[114:117], v[186:189], v[202:205], v[114:117]
	v_mfma_f32_16x16x32_bf16 v[106:109], v[194:197], v[202:205], v[106:109]
	v_mfma_f32_16x16x32_bf16 v[98:101], v[186:189], v[210:213], v[98:101]
	v_mfma_f32_16x16x32_bf16 v[90:93], v[194:197], v[210:213], v[90:93]
	v_mfma_f32_16x16x32_bf16 v[82:85], v[186:189], v[218:221], v[82:85]
	v_mfma_f32_16x16x32_bf16 v[72:75], v[194:197], v[218:221], v[72:75]
	v_mfma_f32_16x16x32_bf16 v[68:71], v[186:189], v[226:229], v[68:71]
	v_mfma_f32_16x16x32_bf16 v[64:67], v[194:197], v[226:229], v[64:67]
	s_barrier
; #define PG8_STAGE(bufoff, gbase, voff) do { _Pragma("unroll") for (int _i = 0; _i < 2; ++_i) \
;         __builtin_amdgcn_global_load_lds((const unsigned*)((const char*)(gbase) + (voff)[_i]), (LAS unsigned*)(lds + (bufoff) + ldsw + _i * 8192), 16, 0, 0); } while (0)
; #define PG8_LDA(dst, b, h) do { _Pragma("unroll") for (int m = 0; m < 4; ++m) _Pragma("unroll") for (int k = 0; k < 2; ++k) dst[m][k] = *(const LAS bf16x8*)(lds + PG8_SA(b, h) + aoff + m * 2048 + k * 1024); } while (0)
; #define PG8_LDB(dst, b, h) do { _Pragma("unroll") for (int n = 0; n < 2; ++n) _Pragma("unroll") for (int k = 0; k < 2; ++k) dst[n][k] = *(const LAS bf16x8*)(lds + PG8_SB(b, h) + boff + n * 2048 + k * 1024); } while (0)
; #define PG8_MMA(ai, bj, At, Bt) do { __builtin_amdgcn_s_setprio(1); _Pragma("unroll") for (int m = 0; m < 4; ++m) _Pragma("unroll") for (int n = 0; n < 2; ++n) _Pragma("unroll") for (int k = 0; k < 2; ++k) \
;         acc[ai][bj][m][n] = __builtin_amdgcn_mfma_f32_16x16x32_bf16(Bt[n][k], At[m][k], acc[ai][bj][m][n], 0, 0, 0); __builtin_amdgcn_s_setprio(0); } while (0)
; #define PG8_WAIT_V(n) asm volatile("s_waitcnt vmcnt(" #n ")" ::: "memory")
; #define PG8_WAIT_L(n) asm volatile("s_waitcnt lgkmcnt(" #n ")" ::: "memory")
; #define PG8_BAR __builtin_amdgcn_s_barrier()
; #define PG8_SCHED __builtin_amdgcn_sched_barrier(0)
; template <class Epi, bool ALIGN_EPI>
; __device__ __forceinline__ void gemm_phase(LAS unsigned char* lds, const Gemm g, const StaticOrder S, const Epi E) {
;     ...
;             PG8_LDA(At, 0, 1); PG8_STAGE(PG8_SB(0, 0), b2, voffB); PG8_STAGE(PG8_SB(0, 1), b2 + hstepB, voffB); PG8_STAGE(PG8_SA(0, 0), a2, voffA);
;             PG8_WAIT_V(8); PG8_WAIT_L(0); PG8_BAR; PG8_MMA(1, 0, At, B0); PG8_MMA(1, 1, At, B1); PG8_BAR; PG8_SCHED;
;             PG8_LDB(B0, 1, 0); PG8_LDB(B1, 1, 1); PG8_SCHED; PG8_LDA(At, 1, 0); PG8_STAGE(PG8_SA(0, 1), a2 + hstepA, voffA);
;             PG8_WAIT_V(8); PG8_WAIT_L(0); PG8_BAR; PG8_MMA(0, 0, At, B0); PG8_MMA(0, 1, At, B1); PG8_BAR; PG8_SCHED;
	s_mov_b32 m0, s0
	v_lshl_add_u64 v[142:143], s[68:69], 0, v[80:81]
	ds_read_b128 v[198:201], v147 offset:16384
	ds_read_b128 v[202:205], v147 offset:17408
	ds_read_b128 v[206:209], v147 offset:18432
	ds_read_b128 v[210:213], v147 offset:19456
	ds_read_b128 v[214:217], v147 offset:20480
	ds_read_b128 v[218:221], v147 offset:21504
	ds_read_b128 v[222:225], v147 offset:22528
	ds_read_b128 v[226:229], v147 offset:23552
	global_load_lds_dwordx4 v[142:143], off
	v_lshl_add_u64 v[164:165], s[68:69], 0, v[140:141]
	s_mov_b32 m0, s33
	v_lshl_add_u64 v[168:169], s[70:71], 0, v[80:81]
	global_load_lds_dwordx4 v[164:165], off
	s_mov_b32 m0, s1
	v_lshl_add_u64 v[170:171], s[66:67], 0, v[138:139]
	global_load_lds_dwordx4 v[168:169], off
	v_lshl_add_u64 v[168:169], s[70:71], 0, v[140:141]
	s_mov_b32 m0, s82
	s_nop 0
	global_load_lds_dwordx4 v[168:169], off
	v_lshl_add_u64 v[168:169], s[66:67], 0, v[136:137]
	s_mov_b32 m0, s21
	s_nop 0
	global_load_lds_dwordx4 v[168:169], off
	s_mov_b32 m0, s26
	s_nop 0
	global_load_lds_dwordx4 v[170:171], off
	s_waitcnt vmcnt(8)
	s_waitcnt lgkmcnt(0)
	s_barrier
	s_waitcnt lgkmcnt(0)
	v_mfma_f32_16x16x32_bf16 v[60:63], v[148:151], v[198:201], v[60:63]
	v_mfma_f32_16x16x32_bf16 v[56:59], v[156:159], v[198:201], v[56:59]
	v_mfma_f32_16x16x32_bf16 v[52:55], v[148:151], v[206:209], v[52:55]
	v_mfma_f32_16x16x32_bf16 v[44:47], v[156:159], v[206:209], v[44:47]
	v_mfma_f32_16x16x32_bf16 v[36:39], v[148:151], v[214:217], v[36:39]
	v_mfma_f32_16x16x32_bf16 v[28:31], v[156:159], v[214:217], v[28:31]
	v_mfma_f32_16x16x32_bf16 v[20:23], v[148:151], v[222:225], v[20:23]
	v_mfma_f32_16x16x32_bf16 v[12:15], v[156:159], v[222:225], v[12:15]
	v_mfma_f32_16x16x32_bf16 v[60:63], v[152:155], v[202:205], v[60:63]
	v_mfma_f32_16x16x32_bf16 v[56:59], v[160:163], v[202:205], v[56:59]
	v_mfma_f32_16x16x32_bf16 v[52:55], v[152:155], v[210:213], v[52:55]
	v_mfma_f32_16x16x32_bf16 v[44:47], v[160:163], v[210:213], v[44:47]
	v_mfma_f32_16x16x32_bf16 v[36:39], v[152:155], v[218:221], v[36:39]
	v_mfma_f32_16x16x32_bf16 v[28:31], v[160:163], v[218:221], v[28:31]
	v_mfma_f32_16x16x32_bf16 v[20:23], v[152:155], v[226:229], v[20:23]
	v_mfma_f32_16x16x32_bf16 v[12:15], v[160:163], v[226:229], v[12:15]
	v_mfma_f32_16x16x32_bf16 v[48:51], v[182:185], v[198:201], v[48:51]
	v_mfma_f32_16x16x32_bf16 v[40:43], v[190:193], v[198:201], v[40:43]
	v_mfma_f32_16x16x32_bf16 v[32:35], v[182:185], v[206:209], v[32:35]
	v_mfma_f32_16x16x32_bf16 v[24:27], v[190:193], v[206:209], v[24:27]
	v_mfma_f32_16x16x32_bf16 v[16:19], v[182:185], v[214:217], v[16:19]
	v_mfma_f32_16x16x32_bf16 v[8:11], v[190:193], v[214:217], v[8:11]
	v_mfma_f32_16x16x32_bf16 v[4:7], v[182:185], v[222:225], v[4:7]
	v_mfma_f32_16x16x32_bf16 v[0:3], v[190:193], v[222:225], v[0:3]
	v_mfma_f32_16x16x32_bf16 v[48:51], v[186:189], v[202:205], v[48:51]
	v_mfma_f32_16x16x32_bf16 v[40:43], v[194:197], v[202:205], v[40:43]
	v_mfma_f32_16x16x32_bf16 v[32:35], v[186:189], v[210:213], v[32:35]
	v_mfma_f32_16x16x32_bf16 v[24:27], v[194:197], v[210:213], v[24:27]
	v_mfma_f32_16x16x32_bf16 v[16:19], v[186:189], v[218:221], v[16:19]
	v_mfma_f32_16x16x32_bf16 v[8:11], v[194:197], v[218:221], v[8:11]
	v_mfma_f32_16x16x32_bf16 v[4:7], v[186:189], v[226:229], v[4:7]
	v_mfma_f32_16x16x32_bf16 v[0:3], v[194:197], v[226:229], v[0:3]
	s_barrier
	v_add_u32_e32 v130, vcc_hi, v146
	ds_read_b128 v[148:151], v130
	ds_read_b128 v[152:155], v130 offset:1024
	ds_read_b128 v[156:159], v130 offset:2048
	ds_read_b128 v[160:163], v130 offset:3072
	v_add_u32_e32 v130, s12, v146
	ds_read_b128 v[182:185], v130
	ds_read_b128 v[186:189], v130 offset:1024
	ds_read_b128 v[190:193], v130 offset:2048
	ds_read_b128 v[194:197], v130 offset:3072
	s_mov_b32 m0, s27
	v_lshl_add_u64 v[172:173], s[64:65], 0, v[136:137]
	ds_read_b128 v[198:201], v147 offset:32768
	ds_read_b128 v[202:205], v147 offset:33792
	ds_read_b128 v[206:209], v147 offset:34816
	ds_read_b128 v[210:213], v147 offset:35840
	ds_read_b128 v[214:217], v147 offset:36864
	ds_read_b128 v[218:221], v147 offset:37888
	ds_read_b128 v[222:225], v147 offset:38912
	ds_read_b128 v[226:229], v147 offset:39936
	global_load_lds_dwordx4 v[172:173], off
	v_lshl_add_u64 v[172:173], s[64:65], 0, v[138:139]
	s_mov_b32 m0, s28
	s_nop 0
	global_load_lds_dwordx4 v[172:173], off
	s_waitcnt vmcnt(8)
	s_waitcnt lgkmcnt(0)
	s_barrier
; #define PG8_STAGE(bufoff, gbase, voff) do { _Pragma("unroll") for (int _i = 0; _i < 2; ++_i) \
;         __builtin_amdgcn_global_load_lds((const unsigned*)((const char*)(gbase) + (voff)[_i]), (LAS unsigned*)(lds + (bufoff) + ldsw + _i * 8192), 16, 0, 0); } while (0)
; #define PG8_LDA(dst, b, h) do { _Pragma("unroll") for (int m = 0; m < 4; ++m) _Pragma("unroll") for (int k = 0; k < 2; ++k) dst[m][k] = *(const LAS bf16x8*)(lds + PG8_SA(b, h) + aoff + m * 2048 + k * 1024); } while (0)
; #define PG8_MMA(ai, bj, At, Bt) do { __builtin_amdgcn_s_setprio(1); _Pragma("unroll") for (int m = 0; m < 4; ++m) _Pragma("unroll") for (int n = 0; n < 2; ++n) _Pragma("unroll") for (int k = 0; k < 2; ++k) \
;         acc[ai][bj][m][n] = __builtin_amdgcn_mfma_f32_16x16x32_bf16(Bt[n][k], At[m][k], acc[ai][bj][m][n], 0, 0, 0); __builtin_amdgcn_s_setprio(0); } while (0)
; #define PG8_WAIT_V(n) asm volatile("s_waitcnt vmcnt(" #n ")" ::: "memory")
; #define PG8_WAIT_L(n) asm volatile("s_waitcnt lgkmcnt(" #n ")" ::: "memory")
; #define PG8_BAR __builtin_amdgcn_s_barrier()
; #define PG8_SCHED __builtin_amdgcn_sched_barrier(0)
; template <class Epi, bool ALIGN_EPI>
; __device__ __forceinline__ void gemm_phase(LAS unsigned char* lds, const Gemm g, const StaticOrder S, const Epi E) {
;     ...
;             PG8_WAIT_V(8); PG8_WAIT_L(0); PG8_BAR; PG8_MMA(0, 0, At, B0); PG8_MMA(0, 1, At, B1); PG8_BAR; PG8_SCHED;
;             PG8_LDA(At, 1, 1); PG8_STAGE(PG8_SB(1, 0), b3, voffB); PG8_STAGE(PG8_SB(1, 1), b3 + hstepB, voffB); PG8_STAGE(PG8_SA(1, 0), a3, voffA);
;             PG8_WAIT_V(8); PG8_WAIT_L(0); PG8_BAR; PG8_MMA(1, 0, At, B0); PG8_MMA(1, 1, At, B1); PG8_BAR; PG8_SCHED;
;         }
;         if constexpr (ALIGN_EPI) { if (wr == 0) PG8_BAR; }
	s_waitcnt lgkmcnt(0)
	v_mfma_f32_16x16x32_bf16 v[126:129], v[148:151], v[198:201], v[126:129]
	v_mfma_f32_16x16x32_bf16 v[122:125], v[156:159], v[198:201], v[122:125]
	v_mfma_f32_16x16x32_bf16 v[118:121], v[148:151], v[206:209], v[118:121]
	v_mfma_f32_16x16x32_bf16 v[110:113], v[156:159], v[206:209], v[110:113]
	v_mfma_f32_16x16x32_bf16 v[102:105], v[148:151], v[214:217], v[102:105]
	v_mfma_f32_16x16x32_bf16 v[94:97], v[156:159], v[214:217], v[94:97]
	v_mfma_f32_16x16x32_bf16 v[86:89], v[148:151], v[222:225], v[86:89]
	v_mfma_f32_16x16x32_bf16 v[76:79], v[156:159], v[222:225], v[76:79]
	v_mfma_f32_16x16x32_bf16 v[126:129], v[152:155], v[202:205], v[126:129]
	v_mfma_f32_16x16x32_bf16 v[122:125], v[160:163], v[202:205], v[122:125]
	v_mfma_f32_16x16x32_bf16 v[118:121], v[152:155], v[210:213], v[118:121]
	v_mfma_f32_16x16x32_bf16 v[110:113], v[160:163], v[210:213], v[110:113]
	v_mfma_f32_16x16x32_bf16 v[102:105], v[152:155], v[218:221], v[102:105]
	v_mfma_f32_16x16x32_bf16 v[94:97], v[160:163], v[218:221], v[94:97]
	v_mfma_f32_16x16x32_bf16 v[86:89], v[152:155], v[226:229], v[86:89]
	v_mfma_f32_16x16x32_bf16 v[76:79], v[160:163], v[226:229], v[76:79]
	v_mfma_f32_16x16x32_bf16 v[114:117], v[182:185], v[198:201], v[114:117]
	v_mfma_f32_16x16x32_bf16 v[106:109], v[190:193], v[198:201], v[106:109]
	v_mfma_f32_16x16x32_bf16 v[98:101], v[182:185], v[206:209], v[98:101]
	v_mfma_f32_16x16x32_bf16 v[90:93], v[190:193], v[206:209], v[90:93]
	v_mfma_f32_16x16x32_bf16 v[82:85], v[182:185], v[214:217], v[82:85]
	v_mfma_f32_16x16x32_bf16 v[72:75], v[190:193], v[214:217], v[72:75]
	v_mfma_f32_16x16x32_bf16 v[68:71], v[182:185], v[222:225], v[68:71]
	v_mfma_f32_16x16x32_bf16 v[64:67], v[190:193], v[222:225], v[64:67]
	v_mfma_f32_16x16x32_bf16 v[114:117], v[186:189], v[202:205], v[114:117]
	v_mfma_f32_16x16x32_bf16 v[106:109], v[194:197], v[202:205], v[106:109]
	v_mfma_f32_16x16x32_bf16 v[98:101], v[186:189], v[210:213], v[98:101]
	v_mfma_f32_16x16x32_bf16 v[90:93], v[194:197], v[210:213], v[90:93]
	v_mfma_f32_16x16x32_bf16 v[82:85], v[186:189], v[218:221], v[82:85]
	v_mfma_f32_16x16x32_bf16 v[72:75], v[194:197], v[218:221], v[72:75]
	v_mfma_f32_16x16x32_bf16 v[68:71], v[186:189], v[226:229], v[68:71]
	v_mfma_f32_16x16x32_bf16 v[64:67], v[194:197], v[226:229], v[64:67]
	s_barrier
	s_mov_b32 m0, vcc_lo
	v_lshl_add_u64 v[142:143], v[142:143], 0, s[80:81]
	ds_read_b128 v[198:201], v147 offset:49152
	ds_read_b128 v[202:205], v147 offset:50176
	ds_read_b128 v[206:209], v147 offset:51200
	ds_read_b128 v[210:213], v147 offset:52224
	ds_read_b128 v[214:217], v147 offset:53248
	ds_read_b128 v[218:221], v147 offset:54272
	ds_read_b128 v[222:225], v147 offset:55296
	ds_read_b128 v[226:229], v147 offset:56320
	global_load_lds_dwordx4 v[142:143], off
	v_lshl_add_u64 v[142:143], v[164:165], 0, s[80:81]
	s_mov_b32 m0, s18
	s_nop 0
	global_load_lds_dwordx4 v[142:143], off
	v_lshl_add_u64 v[142:143], s[62:63], 0, v[80:81]
	s_mov_b32 m0, s15
	s_nop 0
	global_load_lds_dwordx4 v[142:143], off
	v_lshl_add_u64 v[142:143], s[62:63], 0, v[140:141]
	s_mov_b32 m0, s16
	s_nop 0
	global_load_lds_dwordx4 v[142:143], off
	v_lshl_add_u64 v[142:143], v[168:169], 0, s[80:81]
	s_mov_b32 m0, s31
	s_nop 0
	global_load_lds_dwordx4 v[142:143], off
	v_lshl_add_u64 v[142:143], v[170:171], 0, s[80:81]
	s_mov_b32 m0, s61
	s_nop 0
	global_load_lds_dwordx4 v[142:143], off
	s_waitcnt vmcnt(8)
	s_waitcnt lgkmcnt(0)
	s_barrier
	s_waitcnt lgkmcnt(0)
	v_mfma_f32_16x16x32_bf16 v[60:63], v[148:151], v[198:201], v[60:63]
	v_mfma_f32_16x16x32_bf16 v[56:59], v[156:159], v[198:201], v[56:59]
	v_mfma_f32_16x16x32_bf16 v[52:55], v[148:151], v[206:209], v[52:55]
	v_mfma_f32_16x16x32_bf16 v[44:47], v[156:159], v[206:209], v[44:47]
	v_mfma_f32_16x16x32_bf16 v[36:39], v[148:151], v[214:217], v[36:39]
	v_mfma_f32_16x16x32_bf16 v[28:31], v[156:159], v[214:217], v[28:31]
	v_mfma_f32_16x16x32_bf16 v[20:23], v[148:151], v[222:225], v[20:23]
	v_mfma_f32_16x16x32_bf16 v[12:15], v[156:159], v[222:225], v[12:15]
	v_mfma_f32_16x16x32_bf16 v[60:63], v[152:155], v[202:205], v[60:63]
	v_mfma_f32_16x16x32_bf16 v[56:59], v[160:163], v[202:205], v[56:59]
	v_mfma_f32_16x16x32_bf16 v[52:55], v[152:155], v[210:213], v[52:55]
	v_mfma_f32_16x16x32_bf16 v[44:47], v[160:163], v[210:213], v[44:47]
	v_mfma_f32_16x16x32_bf16 v[36:39], v[152:155], v[218:221], v[36:39]
	v_mfma_f32_16x16x32_bf16 v[28:31], v[160:163], v[218:221], v[28:31]
	v_mfma_f32_16x16x32_bf16 v[20:23], v[152:155], v[226:229], v[20:23]
	v_mfma_f32_16x16x32_bf16 v[12:15], v[160:163], v[226:229], v[12:15]
	v_mfma_f32_16x16x32_bf16 v[48:51], v[182:185], v[198:201], v[48:51]
	v_mfma_f32_16x16x32_bf16 v[40:43], v[190:193], v[198:201], v[40:43]
	v_mfma_f32_16x16x32_bf16 v[32:35], v[182:185], v[206:209], v[32:35]
	v_mfma_f32_16x16x32_bf16 v[24:27], v[190:193], v[206:209], v[24:27]
	v_mfma_f32_16x16x32_bf16 v[16:19], v[182:185], v[214:217], v[16:19]
	v_mfma_f32_16x16x32_bf16 v[8:11], v[190:193], v[214:217], v[8:11]
	v_mfma_f32_16x16x32_bf16 v[4:7], v[182:185], v[222:225], v[4:7]
	v_mfma_f32_16x16x32_bf16 v[0:3], v[190:193], v[222:225], v[0:3]
	v_mfma_f32_16x16x32_bf16 v[48:51], v[186:189], v[202:205], v[48:51]
	v_mfma_f32_16x16x32_bf16 v[40:43], v[194:197], v[202:205], v[40:43]
	v_mfma_f32_16x16x32_bf16 v[32:35], v[186:189], v[210:213], v[32:35]
	v_mfma_f32_16x16x32_bf16 v[24:27], v[194:197], v[210:213], v[24:27]
	v_mfma_f32_16x16x32_bf16 v[16:19], v[186:189], v[218:221], v[16:19]
	v_mfma_f32_16x16x32_bf16 v[8:11], v[194:197], v[218:221], v[8:11]
	v_mfma_f32_16x16x32_bf16 v[4:7], v[186:189], v[226:229], v[4:7]
	v_mfma_f32_16x16x32_bf16 v[0:3], v[194:197], v[226:229], v[0:3]
	s_barrier
	s_andn2_b64 vcc, exec, s[42:43]
	s_mov_b64 s[62:63], -1
	s_mov_b64 s[42:43], 0
	s_mov_b64 s[64:65], 0x100
	s_cbranch_vccz .LBB0_1815
	s_setprio 0
	s_and_b64 vcc, exec, s[44:45]
	s_cbranch_vccz .LBB0_1818
	s_barrier

; #define PG8_STAGE(bufoff, gbase, voff) do { _Pragma("unroll") for (int _i = 0; _i < 2; ++_i) \
;         __builtin_amdgcn_global_load_lds((const unsigned*)((const char*)(gbase) + (voff)[_i]), (LAS unsigned*)(lds + (bufoff) + ldsw + _i * 8192), 16, 0, 0); } while (0)
; #define PG8_LDA(dst, b, h) do { _Pragma("unroll") for (int m = 0; m < 4; ++m) _Pragma("unroll") for (int k = 0; k < 2; ++k) dst[m][k] = *(const LAS bf16x8*)(lds + PG8_SA(b, h) + aoff + m * 2048 + k * 1024); } while (0)
; #define PG8_LDB(dst, b, h) do { _Pragma("unroll") for (int n = 0; n < 2; ++n) _Pragma("unroll") for (int k = 0; k < 2; ++k) dst[n][k] = *(const LAS bf16x8*)(lds + PG8_SB(b, h) + boff + n * 2048 + k * 1024); } while (0)
; #define PG8_MMA(ai, bj, At, Bt) do { __builtin_amdgcn_s_setprio(1); _Pragma("unroll") for (int m = 0; m < 4; ++m) _Pragma("unroll") for (int n = 0; n < 2; ++n) _Pragma("unroll") for (int k = 0; k < 2; ++k) \
;         acc[ai][bj][m][n] = __builtin_amdgcn_mfma_f32_16x16x32_bf16(Bt[n][k], At[m][k], acc[ai][bj][m][n], 0, 0, 0); __builtin_amdgcn_s_setprio(0); } while (0)
; #define PG8_WAIT_V(n) asm volatile("s_waitcnt vmcnt(" #n ")" ::: "memory")
; #define PG8_WAIT_L(n) asm volatile("s_waitcnt lgkmcnt(" #n ")" ::: "memory")
; #define PG8_BAR __builtin_amdgcn_s_barrier()
; #define PG8_SCHED __builtin_amdgcn_sched_barrier(0)
; template <class Epi, bool ALIGN_EPI>
; __device__ __forceinline__ void gemm_phase(LAS unsigned char* lds, const Gemm g, const StaticOrder S, const Epi E) {
;     ...
;             const bool last = (t == nt - 2);
;             const char* a1 = cA + (size_t)(t + 1) * kstep;
;             const char* a2 = last ? nA : cA + (size_t)(t + 2) * kstep; const char* b2 = last ? nB : cB + (size_t)(t + 2) * kstep;
;             const char* a3 = a2 + kstep; const char* b3 = b2 + kstep;
;             PG8_LDB(B0, 0, 0); PG8_LDB(B1, 0, 1); PG8_SCHED; PG8_LDA(At, 0, 0); PG8_STAGE(PG8_SA(1, 1), a1 + hstepA, voffA);
;             PG8_WAIT_V(8); PG8_WAIT_L(0); PG8_BAR; PG8_MMA(0, 0, At, B0); PG8_MMA(0, 1, At, B1); PG8_BAR; PG8_SCHED;
;     ...
; #pragma unroll
;         for (int a = 0; a < 2; ++a)
; #pragma unroll
;             for (int b = 0; b < 2; ++b)
; #pragma unroll
;                 for (int m = 0; m < 4; ++m)
; #pragma unroll
;                     for (int n = 0; n < 2; ++n) acc[a][b][m][n] = (f32x4){0.f, 0.f, 0.f, 0.f};
;         cur = nxt; cA = nA; cB = nB; ++ui;
.LBB0_2014:
	s_ashr_i32 s47, s46, 31
	s_lshl_b64 s[0:1], s[46:47], 19
	v_readlane_b32 s12, v255, 39
	s_add_u32 s50, s12, s0
	v_readlane_b32 s0, v255, 40
	s_addc_u32 s51, s0, s1
	s_and_b64 s[0:1], s[42:43], exec
	s_cselect_b32 s34, s51, s63
	s_cselect_b32 s35, s50, s62
	s_add_u32 s47, s62, 0x100
	v_mov_b32_e32 v0, 0
	s_addc_u32 s53, s63, 0
	s_mov_b32 s71, -2
	v_mov_b32_e32 v1, 0
	v_mov_b64_e32 v[2:3], 0
	v_mov_b64_e32 v[4:5], 0
	v_mov_b64_e32 v[6:7], 0
	v_mov_b64_e32 v[8:9], 0
	v_mov_b64_e32 v[10:11], 0
	v_mov_b64_e32 v[12:13], 0
	v_mov_b64_e32 v[14:15], 0
	v_mov_b64_e32 v[16:17], 0
	v_mov_b64_e32 v[18:19], 0
	v_mov_b64_e32 v[20:21], 0
	v_mov_b64_e32 v[22:23], 0
	v_mov_b64_e32 v[24:25], 0
	v_mov_b64_e32 v[26:27], 0
	v_mov_b64_e32 v[28:29], 0
	v_mov_b64_e32 v[30:31], 0
	v_mov_b64_e32 v[32:33], 0
	v_mov_b64_e32 v[34:35], 0
	v_mov_b64_e32 v[36:37], 0
	v_mov_b64_e32 v[38:39], 0
	v_mov_b64_e32 v[40:41], 0
	v_mov_b64_e32 v[42:43], 0
	v_mov_b64_e32 v[44:45], 0
	v_mov_b64_e32 v[46:47], 0
	v_mov_b64_e32 v[48:49], 0
	v_mov_b64_e32 v[50:51], 0
	v_mov_b64_e32 v[52:53], 0
	v_mov_b64_e32 v[54:55], 0
	v_mov_b64_e32 v[56:57], 0
	v_mov_b64_e32 v[58:59], 0
	v_mov_b64_e32 v[60:61], 0
	v_mov_b64_e32 v[62:63], 0
	v_mov_b64_e32 v[64:65], 0
	v_mov_b64_e32 v[66:67], 0
	v_mov_b64_e32 v[68:69], 0
	v_mov_b64_e32 v[70:71], 0
	v_mov_b64_e32 v[72:73], 0
	v_mov_b64_e32 v[74:75], 0
	v_mov_b64_e32 v[76:77], 0
	v_mov_b64_e32 v[78:79], 0
	v_mov_b64_e32 v[82:83], 0
	v_mov_b64_e32 v[84:85], 0
	v_mov_b64_e32 v[86:87], 0
	v_mov_b64_e32 v[88:89], 0
	v_mov_b64_e32 v[90:91], 0
	v_mov_b64_e32 v[92:93], 0
	v_mov_b64_e32 v[94:95], 0
	v_mov_b64_e32 v[96:97], 0
	v_mov_b64_e32 v[98:99], 0
	v_mov_b64_e32 v[100:101], 0
	v_mov_b64_e32 v[102:103], 0
	v_mov_b64_e32 v[104:105], 0
	v_mov_b64_e32 v[106:107], 0
	v_mov_b64_e32 v[108:109], 0
	v_mov_b64_e32 v[110:111], 0
	v_mov_b64_e32 v[112:113], 0
	v_mov_b64_e32 v[114:115], 0
	v_mov_b64_e32 v[116:117], 0
	v_mov_b64_e32 v[118:119], 0
	v_mov_b64_e32 v[120:121], 0
	v_mov_b64_e32 v[122:123], 0
	v_mov_b64_e32 v[124:125], 0
	v_mov_b64_e32 v[126:127], 0
	v_mov_b64_e32 v[128:129], 0
	v_readfirstlane_b32 s0, v167
	s_nop 3
	s_cmpk_lt_u32 s0, 0x100
	s_cbranch_scc1 .Lprio_k7
	s_setprio 1
.Lprio_k7:
.LBB0_2015:
	s_add_u32 s42, s54, 0x100
	s_addc_u32 s43, s55, 0
	s_add_i32 s0, 0, 0x10000
	s_cmp_eq_u32 s71, 12
	s_cselect_b32 s65, s49, s43
	s_cselect_b32 s64, s48, s42
	v_add_u32_e32 v130, s0, v152
	s_cselect_b32 s63, s34, s53
	s_cselect_b32 s62, s35, s47
	s_add_i32 s12, 0, 0x14000
	ds_read_b128 v[146:149], v130
	ds_read_b128 v[154:157], v130 offset:1024
	ds_read_b128 v[158:161], v130 offset:2048
	ds_read_b128 v[162:165], v130 offset:3072
	v_add_u32_e32 v130, s12, v152
	ds_read_b128 v[182:185], v130
	ds_read_b128 v[186:189], v130 offset:1024
	ds_read_b128 v[190:193], v130 offset:2048
	ds_read_b128 v[194:197], v130 offset:3072
	v_lshl_add_u64 v[168:169], s[54:55], 0, v[142:143]
	s_add_i32 m0, s27, 0xc000
	ds_read_b128 v[198:201], v153
	ds_read_b128 v[202:205], v153 offset:1024
	ds_read_b128 v[206:209], v153 offset:2048
	ds_read_b128 v[210:213], v153 offset:3072
	ds_read_b128 v[214:217], v153 offset:4096
	ds_read_b128 v[218:221], v153 offset:5120
	ds_read_b128 v[222:225], v153 offset:6144
	ds_read_b128 v[226:229], v153 offset:7168
	global_load_lds_dwordx4 v[168:169], off
	v_lshl_add_u64 v[168:169], s[54:55], 0, v[144:145]
	s_add_i32 m0, s27, 0xe000
	s_nop 0
	global_load_lds_dwordx4 v[168:169], off
	s_waitcnt vmcnt(8)
	s_waitcnt lgkmcnt(0)
	s_barrier
	s_waitcnt lgkmcnt(0)
	v_mfma_f32_16x16x32_bf16 v[126:129], v[146:149], v[198:201], v[126:129]
	v_mfma_f32_16x16x32_bf16 v[122:125], v[158:161], v[198:201], v[122:125]
	v_mfma_f32_16x16x32_bf16 v[110:113], v[146:149], v[206:209], v[110:113]
	v_mfma_f32_16x16x32_bf16 v[106:109], v[158:161], v[206:209], v[106:109]
	v_mfma_f32_16x16x32_bf16 v[94:97], v[146:149], v[214:217], v[94:97]
	v_mfma_f32_16x16x32_bf16 v[90:93], v[158:161], v[214:217], v[90:93]
	v_mfma_f32_16x16x32_bf16 v[76:79], v[146:149], v[222:225], v[76:79]
	v_mfma_f32_16x16x32_bf16 v[72:75], v[158:161], v[222:225], v[72:75]
	v_mfma_f32_16x16x32_bf16 v[126:129], v[154:157], v[202:205], v[126:129]
	v_mfma_f32_16x16x32_bf16 v[122:125], v[162:165], v[202:205], v[122:125]
	v_mfma_f32_16x16x32_bf16 v[110:113], v[154:157], v[210:213], v[110:113]
	v_mfma_f32_16x16x32_bf16 v[106:109], v[162:165], v[210:213], v[106:109]
	v_mfma_f32_16x16x32_bf16 v[94:97], v[154:157], v[218:221], v[94:97]
	v_mfma_f32_16x16x32_bf16 v[90:93], v[162:165], v[218:221], v[90:93]
	v_mfma_f32_16x16x32_bf16 v[76:79], v[154:157], v[226:229], v[76:79]
	v_mfma_f32_16x16x32_bf16 v[72:75], v[162:165], v[226:229], v[72:75]
	v_mfma_f32_16x16x32_bf16 v[118:121], v[182:185], v[198:201], v[118:121]
	v_mfma_f32_16x16x32_bf16 v[114:117], v[190:193], v[198:201], v[114:117]
	v_mfma_f32_16x16x32_bf16 v[102:105], v[182:185], v[206:209], v[102:105]
	v_mfma_f32_16x16x32_bf16 v[98:101], v[190:193], v[206:209], v[98:101]
	v_mfma_f32_16x16x32_bf16 v[86:89], v[182:185], v[214:217], v[86:89]
	v_mfma_f32_16x16x32_bf16 v[82:85], v[190:193], v[214:217], v[82:85]
	v_mfma_f32_16x16x32_bf16 v[68:71], v[182:185], v[222:225], v[68:71]
	v_mfma_f32_16x16x32_bf16 v[64:67], v[190:193], v[222:225], v[64:67]
	v_mfma_f32_16x16x32_bf16 v[118:121], v[186:189], v[202:205], v[118:121]
	v_mfma_f32_16x16x32_bf16 v[114:117], v[194:197], v[202:205], v[114:117]
	v_mfma_f32_16x16x32_bf16 v[102:105], v[186:189], v[210:213], v[102:105]
	v_mfma_f32_16x16x32_bf16 v[98:101], v[194:197], v[210:213], v[98:101]
	v_mfma_f32_16x16x32_bf16 v[86:89], v[186:189], v[218:221], v[86:89]
	v_mfma_f32_16x16x32_bf16 v[82:85], v[194:197], v[218:221], v[82:85]
	v_mfma_f32_16x16x32_bf16 v[68:71], v[186:189], v[226:229], v[68:71]
	v_mfma_f32_16x16x32_bf16 v[64:67], v[194:197], v[226:229], v[64:67]
	s_barrier
; #define PG8_STAGE(bufoff, gbase, voff) do { _Pragma("unroll") for (int _i = 0; _i < 2; ++_i) \
;         __builtin_amdgcn_global_load_lds((const unsigned*)((const char*)(gbase) + (voff)[_i]), (LAS unsigned*)(lds + (bufoff) + ldsw + _i * 8192), 16, 0, 0); } while (0)
; #define PG8_LDA(dst, b, h) do { _Pragma("unroll") for (int m = 0; m < 4; ++m) _Pragma("unroll") for (int k = 0; k < 2; ++k) dst[m][k] = *(const LAS bf16x8*)(lds + PG8_SA(b, h) + aoff + m * 2048 + k * 1024); } while (0)
; #define PG8_LDB(dst, b, h) do { _Pragma("unroll") for (int n = 0; n < 2; ++n) _Pragma("unroll") for (int k = 0; k < 2; ++k) dst[n][k] = *(const LAS bf16x8*)(lds + PG8_SB(b, h) + boff + n * 2048 + k * 1024); } while (0)
; #define PG8_MMA(ai, bj, At, Bt) do { __builtin_amdgcn_s_setprio(1); _Pragma("unroll") for (int m = 0; m < 4; ++m) _Pragma("unroll") for (int n = 0; n < 2; ++n) _Pragma("unroll") for (int k = 0; k < 2; ++k) \
;         acc[ai][bj][m][n] = __builtin_amdgcn_mfma_f32_16x16x32_bf16(Bt[n][k], At[m][k], acc[ai][bj][m][n], 0, 0, 0); __builtin_amdgcn_s_setprio(0); } while (0)
; #define PG8_WAIT_V(n) asm volatile("s_waitcnt vmcnt(" #n ")" ::: "memory")
; #define PG8_WAIT_L(n) asm volatile("s_waitcnt lgkmcnt(" #n ")" ::: "memory")
; #define PG8_BAR __builtin_amdgcn_s_barrier()
; #define PG8_SCHED __builtin_amdgcn_sched_barrier(0)
; template <class Epi, bool ALIGN_EPI>
; __device__ __forceinline__ void gemm_phase(LAS unsigned char* lds, const Gemm g, const StaticOrder S, const Epi E) {
;     ...
;             PG8_LDA(At, 0, 1); PG8_STAGE(PG8_SB(0, 0), b2, voffB); PG8_STAGE(PG8_SB(0, 1), b2 + hstepB, voffB); PG8_STAGE(PG8_SA(0, 0), a2, voffA);
;             PG8_WAIT_V(8); PG8_WAIT_L(0); PG8_BAR; PG8_MMA(1, 0, At, B0); PG8_MMA(1, 1, At, B1); PG8_BAR; PG8_SCHED;
;             PG8_LDB(B0, 1, 0); PG8_LDB(B1, 1, 1); PG8_SCHED; PG8_LDA(At, 1, 0); PG8_STAGE(PG8_SA(0, 1), a2 + hstepA, voffA);
;             PG8_WAIT_V(8); PG8_WAIT_L(0); PG8_BAR; PG8_MMA(0, 0, At, B0); PG8_MMA(0, 1, At, B1); PG8_BAR; PG8_SCHED;
	s_add_i32 s0, s0, s26
	v_lshl_add_u64 v[168:169], s[62:63], 0, v[80:81]
	s_mov_b32 m0, s0
	ds_read_b128 v[198:201], v153 offset:16384
	ds_read_b128 v[202:205], v153 offset:17408
	ds_read_b128 v[206:209], v153 offset:18432
	ds_read_b128 v[210:213], v153 offset:19456
	ds_read_b128 v[214:217], v153 offset:20480
	ds_read_b128 v[218:221], v153 offset:21504
	ds_read_b128 v[222:225], v153 offset:22528
	ds_read_b128 v[226:229], v153 offset:23552
	global_load_lds_dwordx4 v[168:169], off
	s_add_i32 m0, s0, 0x2000
	s_add_u32 s0, s62, 0x40000
	v_lshl_add_u64 v[170:171], s[62:63], 0, v[140:141]
	s_addc_u32 s1, s63, 0
	s_add_i32 s12, s12, s26
	global_load_lds_dwordx4 v[170:171], off
	v_lshl_add_u64 v[172:173], s[0:1], 0, v[80:81]
	s_mov_b32 m0, s12
	v_lshl_add_u64 v[176:177], s[64:65], 0, v[138:139]
	global_load_lds_dwordx4 v[172:173], off
	v_lshl_add_u64 v[172:173], s[0:1], 0, v[140:141]
	s_add_i32 m0, s12, 0x2000
	s_nop 0
	global_load_lds_dwordx4 v[172:173], off
	v_lshl_add_u64 v[172:173], s[64:65], 0, v[136:137]
	s_mov_b32 m0, s27
	s_nop 0
	global_load_lds_dwordx4 v[172:173], off
	s_mov_b32 m0, s28
	s_nop 0
	global_load_lds_dwordx4 v[176:177], off
	s_waitcnt vmcnt(8)
	s_waitcnt lgkmcnt(0)
	s_barrier
	s_waitcnt lgkmcnt(0)
	v_mfma_f32_16x16x32_bf16 v[60:63], v[146:149], v[198:201], v[60:63]
	v_mfma_f32_16x16x32_bf16 v[56:59], v[158:161], v[198:201], v[56:59]
	v_mfma_f32_16x16x32_bf16 v[44:47], v[146:149], v[206:209], v[44:47]
	v_mfma_f32_16x16x32_bf16 v[40:43], v[158:161], v[206:209], v[40:43]
	v_mfma_f32_16x16x32_bf16 v[28:31], v[146:149], v[214:217], v[28:31]
	v_mfma_f32_16x16x32_bf16 v[24:27], v[158:161], v[214:217], v[24:27]
	v_mfma_f32_16x16x32_bf16 v[12:15], v[146:149], v[222:225], v[12:15]
	v_mfma_f32_16x16x32_bf16 v[8:11], v[158:161], v[222:225], v[8:11]
	v_mfma_f32_16x16x32_bf16 v[60:63], v[154:157], v[202:205], v[60:63]
	v_mfma_f32_16x16x32_bf16 v[56:59], v[162:165], v[202:205], v[56:59]
	v_mfma_f32_16x16x32_bf16 v[44:47], v[154:157], v[210:213], v[44:47]
	v_mfma_f32_16x16x32_bf16 v[40:43], v[162:165], v[210:213], v[40:43]
	v_mfma_f32_16x16x32_bf16 v[28:31], v[154:157], v[218:221], v[28:31]
	v_mfma_f32_16x16x32_bf16 v[24:27], v[162:165], v[218:221], v[24:27]
	v_mfma_f32_16x16x32_bf16 v[12:15], v[154:157], v[226:229], v[12:15]
	v_mfma_f32_16x16x32_bf16 v[8:11], v[162:165], v[226:229], v[8:11]
	v_mfma_f32_16x16x32_bf16 v[52:55], v[182:185], v[198:201], v[52:55]
	v_mfma_f32_16x16x32_bf16 v[48:51], v[190:193], v[198:201], v[48:51]
	v_mfma_f32_16x16x32_bf16 v[36:39], v[182:185], v[206:209], v[36:39]
	v_mfma_f32_16x16x32_bf16 v[32:35], v[190:193], v[206:209], v[32:35]
	v_mfma_f32_16x16x32_bf16 v[20:23], v[182:185], v[214:217], v[20:23]
	v_mfma_f32_16x16x32_bf16 v[16:19], v[190:193], v[214:217], v[16:19]
	v_mfma_f32_16x16x32_bf16 v[4:7], v[182:185], v[222:225], v[4:7]
	v_mfma_f32_16x16x32_bf16 v[0:3], v[190:193], v[222:225], v[0:3]
	v_mfma_f32_16x16x32_bf16 v[52:55], v[186:189], v[202:205], v[52:55]
	v_mfma_f32_16x16x32_bf16 v[48:51], v[194:197], v[202:205], v[48:51]
	v_mfma_f32_16x16x32_bf16 v[36:39], v[186:189], v[210:213], v[36:39]
	v_mfma_f32_16x16x32_bf16 v[32:35], v[194:197], v[210:213], v[32:35]
	v_mfma_f32_16x16x32_bf16 v[20:23], v[186:189], v[218:221], v[20:23]
	v_mfma_f32_16x16x32_bf16 v[16:19], v[194:197], v[218:221], v[16:19]
	v_mfma_f32_16x16x32_bf16 v[4:7], v[186:189], v[226:229], v[4:7]
	v_mfma_f32_16x16x32_bf16 v[0:3], v[194:197], v[226:229], v[0:3]
	s_barrier
	s_add_i32 s12, 0, 0x18000
	v_add_u32_e32 v130, s12, v152
	s_add_i32 s15, 0, 0x1c000
	ds_read_b128 v[146:149], v130
	ds_read_b128 v[154:157], v130 offset:1024
	ds_read_b128 v[158:161], v130 offset:2048
	ds_read_b128 v[162:165], v130 offset:3072
	v_add_u32_e32 v130, s15, v152
	ds_read_b128 v[182:185], v130
	ds_read_b128 v[186:189], v130 offset:1024
	ds_read_b128 v[190:193], v130 offset:2048
	ds_read_b128 v[194:197], v130 offset:3072
	s_add_u32 s0, s64, 0xb0000
	s_addc_u32 s1, s65, 0
	s_mov_b32 m0, s29
	v_lshl_add_u64 v[178:179], s[0:1], 0, v[136:137]
	ds_read_b128 v[198:201], v153 offset:32768
	ds_read_b128 v[202:205], v153 offset:33792
	ds_read_b128 v[206:209], v153 offset:34816
	ds_read_b128 v[210:213], v153 offset:35840
	ds_read_b128 v[214:217], v153 offset:36864
	ds_read_b128 v[218:221], v153 offset:37888
	ds_read_b128 v[222:225], v153 offset:38912
	ds_read_b128 v[226:229], v153 offset:39936
	global_load_lds_dwordx4 v[178:179], off
	v_lshl_add_u64 v[178:179], s[0:1], 0, v[138:139]
	s_mov_b32 m0, s30
	s_nop 0
	global_load_lds_dwordx4 v[178:179], off
	s_waitcnt vmcnt(8)
	s_waitcnt lgkmcnt(0)
	s_barrier
; #define PG8_STAGE(bufoff, gbase, voff) do { _Pragma("unroll") for (int _i = 0; _i < 2; ++_i) \
;         __builtin_amdgcn_global_load_lds((const unsigned*)((const char*)(gbase) + (voff)[_i]), (LAS unsigned*)(lds + (bufoff) + ldsw + _i * 8192), 16, 0, 0); } while (0)
; #define PG8_LDA(dst, b, h) do { _Pragma("unroll") for (int m = 0; m < 4; ++m) _Pragma("unroll") for (int k = 0; k < 2; ++k) dst[m][k] = *(const LAS bf16x8*)(lds + PG8_SA(b, h) + aoff + m * 2048 + k * 1024); } while (0)
; #define PG8_MMA(ai, bj, At, Bt) do { __builtin_amdgcn_s_setprio(1); _Pragma("unroll") for (int m = 0; m < 4; ++m) _Pragma("unroll") for (int n = 0; n < 2; ++n) _Pragma("unroll") for (int k = 0; k < 2; ++k) \
;         acc[ai][bj][m][n] = __builtin_amdgcn_mfma_f32_16x16x32_bf16(Bt[n][k], At[m][k], acc[ai][bj][m][n], 0, 0, 0); __builtin_amdgcn_s_setprio(0); } while (0)
; #define PG8_WAIT_V(n) asm volatile("s_waitcnt vmcnt(" #n ")" ::: "memory")
; #define PG8_WAIT_L(n) asm volatile("s_waitcnt lgkmcnt(" #n ")" ::: "memory")
; #define PG8_BAR __builtin_amdgcn_s_barrier()
; #define PG8_SCHED __builtin_amdgcn_sched_barrier(0)
; template <class Epi, bool ALIGN_EPI>
; __device__ __forceinline__ void gemm_phase(LAS unsigned char* lds, const Gemm g, const StaticOrder S, const Epi E) {
;     ...
;             PG8_WAIT_V(8); PG8_WAIT_L(0); PG8_BAR; PG8_MMA(0, 0, At, B0); PG8_MMA(0, 1, At, B1); PG8_BAR; PG8_SCHED;
;             PG8_LDA(At, 1, 1); PG8_STAGE(PG8_SB(1, 0), b3, voffB); PG8_STAGE(PG8_SB(1, 1), b3 + hstepB, voffB); PG8_STAGE(PG8_SA(1, 0), a3, voffA);
;             PG8_WAIT_V(8); PG8_WAIT_L(0); PG8_BAR; PG8_MMA(1, 0, At, B0); PG8_MMA(1, 1, At, B1); PG8_BAR; PG8_SCHED;
;         }
;         if constexpr (ALIGN_EPI) { if (wr == 0) PG8_BAR; }
	s_waitcnt lgkmcnt(0)
	v_mfma_f32_16x16x32_bf16 v[126:129], v[146:149], v[198:201], v[126:129]
	v_mfma_f32_16x16x32_bf16 v[122:125], v[158:161], v[198:201], v[122:125]
	v_mfma_f32_16x16x32_bf16 v[110:113], v[146:149], v[206:209], v[110:113]
	v_mfma_f32_16x16x32_bf16 v[106:109], v[158:161], v[206:209], v[106:109]
	v_mfma_f32_16x16x32_bf16 v[94:97], v[146:149], v[214:217], v[94:97]
	v_mfma_f32_16x16x32_bf16 v[90:93], v[158:161], v[214:217], v[90:93]
	v_mfma_f32_16x16x32_bf16 v[76:79], v[146:149], v[222:225], v[76:79]
	v_mfma_f32_16x16x32_bf16 v[72:75], v[158:161], v[222:225], v[72:75]
	v_mfma_f32_16x16x32_bf16 v[126:129], v[154:157], v[202:205], v[126:129]
	v_mfma_f32_16x16x32_bf16 v[122:125], v[162:165], v[202:205], v[122:125]
	v_mfma_f32_16x16x32_bf16 v[110:113], v[154:157], v[210:213], v[110:113]
	v_mfma_f32_16x16x32_bf16 v[106:109], v[162:165], v[210:213], v[106:109]
	v_mfma_f32_16x16x32_bf16 v[94:97], v[154:157], v[218:221], v[94:97]
	v_mfma_f32_16x16x32_bf16 v[90:93], v[162:165], v[218:221], v[90:93]
	v_mfma_f32_16x16x32_bf16 v[76:79], v[154:157], v[226:229], v[76:79]
	v_mfma_f32_16x16x32_bf16 v[72:75], v[162:165], v[226:229], v[72:75]
	v_mfma_f32_16x16x32_bf16 v[118:121], v[182:185], v[198:201], v[118:121]
	v_mfma_f32_16x16x32_bf16 v[114:117], v[190:193], v[198:201], v[114:117]
	v_mfma_f32_16x16x32_bf16 v[102:105], v[182:185], v[206:209], v[102:105]
	v_mfma_f32_16x16x32_bf16 v[98:101], v[190:193], v[206:209], v[98:101]
	v_mfma_f32_16x16x32_bf16 v[86:89], v[182:185], v[214:217], v[86:89]
	v_mfma_f32_16x16x32_bf16 v[82:85], v[190:193], v[214:217], v[82:85]
	v_mfma_f32_16x16x32_bf16 v[68:71], v[182:185], v[222:225], v[68:71]
	v_mfma_f32_16x16x32_bf16 v[64:67], v[190:193], v[222:225], v[64:67]
	v_mfma_f32_16x16x32_bf16 v[118:121], v[186:189], v[202:205], v[118:121]
	v_mfma_f32_16x16x32_bf16 v[114:117], v[194:197], v[202:205], v[114:117]
	v_mfma_f32_16x16x32_bf16 v[102:105], v[186:189], v[210:213], v[102:105]
	v_mfma_f32_16x16x32_bf16 v[98:101], v[194:197], v[210:213], v[98:101]
	v_mfma_f32_16x16x32_bf16 v[86:89], v[186:189], v[218:221], v[86:89]
	v_mfma_f32_16x16x32_bf16 v[82:85], v[194:197], v[218:221], v[82:85]
	v_mfma_f32_16x16x32_bf16 v[68:71], v[186:189], v[226:229], v[68:71]
	v_mfma_f32_16x16x32_bf16 v[64:67], v[194:197], v[226:229], v[64:67]
	s_barrier
	s_add_i32 s0, s12, s26
	v_lshl_add_u64 v[168:169], v[168:169], 0, s[80:81]
	s_mov_b32 m0, s0
	ds_read_b128 v[198:201], v153 offset:49152
	ds_read_b128 v[202:205], v153 offset:50176
	ds_read_b128 v[206:209], v153 offset:51200
	ds_read_b128 v[210:213], v153 offset:52224
	ds_read_b128 v[214:217], v153 offset:53248
	ds_read_b128 v[218:221], v153 offset:54272
	ds_read_b128 v[222:225], v153 offset:55296
	ds_read_b128 v[226:229], v153 offset:56320
	global_load_lds_dwordx4 v[168:169], off
	s_add_i32 m0, s0, 0x2000
	s_add_u32 s0, s62, 0x40080
	v_lshl_add_u64 v[168:169], v[170:171], 0, s[80:81]
	s_addc_u32 s1, s63, 0
	s_add_i32 s12, s15, s26
	global_load_lds_dwordx4 v[168:169], off
	v_lshl_add_u64 v[168:169], s[0:1], 0, v[80:81]
	s_mov_b32 m0, s12
	s_nop 0
	global_load_lds_dwordx4 v[168:169], off
	v_lshl_add_u64 v[168:169], s[0:1], 0, v[140:141]
	s_add_i32 m0, s12, 0x2000
	s_nop 0
	global_load_lds_dwordx4 v[168:169], off
	v_lshl_add_u64 v[168:169], v[172:173], 0, s[80:81]
	s_mov_b32 m0, s67
	s_nop 0
	global_load_lds_dwordx4 v[168:169], off
	v_lshl_add_u64 v[168:169], v[176:177], 0, s[80:81]
	s_mov_b32 m0, s68
	s_nop 0
	global_load_lds_dwordx4 v[168:169], off
	s_waitcnt vmcnt(8)
	s_waitcnt lgkmcnt(0)
	s_barrier
	s_waitcnt lgkmcnt(0)
	v_mfma_f32_16x16x32_bf16 v[60:63], v[146:149], v[198:201], v[60:63]
	v_mfma_f32_16x16x32_bf16 v[56:59], v[158:161], v[198:201], v[56:59]
	v_mfma_f32_16x16x32_bf16 v[44:47], v[146:149], v[206:209], v[44:47]
	v_mfma_f32_16x16x32_bf16 v[40:43], v[158:161], v[206:209], v[40:43]
	v_mfma_f32_16x16x32_bf16 v[28:31], v[146:149], v[214:217], v[28:31]
	v_mfma_f32_16x16x32_bf16 v[24:27], v[158:161], v[214:217], v[24:27]
	v_mfma_f32_16x16x32_bf16 v[12:15], v[146:149], v[222:225], v[12:15]
	v_mfma_f32_16x16x32_bf16 v[8:11], v[158:161], v[222:225], v[8:11]
	v_mfma_f32_16x16x32_bf16 v[60:63], v[154:157], v[202:205], v[60:63]
	v_mfma_f32_16x16x32_bf16 v[56:59], v[162:165], v[202:205], v[56:59]
	v_mfma_f32_16x16x32_bf16 v[44:47], v[154:157], v[210:213], v[44:47]
	v_mfma_f32_16x16x32_bf16 v[40:43], v[162:165], v[210:213], v[40:43]
	v_mfma_f32_16x16x32_bf16 v[28:31], v[154:157], v[218:221], v[28:31]
	v_mfma_f32_16x16x32_bf16 v[24:27], v[162:165], v[218:221], v[24:27]
	v_mfma_f32_16x16x32_bf16 v[12:15], v[154:157], v[226:229], v[12:15]
	v_mfma_f32_16x16x32_bf16 v[8:11], v[162:165], v[226:229], v[8:11]
	v_mfma_f32_16x16x32_bf16 v[52:55], v[182:185], v[198:201], v[52:55]
	v_mfma_f32_16x16x32_bf16 v[48:51], v[190:193], v[198:201], v[48:51]
	v_mfma_f32_16x16x32_bf16 v[36:39], v[182:185], v[206:209], v[36:39]
	v_mfma_f32_16x16x32_bf16 v[32:35], v[190:193], v[206:209], v[32:35]
	v_mfma_f32_16x16x32_bf16 v[20:23], v[182:185], v[214:217], v[20:23]
	v_mfma_f32_16x16x32_bf16 v[16:19], v[190:193], v[214:217], v[16:19]
	v_mfma_f32_16x16x32_bf16 v[4:7], v[182:185], v[222:225], v[4:7]
	v_mfma_f32_16x16x32_bf16 v[0:3], v[190:193], v[222:225], v[0:3]
	v_mfma_f32_16x16x32_bf16 v[52:55], v[186:189], v[202:205], v[52:55]
	v_mfma_f32_16x16x32_bf16 v[48:51], v[194:197], v[202:205], v[48:51]
	v_mfma_f32_16x16x32_bf16 v[36:39], v[186:189], v[210:213], v[36:39]
	v_mfma_f32_16x16x32_bf16 v[32:35], v[194:197], v[210:213], v[32:35]
	v_mfma_f32_16x16x32_bf16 v[20:23], v[186:189], v[218:221], v[20:23]
	v_mfma_f32_16x16x32_bf16 v[16:19], v[194:197], v[218:221], v[16:19]
	v_mfma_f32_16x16x32_bf16 v[4:7], v[186:189], v[226:229], v[4:7]
	v_mfma_f32_16x16x32_bf16 v[0:3], v[194:197], v[226:229], v[0:3]
	s_barrier
	s_add_i32 s71, s71, 2
	s_add_u32 s47, s47, 0x100
	s_addc_u32 s53, s53, 0
	s_cmp_gt_u32 s71, 13
	s_mov_b64 s[54:55], s[42:43]
	s_cbranch_scc0 .LBB0_2015
	s_setprio 0
	s_and_b64 vcc, exec, s[44:45]
	s_cbranch_vccz .LBB0_2018
	s_barrier
